# nt policy also on conversion bf16 weight stores, prologue x loads, final_norm X loads and output stores
# baseline (speedup 1.0000x reference)
; DI void ss_set(ssacc_t* p, float v) { *p = (ssacc_t)__float2ull_rn(v * 4294967296.f); }
; DI float sq8(const f32x4& a, const f32x4& b) { return (a[0] * a[0] + a[1] * a[1]) + (a[2] * a[2] + a[3] * a[3]) + (b[0] * b[0] + b[1] * b[1]) + (b[2] * b[2] + b[3] * b[3]); }
; DI u32x4 pack8(const f32x4& a, const f32x4& b) { u32x4 w; w.x = cvtpk(a[0], a[1]); w.y = cvtpk(a[2], a[3]); w.z = cvtpk(b[0], b[1]); w.w = cvtpk(b[2], b[3]); return w; }
; DI float wave_sum(float v) {
; #pragma unroll
;     for (int o = 1; o < 64; o <<= 1) v += __shfl_xor(v, o);
;     return v;
; }
; DI void prologue(PP p, LAS unsigned char* lds) {
;     ...
;         const float* x = p->in[0]; bf16_t* XB = (bf16_t*)(ws + WS_XB); ssacc_t* ss = (ssacc_t*)(ws + WS_SS);
;         for (int m = gw; m < M_; m += NGW) {
;             const f32x4* xr = (const f32x4*)(x + (size_t)m * D_) + lane * 2; float s = 0.f;
; #pragma unroll
;             for (int j = 0; j < 4; ++j) { const f32x4 a = xr[128 * j], b = xr[128 * j + 1]; s += sq8(a, b); *(u32x4*)(XB + (size_t)m * D_ + j * 512 + lane * 8) = pack8(a, b); }
;             s = wave_sum(s); if (lane == 0) ss_set(ss + m, s);
;         }
.LBB0_11:
	v_add_co_u32_e32 v32, vcc, 0xfffff000, v8
	v_lshl_add_u64 v[20:21], v[8:9], 0, s[16:17]
	s_nop 0
	v_addc_co_u32_e32 v33, vcc, -1, v9, vcc
	s_waitcnt lgkmcnt(0)
	global_load_dwordx4 v[16:19], v[32:33], off offset:-2064 nt
	v_lshl_add_u64 v[24:25], s[24:25], 0, v[4:5]
	global_load_dwordx4 v[20:23], v[20:21], off offset:16 nt
	global_load_dwordx4 v[52:55], v[32:33], off offset:-16 nt
	global_load_dwordx4 v[56:59], v[8:9], off offset:-4096 nt
	global_load_dwordx4 v[60:63], v[8:9], off offset:-2064 nt
	global_load_dwordx4 v[64:67], v[8:9], off offset:-2048 nt
	global_load_dwordx4 v[68:71], v[8:9], off offset:-16 nt
	global_load_dwordx4 v[72:75], v[8:9], off nt
	v_add_co_u32_e32 v48, vcc, s9, v24
	s_waitcnt vmcnt(7)
	v_cvt_pk_bf16_f32 v24, v16, v17
	v_addc_co_u32_e32 v49, vcc, 0, v25, vcc
	v_cvt_pk_bf16_f32 v25, v18, v19
	s_waitcnt vmcnt(6)
	v_cvt_pk_bf16_f32 v26, v20, v21
	v_cvt_pk_bf16_f32 v27, v22, v23
	global_store_dwordx4 v[48:49], v[24:27], off
	v_mul_f32_e32 v6, v17, v17
	v_mul_f32_e32 v17, v19, v19
	v_fmac_f32_e32 v6, v16, v16
	v_fmac_f32_e32 v17, v18, v18
	v_mul_f32_e32 v19, v21, v21
	v_add_f32_e32 v6, v6, v17
	v_fmac_f32_e32 v19, v20, v20
	v_mul_f32_e32 v21, v23, v23
	v_add_f32_e32 v6, v6, v19
	v_fmac_f32_e32 v21, v22, v22
	v_add_f32_e32 v6, v21, v6
	s_waitcnt vmcnt(6)
	v_mov_b32_e32 v24, v52
	v_mov_b32_e32 v25, v53
	v_mov_b32_e32 v26, v54
	v_mov_b32_e32 v27, v55
	v_cvt_pk_bf16_f32 v32, v24, v25
	v_cvt_pk_bf16_f32 v33, v26, v27
	s_waitcnt vmcnt(5)
	v_mov_b32_e32 v28, v56
	v_mov_b32_e32 v29, v57
	v_mov_b32_e32 v30, v58
	v_mov_b32_e32 v31, v59
	v_cvt_pk_bf16_f32 v34, v28, v29
	v_cvt_pk_bf16_f32 v35, v30, v31
	global_store_dwordx4 v[48:49], v[32:35], off offset:1024
	v_mul_f32_e32 v16, v25, v25
	v_mul_f32_e32 v17, v27, v27
	v_mul_f32_e32 v18, v29, v29
	v_fmac_f32_e32 v16, v24, v24
	v_fmac_f32_e32 v17, v26, v26
	v_mul_f32_e32 v19, v31, v31
	v_fmac_f32_e32 v18, v28, v28
	v_add_f32_e32 v16, v16, v17
	v_fmac_f32_e32 v19, v30, v30
	v_add_f32_e32 v16, v16, v18
	v_add_f32_e32 v16, v19, v16
	v_add_f32_e32 v6, v6, v16
	s_waitcnt vmcnt(5)
	v_mov_b32_e32 v32, v60
	v_mov_b32_e32 v33, v61
	v_mov_b32_e32 v34, v62
	v_mov_b32_e32 v35, v63
	v_cvt_pk_bf16_f32 v40, v32, v33
	v_cvt_pk_bf16_f32 v41, v34, v35
	s_waitcnt vmcnt(4)
	v_mov_b32_e32 v36, v64
	v_mov_b32_e32 v37, v65
	v_mov_b32_e32 v38, v66
	v_mov_b32_e32 v39, v67
	v_cvt_pk_bf16_f32 v42, v36, v37
	v_cvt_pk_bf16_f32 v43, v38, v39
	global_store_dwordx4 v[48:49], v[40:43], off offset:2048
	v_mul_f32_e32 v16, v33, v33
	v_mul_f32_e32 v17, v35, v35
	v_mul_f32_e32 v18, v37, v37
	v_fmac_f32_e32 v16, v32, v32
	v_fmac_f32_e32 v17, v34, v34
	v_mul_f32_e32 v19, v39, v39
	v_fmac_f32_e32 v18, v36, v36
	v_add_f32_e32 v16, v16, v17
	v_fmac_f32_e32 v19, v38, v38
	v_add_f32_e32 v16, v16, v18
	v_add_f32_e32 v16, v19, v16
	v_add_f32_e32 v6, v6, v16
	s_waitcnt vmcnt(4)
	v_mov_b32_e32 v40, v68
	v_mov_b32_e32 v41, v69
	v_mov_b32_e32 v42, v70
	v_mov_b32_e32 v43, v71
	v_mul_f32_e32 v16, v41, v41
	v_mul_f32_e32 v17, v43, v43
	s_waitcnt vmcnt(3)
	v_mov_b32_e32 v44, v72
	v_mov_b32_e32 v45, v73
	v_mov_b32_e32 v46, v74
	v_mov_b32_e32 v47, v75
	v_mul_f32_e32 v18, v45, v45
	v_fmac_f32_e32 v16, v40, v40
	v_fmac_f32_e32 v17, v42, v42
	v_mul_f32_e32 v19, v47, v47
	v_fmac_f32_e32 v18, v44, v44
	v_add_f32_e32 v16, v16, v17
	v_add_f32_e32 v16, v16, v18
	v_fmac_f32_e32 v19, v46, v46
	v_add_f32_e32 v16, v19, v16
	v_add_f32_e32 v6, v6, v16
	ds_bpermute_b32 v16, v10, v6
	v_cvt_pk_bf16_f32 v18, v40, v41
	v_cvt_pk_bf16_f32 v19, v42, v43
	v_cvt_pk_bf16_f32 v20, v44, v45
	v_cvt_pk_bf16_f32 v21, v46, v47
	s_waitcnt lgkmcnt(0)
	v_add_f32_e32 v6, v6, v16
	ds_bpermute_b32 v16, v11, v6
	global_store_dwordx4 v[48:49], v[18:21], off offset:3072
	s_waitcnt lgkmcnt(0)
	v_add_f32_e32 v6, v6, v16
	ds_bpermute_b32 v16, v12, v6
	s_waitcnt lgkmcnt(0)
	v_add_f32_e32 v6, v6, v16
	ds_bpermute_b32 v16, v13, v6
	s_waitcnt lgkmcnt(0)
	v_add_f32_e32 v6, v6, v16
	ds_bpermute_b32 v16, v14, v6
	s_waitcnt lgkmcnt(0)
	v_add_f32_e32 v6, v6, v16
	ds_bpermute_b32 v16, v15, v6
	s_and_saveexec_b64 s[18:19], s[6:7]
	s_cbranch_execz .LBB0_10
	s_waitcnt lgkmcnt(0)
	v_add_f32_e32 v6, v6, v16
	v_mul_f32_e32 v6, 0x4f800000, v6
	v_rndne_f32_e32 v6, v6
	v_mul_f32_e32 v16, 0x2f800000, v6
	v_floor_f32_e32 v17, v16
	v_fmac_f32_e32 v6, 0xcf800000, v17
	v_cvt_u32_f32_e32 v16, v6
	v_cvt_u32_f32_e32 v17, v17
	s_add_u32 s20, s24, s3
	s_addc_u32 s21, s25, s5
	global_store_dwordx2 v7, v[16:17], s[20:21]
	s_branch .LBB0_10

; #define LAS __attribute__((address_space(3)))
; DI unsigned cvtpk(float lo, float hi) { f32x2 v = {lo, hi}; bf16x2_t b = __builtin_convertvector(v, bf16x2_t); return __builtin_bit_cast(unsigned, b); }
; template <int KIND>
; DI void transpose_item(const float* W, int K, int N, bf16_t* WT, int ldk, const float* g0, const float* g1, const float* g2, LAS float* scr, int item, int lane) {
;     ...
; #pragma unroll
;     for (int j = 0; j < 4; ++j) { const int n = (lane >> 3) + 8 * j; const LAS float* s = scr + (8 * c) * 33 + n;
;         u32x4 o; o.x = cvtpk(s[0 * 33], s[1 * 33]); o.y = cvtpk(s[2 * 33], s[3 * 33]); o.z = cvtpk(s[4 * 33], s[5 * 33]); o.w = cvtpk(s[6 * 33], s[7 * 33]);
;         *(u32x4*)(WT + (size_t)map_n<KIND>(n0 + n) * ldk + kd0 + 8 * c) = o; }
.LBB0_51:
	s_or_b64 exec, exec, s[8:9]
	v_ashrrev_i32_e32 v15, 31, v14
	v_lshlrev_b64 v[2:3], 12, v[14:15]
	s_waitcnt lgkmcnt(3)
	v_cvt_pk_bf16_f32 v6, v6, v7
	s_waitcnt lgkmcnt(2)
	v_cvt_pk_bf16_f32 v7, v8, v9
	s_waitcnt lgkmcnt(1)
	v_cvt_pk_bf16_f32 v8, v10, v11
	s_waitcnt lgkmcnt(0)
	v_cvt_pk_bf16_f32 v9, v12, v13
	v_lshl_add_u64 v[2:3], v[4:5], 0, v[2:3]
	global_store_dwordx4 v[2:3], v[6:9], off nt
	s_waitcnt lgkmcnt(0)

; template <int KIND>
; DI void transpose_item(const float* W, int K, int N, bf16_t* WT, int ldk, const float* g0, const float* g1, const float* g2, LAS float* scr, int item, int lane) {
;     const int nblk = N / 32, kb = item / nblk, nb = item % nblk, k0 = 64 * kb, n0 = 32 * nb;
;     f32x4 tv[8];
; #pragma unroll
;     for (int i = 0; i < 8; ++i) tv[i] = *(const f32x4*)(W + (size_t)(k0 + 8 * i + (lane >> 3)) * N + n0 + 4 * (lane & 7));
; #pragma unroll
;     for (int i = 0; i < 8; ++i) {
;         const int kk = 8 * i + (lane >> 3), k = k0 + kk;
;         float gn = 1.f;
;         if (KIND == 0 || KIND == 1 || KIND == 2 || KIND == 5 || KIND == 6) gn = g0[k];
; DI void convert_weights(PP p, LAS unsigned char* lds, int l, int worker, int nworkers) {
;     ...
;     for (int it = worker; it < I_LAYER; it += nworkers) {
;         int r = it;
;         if (r < I_IN) { transpose_item<0>(p->in[2] + (size_t)l * 2048 * 2880, 2048, 2880, (bf16_t*)(wl + W_IN), 2048, p->in[1] + l * 2048, nullptr, nullptr, scr, r, lane); continue; } r -= I_IN;
;         if (r < I_UQ) { transpose_item<1>(p->in[4] + (size_t)l * 512 * 1536, 512, 1536, (bf16_t*)(wl + W_UQ), 512, p->in[3] + l * 512, nullptr, nullptr, scr, r, lane); continue; } r -= I_UQ;
;         if (r < I_UKV) { transpose_item<2>(p->in[6] + (size_t)l * 256 * 2048, 256, 2048, (bf16_t*)(wl + W_UKV), 256, p->in[5] + l * 256, nullptr, nullptr, scr, r, lane); continue; } r -= I_UKV;
;         if (r < I_GLU) { transpose_item<3>(p->in[15] + (size_t)l * 512 * 1024, 512, 1024, (bf16_t*)(wl + W_GLU), 512, nullptr, nullptr, nullptr, scr, r, lane); continue; } r -= I_GLU;
;         if (r < I_O) { transpose_item<4>(p->in[20] + (size_t)l * 2048 * 2048, 2048, 2048, (bf16_t*)(wl + W_O), 2048, p->in[17] + l * 1024, p->in[18] + l * 512, p->in[19] + l * 512, scr, r, lane); continue; } r -= I_O;
;         if (r < I_G) { transpose_item<5>(p->in[22] + (size_t)l * 2048 * DFF_, 2048, DFF_, (bf16_t*)(wl + W_GU), 2048, p->in[21] + l * 2048, nullptr, nullptr, scr, r, lane); continue; } r -= I_G;
;         if (r < I_G) { transpose_item<6>(p->in[23] + (size_t)l * 2048 * DFF_, 2048, DFF_, (bf16_t*)(wl + W_GU), 2048, p->in[21] + l * 2048, nullptr, nullptr, scr, r, lane); continue; } r -= I_G;
;         transpose_item<7>(p->in[24] + (size_t)l * DFF_ * 2048, DFF_, 2048, (bf16_t*)(wl + W_DN), DFF_, nullptr, nullptr, nullptr, scr, r, lane);
.LBB0_53:
	s_movk_i32 s6, 0xb3f
	v_cmp_lt_i32_e32 vcc, s6, v1
	s_and_saveexec_b64 s[6:7], vcc
	s_xor_b64 s[56:57], exec, s[6:7]
	s_cbranch_execz .LBB0_143
	s_movk_i32 s6, 0xcbf
	v_cmp_lt_u32_e32 vcc, s6, v1
	s_and_saveexec_b64 s[6:7], vcc
	s_xor_b64 s[58:59], exec, s[6:7]
	s_cbranch_execz .LBB0_140
	s_movk_i32 s6, 0xdbf
	v_cmp_lt_u32_e32 vcc, s6, v1
	s_and_saveexec_b64 s[6:7], vcc
	s_xor_b64 s[60:61], exec, s[6:7]
	s_cbranch_execz .LBB0_137
	s_movk_i32 s6, 0xebf
	v_cmp_lt_u32_e32 vcc, s6, v1
	s_and_saveexec_b64 s[6:7], vcc
	s_xor_b64 s[62:63], exec, s[6:7]
	s_cbranch_execz .LBB0_134
	s_movk_i32 s6, 0x16bf
	v_cmp_lt_u32_e32 vcc, s6, v1
	s_and_saveexec_b64 s[6:7], vcc
	s_xor_b64 s[6:7], exec, s[6:7]
	s_cbranch_execz .LBB0_67
	s_movk_i32 s8, 0x2cbf
	v_cmp_lt_u32_e32 vcc, s8, v1
	s_and_saveexec_b64 s[8:9], vcc
	s_xor_b64 s[8:9], exec, s[8:9]
	s_cbranch_execz .LBB0_64
	s_movk_i32 s10, 0x42bf
	v_cmp_lt_u32_e32 vcc, s10, v1
	s_and_saveexec_b64 s[10:11], vcc
	s_xor_b64 s[10:11], exec, s[10:11]
	s_cbranch_execz .LBB0_61
	s_load_dwordx2 s[12:13], s[4:5], 0xc0
	v_add_u32_e32 v2, 0xffffbd40, v1
	v_and_b32_e32 v55, 0x1fc0, v2
	v_add_u32_e32 v2, 0xfff7a800, v52
	v_and_b32_e32 v88, 0x7e0, v2
	v_lshlrev_b32_e32 v2, 2, v88
	v_mov_b32_e32 v3, v37
	v_or_b32_e32 v4, v55, v34
	s_waitcnt lgkmcnt(0)
	v_lshl_add_u64 v[2:3], s[12:13], 0, v[2:3]
	v_lshl_add_u64 v[2:3], v[2:3], 0, v[36:37]
	v_lshlrev_b32_e32 v4, 13, v4
	v_mov_b32_e32 v5, v37
	v_lshl_add_u64 v[30:31], v[2:3], 0, v[4:5]
	v_add_co_u32_e32 v6, vcc, s66, v30
	v_mov_b32_e32 v57, v37
	s_nop 0
	v_addc_co_u32_e32 v7, vcc, 0, v31, vcc
	v_add_co_u32_e32 v10, vcc, s67, v30
	global_load_dwordx4 v[2:5], v[30:31], off nt
	s_nop 0
	global_load_dwordx4 v[6:9], v[6:7], off nt
	v_addc_co_u32_e32 v11, vcc, 0, v31, vcc
	v_add_co_u32_e32 v14, vcc, s68, v30
	v_lshlrev_b32_e32 v56, 1, v55
	s_nop 0
	v_addc_co_u32_e32 v15, vcc, 0, v31, vcc
	v_add_co_u32_e32 v18, vcc, s69, v30
	global_load_dwordx4 v[10:13], v[10:11], off nt
	s_nop 0
	global_load_dwordx4 v[14:17], v[14:15], off nt
	v_addc_co_u32_e32 v19, vcc, 0, v31, vcc
	v_add_co_u32_e32 v22, vcc, s70, v30
	v_or_b32_e32 v55, v88, v34
	s_nop 0
	v_addc_co_u32_e32 v23, vcc, 0, v31, vcc
	global_load_dwordx4 v[18:21], v[18:19], off nt
	s_nop 0
	global_load_dwordx4 v[22:25], v[22:23], off nt
	v_add_co_u32_e32 v26, vcc, s71, v30
	v_mov_b32_e32 v85, v37
	s_nop 0
	v_addc_co_u32_e32 v27, vcc, 0, v31, vcc
	global_load_dwordx4 v[26:29], v[26:27], off nt
	v_add_co_u32_e32 v30, vcc, s72, v30
	v_lshl_add_u64 v[56:57], v[38:39], 0, v[56:57]
	s_nop 0
	v_addc_co_u32_e32 v31, vcc, 0, v31, vcc
	global_load_dwordx4 v[30:33], v[30:31], off nt
	v_mul_u32_u24_e32 v84, 0x2c00, v55
	v_lshl_add_u64 v[84:85], v[56:57], 0, v[84:85]
	v_or_b32_e32 v86, v88, v53
	v_mov_b32_e32 v87, v37
	v_mul_u32_u24_e32 v86, 0x2c00, v86
	v_lshl_add_u64 v[86:87], v[56:57], 0, v[86:87]
	s_waitcnt vmcnt(7)
	ds_write2_b32 v65, v2, v3 offset1:1
	ds_write2_b32 v65, v4, v5 offset0:2 offset1:3
	s_waitcnt vmcnt(6)
	ds_write2_b32 v66, v6, v7 offset1:1
	ds_write2_b32 v67, v8, v9 offset1:1
	s_waitcnt vmcnt(5)
	ds_write2_b32 v68, v10, v11 offset1:1
	ds_write2_b32 v69, v12, v13 offset1:1
	s_waitcnt vmcnt(4)
	ds_write2_b32 v70, v14, v15 offset1:1
	ds_write2_b32 v71, v16, v17 offset1:1
	s_waitcnt vmcnt(3)
	ds_write2_b32 v72, v18, v19 offset1:1
	ds_write2_b32 v73, v20, v21 offset1:1
	s_waitcnt vmcnt(2)
	ds_write2_b32 v74, v22, v23 offset1:1
	ds_write2_b32 v75, v24, v25 offset1:1
	s_waitcnt vmcnt(1)
	ds_write2_b32 v76, v26, v27 offset1:1
	ds_write2_b32 v77, v28, v29 offset1:1
	s_waitcnt vmcnt(0)
	ds_write2_b32 v78, v30, v31 offset1:1
	ds_write2_b32 v79, v32, v33 offset1:1
	s_waitcnt lgkmcnt(0)
	ds_read2_b32 v[6:7], v60 offset0:33 offset1:41
	ds_read2_b32 v[8:9], v60 offset1:8
	ds_read2_b32 v[10:11], v60 offset0:66 offset1:74
	ds_read2_b32 v[12:13], v60 offset0:99 offset1:107
	ds_read2_b32 v[14:15], v60 offset0:132 offset1:140
	ds_read2_b32 v[16:17], v60 offset0:165 offset1:173
	ds_read2_b32 v[18:19], v60 offset0:198 offset1:206
	ds_read2_b32 v[20:21], v60 offset0:231 offset1:239
	ds_read2_b32 v[22:23], v60 offset0:16 offset1:24
	ds_read2_b32 v[24:25], v60 offset0:49 offset1:57
	ds_read2_b32 v[26:27], v60 offset0:82 offset1:90
	ds_read2_b32 v[28:29], v60 offset0:115 offset1:123
	s_waitcnt lgkmcnt(10)
	v_cvt_pk_bf16_f32 v2, v8, v6
	s_waitcnt lgkmcnt(8)
	v_cvt_pk_bf16_f32 v3, v10, v12
	s_waitcnt lgkmcnt(6)
	v_cvt_pk_bf16_f32 v4, v14, v16
	s_waitcnt lgkmcnt(4)
	v_cvt_pk_bf16_f32 v5, v18, v20
	global_store_dwordx4 v[84:85], v[2:5], off nt
	v_cvt_pk_bf16_f32 v6, v9, v7
	v_cvt_pk_bf16_f32 v7, v11, v13
	v_cvt_pk_bf16_f32 v8, v15, v17
	ds_read2_b32 v[10:11], v60 offset0:148 offset1:156
	ds_read2_b32 v[12:13], v60 offset0:181 offset1:189
	ds_read2_b32 v[14:15], v60 offset0:214 offset1:222
	ds_read2_b32 v[16:17], v60 offset0:247 offset1:255
	v_cvt_pk_bf16_f32 v9, v19, v21
	global_store_dwordx4 v[86:87], v[6:9], off nt
	s_waitcnt lgkmcnt(6)
	v_cvt_pk_bf16_f32 v2, v22, v24
	s_waitcnt lgkmcnt(4)
	v_cvt_pk_bf16_f32 v3, v26, v28
	v_or_b32_e32 v6, v88, v58
	v_mul_u32_u24_e32 v6, 0x2c00, v6
	v_mov_b32_e32 v7, v37
	s_waitcnt lgkmcnt(2)
	v_cvt_pk_bf16_f32 v4, v10, v12
	s_waitcnt lgkmcnt(0)
	v_cvt_pk_bf16_f32 v5, v14, v16
	v_lshl_add_u64 v[6:7], v[56:57], 0, v[6:7]
	global_store_dwordx4 v[6:7], v[2:5], off nt
	v_or_b32_e32 v6, v88, v59
	v_mul_u32_u24_e32 v6, 0x2c00, v6
	v_mov_b32_e32 v7, v37
	v_cvt_pk_bf16_f32 v2, v23, v25
	v_cvt_pk_bf16_f32 v3, v27, v29
	v_cvt_pk_bf16_f32 v4, v11, v13
	v_cvt_pk_bf16_f32 v5, v15, v17
	v_lshl_add_u64 v[6:7], v[56:57], 0, v[6:7]
	global_store_dwordx4 v[6:7], v[2:5], off nt
	s_waitcnt lgkmcnt(0)
; #define LAS __attribute__((address_space(3)))
; DI unsigned cvtpk(float lo, float hi) { f32x2 v = {lo, hi}; bf16x2_t b = __builtin_convertvector(v, bf16x2_t); return __builtin_bit_cast(unsigned, b); }
; template <int KIND> DI int map_n(int n) {
;     ...
;     if (KIND == 6) return 2 * n + 1;
; template <int KIND>
; DI void transpose_item(const float* W, int K, int N, bf16_t* WT, int ldk, const float* g0, const float* g1, const float* g2, LAS float* scr, int item, int lane) {
;     const int nblk = N / 32, kb = item / nblk, nb = item % nblk, k0 = 64 * kb, n0 = 32 * nb;
;     f32x4 tv[8];
; #pragma unroll
;     for (int i = 0; i < 8; ++i) tv[i] = *(const f32x4*)(W + (size_t)(k0 + 8 * i + (lane >> 3)) * N + n0 + 4 * (lane & 7));
; #pragma unroll
;     for (int i = 0; i < 8; ++i) {
;         const int kk = 8 * i + (lane >> 3), k = k0 + kk;
;         float gn = 1.f;
;         if (KIND == 0 || KIND == 1 || KIND == 2 || KIND == 5 || KIND == 6) gn = g0[k];
;         if (KIND == 4) gn = k < 1024 ? g0[k] : (k < 1536 ? g1[k - 1024] : g2[k - 1536]);
;         LAS float* d = scr + kk * 33 + 4 * (lane & 7);
;         d[0] = tv[i][0] * gn; d[1] = tv[i][1] * gn; d[2] = tv[i][2] * gn; d[3] = tv[i][3] * gn;
;     }
;     asm volatile("s_waitcnt lgkmcnt(0)" ::: "memory");
;     int kd0 = k0;
;     if (KIND == 4) kd0 = k0 < 1024 ? k0 + 512 : (k0 < 1536 ? k0 - 1024 : k0);
;     const int c = lane & 7;
; #pragma unroll
;     for (int j = 0; j < 4; ++j) { const int n = (lane >> 3) + 8 * j; const LAS float* s = scr + (8 * c) * 33 + n;
;         u32x4 o; o.x = cvtpk(s[0 * 33], s[1 * 33]); o.y = cvtpk(s[2 * 33], s[3 * 33]); o.z = cvtpk(s[4 * 33], s[5 * 33]); o.w = cvtpk(s[6 * 33], s[7 * 33]);
;         *(u32x4*)(WT + (size_t)map_n<KIND>(n0 + n) * ldk + kd0 + 8 * c) = o; }
;     asm volatile("s_waitcnt lgkmcnt(0)" ::: "memory");
; }
; DI void convert_weights(PP p, LAS unsigned char* lds, int l, int worker, int nworkers) {
;     ...
;         if (r < I_G) { transpose_item<6>(p->in[23] + (size_t)l * 2048 * DFF_, 2048, DFF_, (bf16_t*)(wl + W_GU), 2048, p->in[21] + l * 2048, nullptr, nullptr, scr, r, lane); continue; } r -= I_G;
.LBB0_61:
	s_andn2_saveexec_b64 s[10:11], s[10:11]
	s_cbranch_execz .LBB0_63
	v_add_u16_e32 v2, 0xd340, v1
	v_mul_u32_u24_e32 v3, 0xba2f, v2
	s_load_dwordx2 s[12:13], s[4:5], 0xa8
	s_load_dwordx2 s[14:15], s[4:5], 0xb8
	v_lshrrev_b32_e32 v3, 23, v3
	v_mul_lo_u16_e32 v4, 0xb0, v3
	v_sub_u16_e32 v2, v2, v4
	v_lshlrev_b16_e32 v55, 6, v3
	v_lshlrev_b16_e32 v57, 5, v2
	v_or_b32_e32 v20, v34, v55
	v_lshlrev_b32_e32 v2, 2, v57
	v_mov_b32_e32 v3, v37
	s_waitcnt lgkmcnt(0)
	v_lshl_add_u64 v[2:3], s[14:15], 0, v[2:3]
	v_mul_u32_u24_e32 v4, 0x1600, v20
	v_lshl_add_u64 v[2:3], v[2:3], 0, v[36:37]
	v_lshlrev_b32_e32 v4, 2, v4
	v_mov_b32_e32 v5, v37
	v_lshl_add_u64 v[30:31], v[2:3], 0, v[4:5]
	v_add_co_u32_e32 v6, vcc, s73, v30
	v_lshlrev_b32_e32 v32, 2, v20
	s_nop 0
	v_addc_co_u32_e32 v7, vcc, 0, v31, vcc
	v_add_co_u32_e32 v10, vcc, s74, v30
	global_load_dwordx4 v[2:5], v[30:31], off nt
	s_nop 0
	global_load_dwordx4 v[6:9], v[6:7], off nt
	v_addc_co_u32_e32 v11, vcc, 0, v31, vcc
	v_add_co_u32_e32 v14, vcc, s75, v30
	v_add_u32_e32 v85, v35, v61
	s_nop 0
	v_addc_co_u32_e32 v15, vcc, 0, v31, vcc
	v_add_co_u32_e32 v18, vcc, s76, v30
	global_load_dwordx4 v[10:13], v[10:11], off nt
	s_nop 0
	global_load_dwordx4 v[14:17], v[14:15], off nt
	v_addc_co_u32_e32 v19, vcc, 0, v31, vcc
	v_add_co_u32_e32 v22, vcc, s77, v30
	global_load_dword v56, v32, s[12:13]
	s_nop 0
	v_addc_co_u32_e32 v23, vcc, 0, v31, vcc
	v_add_co_u32_e32 v26, vcc, s78, v30
	global_load_dwordx4 v[18:21], v[18:19], off nt
	s_nop 0
	global_load_dwordx4 v[22:25], v[22:23], off nt
	s_nop 0
	global_load_dword v84, v32, s[12:13] offset:32
	global_load_dword v86, v32, s[12:13] offset:64
	global_load_dword v88, v32, s[12:13] offset:96
	global_load_dword v90, v32, s[12:13] offset:128
	v_addc_co_u32_e32 v27, vcc, 0, v31, vcc
	v_add_co_u32_e32 v30, vcc, s79, v30
	global_load_dword v92, v32, s[12:13] offset:160
	s_nop 0
	global_load_dwordx4 v[26:29], v[26:27], off nt
	s_nop 0
	global_load_dword v94, v32, s[12:13] offset:192
	v_addc_co_u32_e32 v31, vcc, 0, v31, vcc
	global_load_dword v96, v32, s[12:13] offset:224
	s_nop 0
	global_load_dwordx4 v[30:33], v[30:31], off nt
	v_add_u32_e32 v87, 0x420, v85
	v_add_u32_e32 v89, 0x428, v85
	v_add_u32_e32 v91, 0x840, v85
	s_waitcnt vmcnt(11)
	v_pk_mul_f32 v[2:3], v[2:3], v[56:57] op_sel_hi:[1,0]
	v_pk_mul_f32 v[4:5], v[4:5], v[56:57] op_sel_hi:[1,0]
	ds_write2_b32 v65, v2, v3 offset1:1
	ds_write2_b32 v65, v4, v5 offset0:2 offset1:3
	s_waitcnt vmcnt(8)
	v_pk_mul_f32 v[2:3], v[6:7], v[84:85] op_sel_hi:[1,0]
	v_pk_mul_f32 v[4:5], v[8:9], v[84:85] op_sel_hi:[1,0]
	s_waitcnt vmcnt(7)
	v_pk_mul_f32 v[6:7], v[10:11], v[86:87] op_sel_hi:[1,0]
	v_pk_mul_f32 v[8:9], v[12:13], v[86:87] op_sel_hi:[1,0]
	s_waitcnt vmcnt(6)
	v_pk_mul_f32 v[10:11], v[14:15], v[88:89] op_sel_hi:[1,0]
	v_pk_mul_f32 v[12:13], v[16:17], v[88:89] op_sel_hi:[1,0]
	s_waitcnt vmcnt(5)
	v_pk_mul_f32 v[14:15], v[18:19], v[90:91] op_sel_hi:[1,0]
	v_pk_mul_f32 v[16:17], v[20:21], v[90:91] op_sel_hi:[1,0]
	s_waitcnt vmcnt(4)
	v_pk_mul_f32 v[18:19], v[22:23], v[92:93] op_sel_hi:[1,0]
	v_pk_mul_f32 v[20:21], v[24:25], v[92:93] op_sel_hi:[1,0]
	s_waitcnt vmcnt(2)
	v_pk_mul_f32 v[22:23], v[26:27], v[94:95] op_sel_hi:[1,0]
	ds_write2_b32 v66, v2, v3 offset1:1
	ds_write2_b32 v67, v4, v5 offset1:1
	ds_write2_b32 v68, v6, v7 offset1:1
	ds_write2_b32 v69, v8, v9 offset1:1
	ds_write2_b32 v70, v10, v11 offset1:1
	ds_write2_b32 v71, v12, v13 offset1:1
	ds_write2_b32 v85, v14, v15 offset1:1
	ds_write2_b32 v85, v16, v17 offset0:2 offset1:3
	ds_write2_b32 v87, v18, v19 offset1:1
	ds_write2_b32 v89, v20, v21 offset1:1
	ds_write2_b32 v91, v22, v23 offset1:1
	v_pk_mul_f32 v[2:3], v[28:29], v[94:95] op_sel_hi:[1,0]
	v_add_u32_e32 v4, 0x848, v85
	ds_write2_b32 v4, v2, v3 offset1:1
	s_waitcnt vmcnt(0)
	v_pk_mul_f32 v[2:3], v[30:31], v[96:97] op_sel_hi:[1,0]
	v_add_u32_e32 v4, 0xc60, v85
	ds_write2_b32 v4, v2, v3 offset1:1
	v_pk_mul_f32 v[2:3], v[32:33], v[96:97] op_sel_hi:[1,0]
	v_add_u32_e32 v4, 0xc68, v85
	ds_write2_b32 v4, v2, v3 offset1:1
	s_waitcnt lgkmcnt(0)
	ds_read2_b32 v[6:7], v60 offset0:33 offset1:41
	ds_read2_b32 v[8:9], v60 offset1:8
	ds_read2_b32 v[10:11], v60 offset0:66 offset1:74
	ds_read2_b32 v[12:13], v60 offset0:99 offset1:107
	ds_read2_b32 v[14:15], v60 offset0:132 offset1:140
	ds_read2_b32 v[16:17], v60 offset0:165 offset1:173
	ds_read2_b32 v[18:19], v60 offset0:198 offset1:206
	ds_read2_b32 v[20:21], v60 offset0:231 offset1:239
	s_waitcnt lgkmcnt(6)
	v_cvt_pk_bf16_f32 v2, v8, v6
	v_or_b32_e32 v6, v34, v57
	v_lshlrev_b32_e32 v22, 13, v6
	v_mov_b32_e32 v23, v37
	v_lshl_add_u64 v[22:23], s[22:23], 0, v[22:23]
	v_lshlrev_b32_e32 v24, 1, v55
	v_mov_b32_e32 v25, v37
	v_lshl_add_u64 v[22:23], v[22:23], 0, v[24:25]
	v_mov_b32_e32 v55, v37
	v_lshl_add_u64 v[22:23], v[22:23], 0, v[54:55]
	v_add_co_u32_e32 v22, vcc, s80, v22
	s_waitcnt lgkmcnt(4)
	v_cvt_pk_bf16_f32 v3, v10, v12
	s_waitcnt lgkmcnt(2)
	v_cvt_pk_bf16_f32 v4, v14, v16
	s_waitcnt lgkmcnt(0)
	v_cvt_pk_bf16_f32 v5, v18, v20
	v_addc_co_u32_e32 v23, vcc, 0, v23, vcc
	v_or_b32_e32 v6, v53, v57
	global_store_dwordx4 v[22:23], v[2:5], off nt
	v_lshlrev_b32_e32 v6, 13, v6
	s_nop 0
	v_cvt_pk_bf16_f32 v2, v9, v7
	v_mov_b32_e32 v7, v37
	v_lshl_add_u64 v[6:7], s[22:23], 0, v[6:7]
	v_lshl_add_u64 v[6:7], v[6:7], 0, v[24:25]
	v_lshl_add_u64 v[6:7], v[6:7], 0, v[54:55]
	v_add_co_u32_e32 v6, vcc, s80, v6
	v_cvt_pk_bf16_f32 v3, v11, v13
	v_cvt_pk_bf16_f32 v4, v15, v17
	v_cvt_pk_bf16_f32 v5, v19, v21
	v_addc_co_u32_e32 v7, vcc, 0, v7, vcc
	ds_read2_b32 v[8:9], v60 offset0:49 offset1:57
	ds_read2_b32 v[10:11], v60 offset0:16 offset1:24
	ds_read2_b32 v[12:13], v60 offset0:82 offset1:90
	ds_read2_b32 v[14:15], v60 offset0:115 offset1:123
	ds_read2_b32 v[16:17], v60 offset0:148 offset1:156
	ds_read2_b32 v[18:19], v60 offset0:181 offset1:189
	ds_read2_b32 v[20:21], v60 offset0:214 offset1:222
	ds_read2_b32 v[22:23], v60 offset0:247 offset1:255
	global_store_dwordx4 v[6:7], v[2:5], off nt
	v_or_b32_e32 v6, v58, v57
	v_lshlrev_b32_e32 v6, 13, v6
	v_mov_b32_e32 v7, v37
	v_lshl_add_u64 v[6:7], s[22:23], 0, v[6:7]
	v_lshl_add_u64 v[6:7], v[6:7], 0, v[24:25]
	v_lshl_add_u64 v[6:7], v[6:7], 0, v[54:55]
	v_add_co_u32_e32 v6, vcc, s80, v6
	s_waitcnt lgkmcnt(6)
	v_cvt_pk_bf16_f32 v2, v10, v8
	s_waitcnt lgkmcnt(4)
	v_cvt_pk_bf16_f32 v3, v12, v14
	s_waitcnt lgkmcnt(2)
	v_cvt_pk_bf16_f32 v4, v16, v18
	s_waitcnt lgkmcnt(0)
	v_cvt_pk_bf16_f32 v5, v20, v22
	v_addc_co_u32_e32 v7, vcc, 0, v7, vcc
	global_store_dwordx4 v[6:7], v[2:5], off nt
	v_or_b32_e32 v6, v59, v57
	v_lshlrev_b32_e32 v6, 13, v6
	v_mov_b32_e32 v7, v37
	v_lshl_add_u64 v[6:7], s[22:23], 0, v[6:7]
	v_lshl_add_u64 v[6:7], v[6:7], 0, v[24:25]
	v_lshl_add_u64 v[6:7], v[6:7], 0, v[54:55]
	v_add_co_u32_e32 v6, vcc, 0x1000, v6
	v_cvt_pk_bf16_f32 v2, v11, v9
	v_cvt_pk_bf16_f32 v3, v13, v15
	v_cvt_pk_bf16_f32 v4, v17, v19
	v_cvt_pk_bf16_f32 v5, v21, v23
	v_addc_co_u32_e32 v7, vcc, 0, v7, vcc
	global_store_dwordx4 v[6:7], v[2:5], off nt
	s_waitcnt lgkmcnt(0)

; #define LAS __attribute__((address_space(3)))
; DI unsigned cvtpk(float lo, float hi) { f32x2 v = {lo, hi}; bf16x2_t b = __builtin_convertvector(v, bf16x2_t); return __builtin_bit_cast(unsigned, b); }
; template <int KIND> DI int map_n(int n) {
;     ...
;     if (KIND == 5) return 2 * n;
; template <int KIND>
; DI void transpose_item(const float* W, int K, int N, bf16_t* WT, int ldk, const float* g0, const float* g1, const float* g2, LAS float* scr, int item, int lane) {
;     const int nblk = N / 32, kb = item / nblk, nb = item % nblk, k0 = 64 * kb, n0 = 32 * nb;
;     f32x4 tv[8];
; #pragma unroll
;     for (int i = 0; i < 8; ++i) tv[i] = *(const f32x4*)(W + (size_t)(k0 + 8 * i + (lane >> 3)) * N + n0 + 4 * (lane & 7));
; #pragma unroll
;     for (int i = 0; i < 8; ++i) {
;         const int kk = 8 * i + (lane >> 3), k = k0 + kk;
;         float gn = 1.f;
;         if (KIND == 0 || KIND == 1 || KIND == 2 || KIND == 5 || KIND == 6) gn = g0[k];
;         if (KIND == 4) gn = k < 1024 ? g0[k] : (k < 1536 ? g1[k - 1024] : g2[k - 1536]);
;         LAS float* d = scr + kk * 33 + 4 * (lane & 7);
;         d[0] = tv[i][0] * gn; d[1] = tv[i][1] * gn; d[2] = tv[i][2] * gn; d[3] = tv[i][3] * gn;
;     }
;     asm volatile("s_waitcnt lgkmcnt(0)" ::: "memory");
;     int kd0 = k0;
;     if (KIND == 4) kd0 = k0 < 1024 ? k0 + 512 : (k0 < 1536 ? k0 - 1024 : k0);
;     const int c = lane & 7;
; #pragma unroll
;     for (int j = 0; j < 4; ++j) { const int n = (lane >> 3) + 8 * j; const LAS float* s = scr + (8 * c) * 33 + n;
;         u32x4 o; o.x = cvtpk(s[0 * 33], s[1 * 33]); o.y = cvtpk(s[2 * 33], s[3 * 33]); o.z = cvtpk(s[4 * 33], s[5 * 33]); o.w = cvtpk(s[6 * 33], s[7 * 33]);
;         *(u32x4*)(WT + (size_t)map_n<KIND>(n0 + n) * ldk + kd0 + 8 * c) = o; }
;     asm volatile("s_waitcnt lgkmcnt(0)" ::: "memory");
; }
; DI void convert_weights(PP p, LAS unsigned char* lds, int l, int worker, int nworkers) {
;     ...
;         if (r < I_G) { transpose_item<5>(p->in[22] + (size_t)l * 2048 * DFF_, 2048, DFF_, (bf16_t*)(wl + W_GU), 2048, p->in[21] + l * 2048, nullptr, nullptr, scr, r, lane); continue; } r -= I_G;
.LBB0_64:
	s_andn2_saveexec_b64 s[12:13], s[8:9]
	s_cbranch_execz .LBB0_66
	v_add_u16_e32 v2, 0xe940, v1
	v_mul_u32_u24_e32 v3, 0xba2f, v2
	s_load_dwordx4 s[8:11], s[4:5], 0xa8
	v_lshrrev_b32_e32 v3, 23, v3
	v_mul_lo_u16_e32 v4, 0xb0, v3
	v_sub_u16_e32 v2, v2, v4
	v_lshlrev_b16_e32 v55, 6, v3
	v_lshlrev_b16_e32 v57, 5, v2
	v_or_b32_e32 v20, v34, v55
	v_lshlrev_b32_e32 v2, 2, v57
	v_mov_b32_e32 v3, v37
	s_waitcnt lgkmcnt(0)
	v_lshl_add_u64 v[2:3], s[10:11], 0, v[2:3]
	v_mul_u32_u24_e32 v4, 0x1600, v20
	v_lshl_add_u64 v[2:3], v[2:3], 0, v[36:37]
	v_lshlrev_b32_e32 v4, 2, v4
	v_mov_b32_e32 v5, v37
	v_lshl_add_u64 v[30:31], v[2:3], 0, v[4:5]
	v_add_co_u32_e32 v6, vcc, s73, v30
	v_lshlrev_b32_e32 v32, 2, v20
	s_nop 0
	v_addc_co_u32_e32 v7, vcc, 0, v31, vcc
	v_add_co_u32_e32 v10, vcc, s74, v30
	global_load_dwordx4 v[2:5], v[30:31], off nt
	s_nop 0
	global_load_dwordx4 v[6:9], v[6:7], off nt
	v_addc_co_u32_e32 v11, vcc, 0, v31, vcc
	v_add_co_u32_e32 v14, vcc, s75, v30
	v_add_u32_e32 v85, v35, v61
	s_nop 0
	v_addc_co_u32_e32 v15, vcc, 0, v31, vcc
	v_add_co_u32_e32 v18, vcc, s76, v30
	global_load_dwordx4 v[10:13], v[10:11], off nt
	s_nop 0
	global_load_dwordx4 v[14:17], v[14:15], off nt
	v_addc_co_u32_e32 v19, vcc, 0, v31, vcc
	v_add_co_u32_e32 v22, vcc, s77, v30
	global_load_dword v56, v32, s[8:9]
	s_nop 0
	v_addc_co_u32_e32 v23, vcc, 0, v31, vcc
	v_add_co_u32_e32 v26, vcc, s78, v30
	global_load_dwordx4 v[18:21], v[18:19], off nt
	s_nop 0
	global_load_dwordx4 v[22:25], v[22:23], off nt
	s_nop 0
	global_load_dword v84, v32, s[8:9] offset:32
	global_load_dword v86, v32, s[8:9] offset:64
	global_load_dword v88, v32, s[8:9] offset:96
	global_load_dword v90, v32, s[8:9] offset:128
	v_addc_co_u32_e32 v27, vcc, 0, v31, vcc
	v_add_co_u32_e32 v30, vcc, s79, v30
	global_load_dword v92, v32, s[8:9] offset:160
	s_nop 0
	global_load_dwordx4 v[26:29], v[26:27], off nt
	s_nop 0
	global_load_dword v94, v32, s[8:9] offset:192
	v_addc_co_u32_e32 v31, vcc, 0, v31, vcc
	global_load_dword v96, v32, s[8:9] offset:224
	s_nop 0
	global_load_dwordx4 v[30:33], v[30:31], off nt
	v_add_u32_e32 v87, 0x420, v85
	v_add_u32_e32 v89, 0x428, v85
	v_add_u32_e32 v91, 0x840, v85
	s_waitcnt vmcnt(11)
	v_pk_mul_f32 v[2:3], v[2:3], v[56:57] op_sel_hi:[1,0]
	v_pk_mul_f32 v[4:5], v[4:5], v[56:57] op_sel_hi:[1,0]
	ds_write2_b32 v65, v2, v3 offset1:1
	ds_write2_b32 v65, v4, v5 offset0:2 offset1:3
	s_waitcnt vmcnt(8)
	v_pk_mul_f32 v[2:3], v[6:7], v[84:85] op_sel_hi:[1,0]
	v_pk_mul_f32 v[4:5], v[8:9], v[84:85] op_sel_hi:[1,0]
	s_waitcnt vmcnt(7)
	v_pk_mul_f32 v[6:7], v[10:11], v[86:87] op_sel_hi:[1,0]
	v_pk_mul_f32 v[8:9], v[12:13], v[86:87] op_sel_hi:[1,0]
	s_waitcnt vmcnt(6)
	v_pk_mul_f32 v[10:11], v[14:15], v[88:89] op_sel_hi:[1,0]
	v_pk_mul_f32 v[12:13], v[16:17], v[88:89] op_sel_hi:[1,0]
	s_waitcnt vmcnt(5)
	v_pk_mul_f32 v[14:15], v[18:19], v[90:91] op_sel_hi:[1,0]
	v_pk_mul_f32 v[16:17], v[20:21], v[90:91] op_sel_hi:[1,0]
	s_waitcnt vmcnt(4)
	v_pk_mul_f32 v[18:19], v[22:23], v[92:93] op_sel_hi:[1,0]
	v_pk_mul_f32 v[20:21], v[24:25], v[92:93] op_sel_hi:[1,0]
	s_waitcnt vmcnt(2)
	v_pk_mul_f32 v[22:23], v[26:27], v[94:95] op_sel_hi:[1,0]
	v_pk_mul_f32 v[24:25], v[28:29], v[94:95] op_sel_hi:[1,0]
	ds_write2_b32 v66, v2, v3 offset1:1
	ds_write2_b32 v67, v4, v5 offset1:1
	ds_write2_b32 v68, v6, v7 offset1:1
	ds_write2_b32 v69, v8, v9 offset1:1
	ds_write2_b32 v70, v10, v11 offset1:1
	ds_write2_b32 v71, v12, v13 offset1:1
	ds_write2_b32 v85, v14, v15 offset1:1
	ds_write2_b32 v85, v16, v17 offset0:2 offset1:3
	ds_write2_b32 v87, v18, v19 offset1:1
	ds_write2_b32 v89, v20, v21 offset1:1
	ds_write2_b32 v91, v22, v23 offset1:1
	v_add_u32_e32 v2, 0x848, v85
	ds_write2_b32 v2, v24, v25 offset1:1
	s_waitcnt vmcnt(0)
	v_pk_mul_f32 v[2:3], v[30:31], v[96:97] op_sel_hi:[1,0]
	v_add_u32_e32 v4, 0xc60, v85
	ds_write2_b32 v4, v2, v3 offset1:1
	v_pk_mul_f32 v[2:3], v[32:33], v[96:97] op_sel_hi:[1,0]
	v_add_u32_e32 v4, 0xc68, v85
	ds_write2_b32 v4, v2, v3 offset1:1
	s_waitcnt lgkmcnt(0)
	ds_read2_b32 v[6:7], v60 offset0:33 offset1:41
	ds_read2_b32 v[8:9], v60 offset1:8
	ds_read2_b32 v[10:11], v60 offset0:66 offset1:74
	ds_read2_b32 v[12:13], v60 offset0:99 offset1:107
	ds_read2_b32 v[14:15], v60 offset0:132 offset1:140
	ds_read2_b32 v[16:17], v60 offset0:165 offset1:173
	ds_read2_b32 v[18:19], v60 offset0:198 offset1:206
	ds_read2_b32 v[20:21], v60 offset0:231 offset1:239
	v_lshlrev_b32_e32 v2, 1, v55
	v_mov_b32_e32 v3, v37
	v_lshl_add_u64 v[22:23], v[40:41], 0, v[2:3]
	s_waitcnt lgkmcnt(6)
	v_cvt_pk_bf16_f32 v2, v8, v6
	v_or_b32_e32 v6, v34, v57
	v_lshlrev_b32_e32 v24, 13, v6
	v_mov_b32_e32 v25, v37
	s_waitcnt lgkmcnt(4)
	v_cvt_pk_bf16_f32 v3, v10, v12
	s_waitcnt lgkmcnt(2)
	v_cvt_pk_bf16_f32 v4, v14, v16
	s_waitcnt lgkmcnt(0)
	v_cvt_pk_bf16_f32 v5, v18, v20
	v_lshl_add_u64 v[24:25], v[22:23], 0, v[24:25]
	global_store_dwordx4 v[24:25], v[2:5], off nt
	v_or_b32_e32 v6, v53, v57
	v_lshlrev_b32_e32 v6, 13, v6
	v_cvt_pk_bf16_f32 v2, v9, v7
	v_cvt_pk_bf16_f32 v3, v11, v13
	v_cvt_pk_bf16_f32 v4, v15, v17
	v_cvt_pk_bf16_f32 v5, v19, v21
	ds_read2_b32 v[8:9], v60 offset0:49 offset1:57
	ds_read2_b32 v[10:11], v60 offset0:16 offset1:24
	ds_read2_b32 v[12:13], v60 offset0:82 offset1:90
	ds_read2_b32 v[14:15], v60 offset0:115 offset1:123
	ds_read2_b32 v[16:17], v60 offset0:148 offset1:156
	ds_read2_b32 v[18:19], v60 offset0:181 offset1:189
	ds_read2_b32 v[20:21], v60 offset0:214 offset1:222
	ds_read2_b32 v[24:25], v60 offset0:247 offset1:255
	v_mov_b32_e32 v7, v37
	v_lshl_add_u64 v[6:7], v[22:23], 0, v[6:7]
	global_store_dwordx4 v[6:7], v[2:5], off nt
	v_or_b32_e32 v6, v58, v57
	v_lshlrev_b32_e32 v6, 13, v6
	v_mov_b32_e32 v7, v37
	s_waitcnt lgkmcnt(6)
	v_cvt_pk_bf16_f32 v2, v10, v8
	s_waitcnt lgkmcnt(4)
	v_cvt_pk_bf16_f32 v3, v12, v14
	s_waitcnt lgkmcnt(2)
	v_cvt_pk_bf16_f32 v4, v16, v18
	s_waitcnt lgkmcnt(0)
	v_cvt_pk_bf16_f32 v5, v20, v24
	v_lshl_add_u64 v[6:7], v[22:23], 0, v[6:7]
	global_store_dwordx4 v[6:7], v[2:5], off nt
	v_or_b32_e32 v6, v59, v57
	v_lshlrev_b32_e32 v6, 13, v6
	v_mov_b32_e32 v7, v37
	v_cvt_pk_bf16_f32 v2, v11, v9
	v_cvt_pk_bf16_f32 v3, v13, v15
	v_cvt_pk_bf16_f32 v4, v17, v19
	v_cvt_pk_bf16_f32 v5, v21, v25
	v_lshl_add_u64 v[6:7], v[22:23], 0, v[6:7]
	global_store_dwordx4 v[6:7], v[2:5], off nt
	s_waitcnt lgkmcnt(0)

; #define LAS __attribute__((address_space(3)))
; DI unsigned cvtpk(float lo, float hi) { f32x2 v = {lo, hi}; bf16x2_t b = __builtin_convertvector(v, bf16x2_t); return __builtin_bit_cast(unsigned, b); }
; template <int KIND>
; DI void transpose_item(const float* W, int K, int N, bf16_t* WT, int ldk, const float* g0, const float* g1, const float* g2, LAS float* scr, int item, int lane) {
;     ...
;         LAS float* d = scr + kk * 33 + 4 * (lane & 7);
;         d[0] = tv[i][0] * gn; d[1] = tv[i][1] * gn; d[2] = tv[i][2] * gn; d[3] = tv[i][3] * gn;
;     }
;     asm volatile("s_waitcnt lgkmcnt(0)" ::: "memory");
;     int kd0 = k0;
;     if (KIND == 4) kd0 = k0 < 1024 ? k0 + 512 : (k0 < 1536 ? k0 - 1024 : k0);
;     const int c = lane & 7;
; #pragma unroll
;     for (int j = 0; j < 4; ++j) { const int n = (lane >> 3) + 8 * j; const LAS float* s = scr + (8 * c) * 33 + n;
;         u32x4 o; o.x = cvtpk(s[0 * 33], s[1 * 33]); o.y = cvtpk(s[2 * 33], s[3 * 33]); o.z = cvtpk(s[4 * 33], s[5 * 33]); o.w = cvtpk(s[6 * 33], s[7 * 33]);
;         *(u32x4*)(WT + (size_t)map_n<KIND>(n0 + n) * ldk + kd0 + 8 * c) = o; }
.LBB0_130:
	s_andn2_saveexec_b64 s[6:7], s[8:9]
	v_mov_b32_e32 v31, v37
	v_lshl_add_u64 v[6:7], s[12:13], 0, v[30:31]
	v_lshl_add_u64 v[6:7], v[6:7], 0, s[54:55]
	s_or_b64 exec, exec, s[6:7]
	global_load_dword v6, v[6:7], off
	s_movk_i32 s6, 0x600
	v_add_u32_e32 v7, 0xc60, v18
	v_add_u32_e32 v10, 0xfffffc00, v84
	v_cmp_gt_u32_e64 s[6:7], s6, v55
	v_add_u32_e32 v8, 0x200, v84
	v_add_u32_e32 v26, 0xc68, v18
	v_cndmask_b32_e64 v19, v84, v10, s[6:7]
	v_mov_b32_e32 v9, v37
	v_or_b32_e32 v12, v85, v34
	v_or_b32_e32 v14, v85, v53
	v_or_b32_e32 v16, v85, v58
	v_or_b32_e32 v18, v85, v59
	v_cndmask_b32_e32 v8, v19, v8, vcc
	v_mov_b32_e32 v11, v37
	v_mov_b32_e32 v13, v37
	v_mov_b32_e32 v15, v37
	v_mov_b32_e32 v17, v37
	v_lshlrev_b32_e32 v10, 12, v12
	v_lshlrev_b32_e32 v12, 12, v14
	v_lshlrev_b32_e32 v14, 12, v16
	v_lshlrev_b32_e32 v16, 12, v18
	v_lshl_add_u64 v[8:9], v[8:9], 1, v[42:43]
	v_lshl_add_u64 v[18:19], v[8:9], 0, v[10:11]
	v_lshl_add_u64 v[20:21], v[8:9], 0, v[12:13]
	v_lshl_add_u64 v[22:23], v[8:9], 0, v[14:15]
	v_lshl_add_u64 v[24:25], v[8:9], 0, v[16:17]
	s_waitcnt vmcnt(0)
	v_pk_mul_f32 v[2:3], v[2:3], v[6:7] op_sel_hi:[1,0]
	v_pk_mul_f32 v[4:5], v[4:5], v[6:7] op_sel_hi:[1,0]
	ds_write2_b32 v7, v2, v3 offset1:1
	ds_write2_b32 v26, v4, v5 offset1:1
	s_waitcnt lgkmcnt(0)
	ds_read2_b32 v[6:7], v60 offset0:33 offset1:41
	ds_read2_b32 v[8:9], v60 offset1:8
	ds_read2_b32 v[10:11], v60 offset0:66 offset1:74
	ds_read2_b32 v[12:13], v60 offset0:99 offset1:107
	ds_read2_b32 v[14:15], v60 offset0:132 offset1:140
	ds_read2_b32 v[16:17], v60 offset0:165 offset1:173
	ds_read2_b32 v[26:27], v60 offset0:198 offset1:206
	ds_read2_b32 v[28:29], v60 offset0:231 offset1:239
	ds_read2_b32 v[30:31], v60 offset0:49 offset1:57
	ds_read2_b32 v[32:33], v60 offset0:16 offset1:24
	ds_read2_b32 v[56:57], v60 offset0:82 offset1:90
	ds_read2_b32 v[84:85], v60 offset0:115 offset1:123
	ds_read2_b32 v[86:87], v60 offset0:148 offset1:156
	ds_read2_b32 v[88:89], v60 offset0:181 offset1:189
	ds_read2_b32 v[90:91], v60 offset0:214 offset1:222
	ds_read2_b32 v[92:93], v60 offset0:247 offset1:255
	s_waitcnt lgkmcnt(14)
	v_cvt_pk_bf16_f32 v2, v8, v6
	s_waitcnt lgkmcnt(12)
	v_cvt_pk_bf16_f32 v3, v10, v12
	s_waitcnt lgkmcnt(10)
	v_cvt_pk_bf16_f32 v4, v14, v16
	s_waitcnt lgkmcnt(8)
	v_cvt_pk_bf16_f32 v5, v26, v28
	v_cvt_pk_bf16_f32 v6, v9, v7
	v_cvt_pk_bf16_f32 v7, v11, v13
	v_cvt_pk_bf16_f32 v8, v15, v17
	v_cvt_pk_bf16_f32 v9, v27, v29
	s_waitcnt lgkmcnt(6)
	v_cvt_pk_bf16_f32 v10, v32, v30
	s_waitcnt lgkmcnt(4)
	v_cvt_pk_bf16_f32 v11, v56, v84
	s_waitcnt lgkmcnt(2)
	v_cvt_pk_bf16_f32 v12, v86, v88
	s_waitcnt lgkmcnt(0)
	v_cvt_pk_bf16_f32 v13, v90, v92
	v_cvt_pk_bf16_f32 v14, v33, v31
	v_cvt_pk_bf16_f32 v15, v57, v85
	v_cvt_pk_bf16_f32 v16, v87, v89
	v_cvt_pk_bf16_f32 v17, v91, v93
	global_store_dwordx4 v[18:19], v[2:5], off nt
	global_store_dwordx4 v[20:21], v[6:9], off nt
	global_store_dwordx4 v[22:23], v[10:13], off nt
	global_store_dwordx4 v[24:25], v[14:17], off nt
	s_waitcnt lgkmcnt(0)

; #define LAS __attribute__((address_space(3)))
; DI unsigned cvtpk(float lo, float hi) { f32x2 v = {lo, hi}; bf16x2_t b = __builtin_convertvector(v, bf16x2_t); return __builtin_bit_cast(unsigned, b); }
; template <int KIND> DI int map_n(int n) {
;     ...
;     if (KIND == 3) return n < 512 ? 2 * n : 2 * (n - 512) + 1;
; template <int KIND>
; DI void transpose_item(const float* W, int K, int N, bf16_t* WT, int ldk, const float* g0, const float* g1, const float* g2, LAS float* scr, int item, int lane) {
;     const int nblk = N / 32, kb = item / nblk, nb = item % nblk, k0 = 64 * kb, n0 = 32 * nb;
;     f32x4 tv[8];
; #pragma unroll
;     for (int i = 0; i < 8; ++i) tv[i] = *(const f32x4*)(W + (size_t)(k0 + 8 * i + (lane >> 3)) * N + n0 + 4 * (lane & 7));
; #pragma unroll
;     for (int i = 0; i < 8; ++i) {
;         const int kk = 8 * i + (lane >> 3), k = k0 + kk;
;         float gn = 1.f;
;         if (KIND == 0 || KIND == 1 || KIND == 2 || KIND == 5 || KIND == 6) gn = g0[k];
;         if (KIND == 4) gn = k < 1024 ? g0[k] : (k < 1536 ? g1[k - 1024] : g2[k - 1536]);
;         LAS float* d = scr + kk * 33 + 4 * (lane & 7);
;         d[0] = tv[i][0] * gn; d[1] = tv[i][1] * gn; d[2] = tv[i][2] * gn; d[3] = tv[i][3] * gn;
;     }
;     asm volatile("s_waitcnt lgkmcnt(0)" ::: "memory");
;     int kd0 = k0;
;     if (KIND == 4) kd0 = k0 < 1024 ? k0 + 512 : (k0 < 1536 ? k0 - 1024 : k0);
;     const int c = lane & 7;
; #pragma unroll
;     for (int j = 0; j < 4; ++j) { const int n = (lane >> 3) + 8 * j; const LAS float* s = scr + (8 * c) * 33 + n;
;         u32x4 o; o.x = cvtpk(s[0 * 33], s[1 * 33]); o.y = cvtpk(s[2 * 33], s[3 * 33]); o.z = cvtpk(s[4 * 33], s[5 * 33]); o.w = cvtpk(s[6 * 33], s[7 * 33]);
;         *(u32x4*)(WT + (size_t)map_n<KIND>(n0 + n) * ldk + kd0 + 8 * c) = o; }
;     asm volatile("s_waitcnt lgkmcnt(0)" ::: "memory");
; }
; DI void convert_weights(PP p, LAS unsigned char* lds, int l, int worker, int nworkers) {
;     ...
;         if (r < I_GLU) { transpose_item<3>(p->in[15] + (size_t)l * 512 * 1024, 512, 1024, (bf16_t*)(wl + W_GLU), 512, nullptr, nullptr, nullptr, scr, r, lane); continue; } r -= I_GLU;
.LBB0_134:
	s_andn2_saveexec_b64 s[8:9], s[62:63]
	s_cbranch_execz .LBB0_136
	s_load_dwordx2 s[6:7], s[4:5], 0x78
	v_add_u32_e32 v2, 0xfffe4800, v52
	v_and_b32_e32 v88, 0x3e0, v2
	v_and_b32_e32 v55, 0x1c0, v64
	v_lshlrev_b32_e32 v2, 2, v88
	v_mov_b32_e32 v3, v37
	v_or_b32_e32 v4, v55, v34
	s_waitcnt lgkmcnt(0)
	v_lshl_add_u64 v[2:3], s[6:7], 0, v[2:3]
	v_lshl_add_u64 v[2:3], v[2:3], 0, v[36:37]
	v_lshlrev_b32_e32 v4, 12, v4
	v_mov_b32_e32 v5, v37
	v_lshl_add_u64 v[30:31], v[2:3], 0, v[4:5]
	s_mov_b32 s6, 0x8000
	v_add_co_u32_e32 v6, vcc, s6, v30
	s_mov_b32 s6, 0x28000
	s_nop 0
	v_addc_co_u32_e32 v7, vcc, 0, v31, vcc
	v_add_co_u32_e32 v10, vcc, s66, v30
	global_load_dwordx4 v[2:5], v[30:31], off nt
	s_nop 0
	global_load_dwordx4 v[6:9], v[6:7], off nt
	v_addc_co_u32_e32 v11, vcc, 0, v31, vcc
	v_add_co_u32_e32 v14, vcc, s82, v30
	v_lshlrev_b32_e32 v56, 1, v55
	s_nop 0
	v_addc_co_u32_e32 v15, vcc, 0, v31, vcc
	global_load_dwordx4 v[10:13], v[10:11], off nt
	s_nop 0
	global_load_dwordx4 v[14:17], v[14:15], off nt
	v_add_co_u32_e32 v18, vcc, s67, v30
	v_or_b32_e32 v55, v88, v34
	s_nop 0
	v_addc_co_u32_e32 v19, vcc, 0, v31, vcc
	global_load_dwordx4 v[18:21], v[18:19], off nt
	v_add_co_u32_e32 v26, vcc, s6, v30
	v_add_co_u32_e64 v22, s[6:7], s68, v30
	s_nop 0
	v_addc_co_u32_e32 v27, vcc, 0, v31, vcc
	v_addc_co_u32_e64 v23, s[6:7], 0, v31, s[6:7]
	global_load_dwordx4 v[22:25], v[22:23], off nt
	s_mov_b32 s6, 0x38000
	global_load_dwordx4 v[26:29], v[26:27], off nt
	v_add_co_u32_e32 v30, vcc, s6, v30
	s_movk_i32 s6, 0x200
	s_nop 0
	v_addc_co_u32_e32 v31, vcc, 0, v31, vcc
	global_load_dwordx4 v[30:33], v[30:31], off nt
	v_or_b32_e32 v84, v88, v53
	v_lshlrev_b32_e32 v55, 1, v55
	v_lshlrev_b32_e32 v85, 1, v84
	v_add_u32_e32 v84, 0xfffffc01, v55
	v_cmp_gt_u32_e32 vcc, s6, v88
	v_add_u32_e32 v86, 0xfffffc01, v85
	v_mov_b32_e32 v57, v37
	v_cndmask_b32_e32 v84, v84, v55, vcc
	v_cndmask_b32_e32 v86, v86, v85, vcc
	v_ashrrev_i32_e32 v85, 31, v84
	v_lshl_add_u64 v[56:57], v[44:45], 0, v[56:57]
	v_lshlrev_b64 v[84:85], 10, v[84:85]
	v_ashrrev_i32_e32 v87, 31, v86
	s_waitcnt vmcnt(7)
	ds_write2_b32 v65, v2, v3 offset1:1
	ds_write2_b32 v65, v4, v5 offset0:2 offset1:3
	s_waitcnt vmcnt(5)
	ds_write2_b32 v68, v10, v11 offset1:1
	ds_write2_b32 v69, v12, v13 offset1:1
	s_waitcnt vmcnt(3)
	ds_write2_b32 v72, v18, v19 offset1:1
	ds_write2_b32 v73, v20, v21 offset1:1
	s_waitcnt vmcnt(2)
	ds_write2_b32 v76, v22, v23 offset1:1
	ds_write2_b32 v77, v24, v25 offset1:1
	ds_write2_b32 v66, v6, v7 offset1:1
	ds_write2_b32 v67, v8, v9 offset1:1
	ds_write2_b32 v70, v14, v15 offset1:1
	ds_write2_b32 v71, v16, v17 offset1:1
	s_waitcnt vmcnt(1)
	ds_write2_b32 v74, v26, v27 offset1:1
	ds_write2_b32 v75, v28, v29 offset1:1
	s_waitcnt vmcnt(0)
	ds_write2_b32 v78, v30, v31 offset1:1
	ds_write2_b32 v79, v32, v33 offset1:1
	s_waitcnt lgkmcnt(0)
	ds_read2_b32 v[6:7], v60 offset0:33 offset1:41
	ds_read2_b32 v[8:9], v60 offset1:8
	ds_read2_b32 v[10:11], v60 offset0:66 offset1:74
	ds_read2_b32 v[12:13], v60 offset0:99 offset1:107
	ds_read2_b32 v[14:15], v60 offset0:132 offset1:140
	ds_read2_b32 v[16:17], v60 offset0:165 offset1:173
	ds_read2_b32 v[18:19], v60 offset0:198 offset1:206
	ds_read2_b32 v[20:21], v60 offset0:231 offset1:239
	v_lshl_add_u64 v[22:23], v[56:57], 0, v[84:85]
	s_waitcnt lgkmcnt(6)
	v_cvt_pk_bf16_f32 v2, v8, v6
	s_waitcnt lgkmcnt(4)
	v_cvt_pk_bf16_f32 v3, v10, v12
	s_waitcnt lgkmcnt(2)
	v_cvt_pk_bf16_f32 v4, v14, v16
	s_waitcnt lgkmcnt(0)
	v_cvt_pk_bf16_f32 v5, v18, v20
	global_store_dwordx4 v[22:23], v[2:5], off nt
	v_cvt_pk_bf16_f32 v6, v9, v7
	v_cvt_pk_bf16_f32 v7, v11, v13
	v_lshlrev_b64 v[2:3], 10, v[86:87]
	v_cvt_pk_bf16_f32 v8, v15, v17
	v_cvt_pk_bf16_f32 v9, v19, v21
	v_lshl_add_u64 v[2:3], v[56:57], 0, v[2:3]
	ds_read2_b32 v[10:11], v60 offset0:49 offset1:57
	ds_read2_b32 v[12:13], v60 offset0:16 offset1:24
	ds_read2_b32 v[14:15], v60 offset0:82 offset1:90
	ds_read2_b32 v[16:17], v60 offset0:115 offset1:123
	ds_read2_b32 v[18:19], v60 offset0:148 offset1:156
	ds_read2_b32 v[20:21], v60 offset0:181 offset1:189
	ds_read2_b32 v[22:23], v60 offset0:214 offset1:222
	ds_read2_b32 v[24:25], v60 offset0:247 offset1:255
	global_store_dwordx4 v[2:3], v[6:9], off nt
	s_waitcnt lgkmcnt(6)
	v_cvt_pk_bf16_f32 v2, v12, v10
	s_waitcnt lgkmcnt(4)
	v_cvt_pk_bf16_f32 v3, v14, v16
	v_or_b32_e32 v6, v88, v58
	v_lshlrev_b32_e32 v6, 1, v6
	v_add_u32_e32 v7, 0xfffffc01, v6
	v_cndmask_b32_e32 v6, v7, v6, vcc
	v_ashrrev_i32_e32 v7, 31, v6
	v_lshlrev_b64 v[6:7], 10, v[6:7]
	s_waitcnt lgkmcnt(2)
	v_cvt_pk_bf16_f32 v4, v18, v20
	s_waitcnt lgkmcnt(0)
	v_cvt_pk_bf16_f32 v5, v22, v24
	v_lshl_add_u64 v[6:7], v[56:57], 0, v[6:7]
	global_store_dwordx4 v[6:7], v[2:5], off nt
	v_or_b32_e32 v6, v88, v59
	v_lshlrev_b32_e32 v6, 1, v6
	v_add_u32_e32 v7, 0xfffffc01, v6
	v_cndmask_b32_e32 v6, v7, v6, vcc
	v_ashrrev_i32_e32 v7, 31, v6
	v_lshlrev_b64 v[6:7], 10, v[6:7]
	v_cvt_pk_bf16_f32 v2, v13, v11
	v_cvt_pk_bf16_f32 v3, v15, v17
	v_cvt_pk_bf16_f32 v4, v19, v21
	v_cvt_pk_bf16_f32 v5, v23, v25
	v_lshl_add_u64 v[6:7], v[56:57], 0, v[6:7]
	global_store_dwordx4 v[6:7], v[2:5], off nt
	s_waitcnt lgkmcnt(0)

; #define LAS __attribute__((address_space(3)))
; DI unsigned cvtpk(float lo, float hi) { f32x2 v = {lo, hi}; bf16x2_t b = __builtin_convertvector(v, bf16x2_t); return __builtin_bit_cast(unsigned, b); }
; template <int KIND>
; DI void transpose_item(const float* W, int K, int N, bf16_t* WT, int ldk, const float* g0, const float* g1, const float* g2, LAS float* scr, int item, int lane) {
;     const int nblk = N / 32, kb = item / nblk, nb = item % nblk, k0 = 64 * kb, n0 = 32 * nb;
;     f32x4 tv[8];
; #pragma unroll
;     for (int i = 0; i < 8; ++i) tv[i] = *(const f32x4*)(W + (size_t)(k0 + 8 * i + (lane >> 3)) * N + n0 + 4 * (lane & 7));
; #pragma unroll
;     for (int i = 0; i < 8; ++i) {
;         const int kk = 8 * i + (lane >> 3), k = k0 + kk;
;         float gn = 1.f;
;         if (KIND == 0 || KIND == 1 || KIND == 2 || KIND == 5 || KIND == 6) gn = g0[k];
;         if (KIND == 4) gn = k < 1024 ? g0[k] : (k < 1536 ? g1[k - 1024] : g2[k - 1536]);
;         LAS float* d = scr + kk * 33 + 4 * (lane & 7);
;         d[0] = tv[i][0] * gn; d[1] = tv[i][1] * gn; d[2] = tv[i][2] * gn; d[3] = tv[i][3] * gn;
;     }
;     asm volatile("s_waitcnt lgkmcnt(0)" ::: "memory");
;     int kd0 = k0;
;     if (KIND == 4) kd0 = k0 < 1024 ? k0 + 512 : (k0 < 1536 ? k0 - 1024 : k0);
;     const int c = lane & 7;
; #pragma unroll
;     for (int j = 0; j < 4; ++j) { const int n = (lane >> 3) + 8 * j; const LAS float* s = scr + (8 * c) * 33 + n;
;         u32x4 o; o.x = cvtpk(s[0 * 33], s[1 * 33]); o.y = cvtpk(s[2 * 33], s[3 * 33]); o.z = cvtpk(s[4 * 33], s[5 * 33]); o.w = cvtpk(s[6 * 33], s[7 * 33]);
;         *(u32x4*)(WT + (size_t)map_n<KIND>(n0 + n) * ldk + kd0 + 8 * c) = o; }
;     asm volatile("s_waitcnt lgkmcnt(0)" ::: "memory");
; }
; DI void convert_weights(PP p, LAS unsigned char* lds, int l, int worker, int nworkers) {
;     ...
;         if (r < I_UKV) { transpose_item<2>(p->in[6] + (size_t)l * 256 * 2048, 256, 2048, (bf16_t*)(wl + W_UKV), 256, p->in[5] + l * 256, nullptr, nullptr, scr, r, lane); continue; } r -= I_UKV;
.LBB0_137:
	s_andn2_saveexec_b64 s[6:7], s[60:61]
	s_cbranch_execz .LBB0_139
	s_load_dwordx4 s[8:11], s[4:5], 0x28
	v_add_u32_e32 v2, 0xfffff340, v1
	v_and_b32_e32 v55, 0xc0, v2
	v_add_u32_e32 v2, 0xfffe6800, v52
	v_and_b32_e32 v57, 0x7e0, v2
	v_lshlrev_b32_e32 v2, 2, v57
	v_mov_b32_e32 v3, v37
	v_or_b32_e32 v20, v55, v34
	s_waitcnt lgkmcnt(0)
	v_lshl_add_u64 v[2:3], s[10:11], 0, v[2:3]
	v_lshl_add_u64 v[2:3], v[2:3], 0, v[36:37]
	v_lshlrev_b32_e32 v4, 13, v20
	v_mov_b32_e32 v5, v37
	v_lshl_add_u64 v[30:31], v[2:3], 0, v[4:5]
	v_add_co_u32_e32 v6, vcc, s66, v30
	v_lshlrev_b32_e32 v32, 2, v20
	s_nop 0
	v_addc_co_u32_e32 v7, vcc, 0, v31, vcc
	v_add_co_u32_e32 v10, vcc, s67, v30
	global_load_dwordx4 v[2:5], v[30:31], off nt
	s_nop 0
	global_load_dwordx4 v[6:9], v[6:7], off nt
	v_addc_co_u32_e32 v11, vcc, 0, v31, vcc
	v_add_co_u32_e32 v14, vcc, s68, v30
	v_add_u32_e32 v85, v35, v61
	s_nop 0
	v_addc_co_u32_e32 v15, vcc, 0, v31, vcc
	v_add_co_u32_e32 v18, vcc, s69, v30
	global_load_dwordx4 v[10:13], v[10:11], off nt
	s_nop 0
	global_load_dwordx4 v[14:17], v[14:15], off nt
	v_addc_co_u32_e32 v19, vcc, 0, v31, vcc
	v_add_co_u32_e32 v22, vcc, s70, v30
	global_load_dword v56, v32, s[8:9]
	s_nop 0
	v_addc_co_u32_e32 v23, vcc, 0, v31, vcc
	v_add_co_u32_e32 v26, vcc, s71, v30
	global_load_dwordx4 v[18:21], v[18:19], off nt
	s_nop 0
	global_load_dwordx4 v[22:25], v[22:23], off nt
	s_nop 0
	global_load_dword v84, v32, s[8:9] offset:32
	global_load_dword v86, v32, s[8:9] offset:64
	global_load_dword v88, v32, s[8:9] offset:96
	global_load_dword v90, v32, s[8:9] offset:128
	v_addc_co_u32_e32 v27, vcc, 0, v31, vcc
	v_add_co_u32_e32 v30, vcc, s72, v30
	global_load_dword v92, v32, s[8:9] offset:160
	s_nop 0
	global_load_dwordx4 v[26:29], v[26:27], off nt
	s_nop 0
	global_load_dword v94, v32, s[8:9] offset:192
	v_addc_co_u32_e32 v31, vcc, 0, v31, vcc
	global_load_dword v96, v32, s[8:9] offset:224
	s_nop 0
	global_load_dwordx4 v[30:33], v[30:31], off nt
	v_add_u32_e32 v87, 0x420, v85
	v_add_u32_e32 v89, 0x428, v85
	v_add_u32_e32 v91, 0x840, v85
	v_add_u32_e32 v93, 0x848, v85
	s_waitcnt vmcnt(11)
	v_pk_mul_f32 v[2:3], v[2:3], v[56:57] op_sel_hi:[1,0]
	v_pk_mul_f32 v[4:5], v[4:5], v[56:57] op_sel_hi:[1,0]
	ds_write2_b32 v65, v2, v3 offset1:1
	ds_write2_b32 v65, v4, v5 offset0:2 offset1:3
	s_waitcnt vmcnt(8)
	v_pk_mul_f32 v[2:3], v[6:7], v[84:85] op_sel_hi:[1,0]
	v_pk_mul_f32 v[4:5], v[8:9], v[84:85] op_sel_hi:[1,0]
	s_waitcnt vmcnt(7)
	v_pk_mul_f32 v[6:7], v[10:11], v[86:87] op_sel_hi:[1,0]
	v_pk_mul_f32 v[8:9], v[12:13], v[86:87] op_sel_hi:[1,0]
	s_waitcnt vmcnt(6)
	v_pk_mul_f32 v[10:11], v[14:15], v[88:89] op_sel_hi:[1,0]
	v_pk_mul_f32 v[12:13], v[16:17], v[88:89] op_sel_hi:[1,0]
	s_waitcnt vmcnt(5)
	v_pk_mul_f32 v[14:15], v[18:19], v[90:91] op_sel_hi:[1,0]
	v_pk_mul_f32 v[16:17], v[20:21], v[90:91] op_sel_hi:[1,0]
	s_waitcnt vmcnt(4)
	v_pk_mul_f32 v[18:19], v[22:23], v[92:93] op_sel_hi:[1,0]
	v_pk_mul_f32 v[20:21], v[24:25], v[92:93] op_sel_hi:[1,0]
	s_waitcnt vmcnt(2)
	v_pk_mul_f32 v[22:23], v[26:27], v[94:95] op_sel_hi:[1,0]
	v_pk_mul_f32 v[24:25], v[28:29], v[94:95] op_sel_hi:[1,0]
	ds_write2_b32 v66, v2, v3 offset1:1
	ds_write2_b32 v67, v4, v5 offset1:1
	ds_write2_b32 v68, v6, v7 offset1:1
	ds_write2_b32 v69, v8, v9 offset1:1
	ds_write2_b32 v70, v10, v11 offset1:1
	ds_write2_b32 v71, v12, v13 offset1:1
	ds_write2_b32 v85, v14, v15 offset1:1
	ds_write2_b32 v85, v16, v17 offset0:2 offset1:3
	ds_write2_b32 v87, v18, v19 offset1:1
	ds_write2_b32 v89, v20, v21 offset1:1
	ds_write2_b32 v91, v22, v23 offset1:1
	ds_write2_b32 v93, v24, v25 offset1:1
	s_waitcnt vmcnt(0)
	v_pk_mul_f32 v[2:3], v[30:31], v[96:97] op_sel_hi:[1,0]
	v_add_u32_e32 v4, 0xc60, v85
	ds_write2_b32 v4, v2, v3 offset1:1
	v_pk_mul_f32 v[2:3], v[32:33], v[96:97] op_sel_hi:[1,0]
	v_add_u32_e32 v4, 0xc68, v85
	ds_write2_b32 v4, v2, v3 offset1:1
	s_waitcnt lgkmcnt(0)
	ds_read2_b32 v[6:7], v60 offset0:33 offset1:41
	ds_read2_b32 v[8:9], v60 offset1:8
	ds_read2_b32 v[10:11], v60 offset0:66 offset1:74
	ds_read2_b32 v[12:13], v60 offset0:99 offset1:107
	ds_read2_b32 v[14:15], v60 offset0:132 offset1:140
	ds_read2_b32 v[16:17], v60 offset0:165 offset1:173
	ds_read2_b32 v[18:19], v60 offset0:198 offset1:206
	ds_read2_b32 v[20:21], v60 offset0:231 offset1:239
	v_lshlrev_b32_e32 v2, 1, v55
	v_mov_b32_e32 v3, v37
	v_lshl_add_u64 v[22:23], v[46:47], 0, v[2:3]
	s_waitcnt lgkmcnt(6)
	v_cvt_pk_bf16_f32 v2, v8, v6
	v_or_b32_e32 v6, v57, v34
	v_lshlrev_b32_e32 v24, 9, v6
	v_mov_b32_e32 v25, v37
	s_waitcnt lgkmcnt(4)
	v_cvt_pk_bf16_f32 v3, v10, v12
	s_waitcnt lgkmcnt(2)
	v_cvt_pk_bf16_f32 v4, v14, v16
	s_waitcnt lgkmcnt(0)
	v_cvt_pk_bf16_f32 v5, v18, v20
	v_lshl_add_u64 v[24:25], v[22:23], 0, v[24:25]
	global_store_dwordx4 v[24:25], v[2:5], off nt
	v_or_b32_e32 v6, v57, v53
	v_lshlrev_b32_e32 v6, 9, v6
	v_cvt_pk_bf16_f32 v2, v9, v7
	v_cvt_pk_bf16_f32 v3, v11, v13
	v_cvt_pk_bf16_f32 v4, v15, v17
	v_cvt_pk_bf16_f32 v5, v19, v21
	ds_read2_b32 v[8:9], v60 offset0:49 offset1:57
	ds_read2_b32 v[10:11], v60 offset0:16 offset1:24
	ds_read2_b32 v[12:13], v60 offset0:82 offset1:90
	ds_read2_b32 v[14:15], v60 offset0:115 offset1:123
	ds_read2_b32 v[16:17], v60 offset0:148 offset1:156
	ds_read2_b32 v[18:19], v60 offset0:181 offset1:189
	ds_read2_b32 v[20:21], v60 offset0:214 offset1:222
	ds_read2_b32 v[24:25], v60 offset0:247 offset1:255
	v_mov_b32_e32 v7, v37
	v_lshl_add_u64 v[6:7], v[22:23], 0, v[6:7]
	global_store_dwordx4 v[6:7], v[2:5], off nt
	v_or_b32_e32 v6, v57, v58
	v_lshlrev_b32_e32 v6, 9, v6
	v_mov_b32_e32 v7, v37
	s_waitcnt lgkmcnt(6)
	v_cvt_pk_bf16_f32 v2, v10, v8
	s_waitcnt lgkmcnt(4)
	v_cvt_pk_bf16_f32 v3, v12, v14
	s_waitcnt lgkmcnt(2)
	v_cvt_pk_bf16_f32 v4, v16, v18
	s_waitcnt lgkmcnt(0)
	v_cvt_pk_bf16_f32 v5, v20, v24
	v_lshl_add_u64 v[6:7], v[22:23], 0, v[6:7]
	global_store_dwordx4 v[6:7], v[2:5], off nt
	v_or_b32_e32 v6, v57, v59
	v_lshlrev_b32_e32 v6, 9, v6
	v_mov_b32_e32 v7, v37
	v_cvt_pk_bf16_f32 v2, v11, v9
	v_cvt_pk_bf16_f32 v3, v13, v15
	v_cvt_pk_bf16_f32 v4, v17, v19
	v_cvt_pk_bf16_f32 v5, v21, v25
	v_lshl_add_u64 v[6:7], v[22:23], 0, v[6:7]
	global_store_dwordx4 v[6:7], v[2:5], off nt
	s_waitcnt lgkmcnt(0)

; #define LAS __attribute__((address_space(3)))
; template <int KIND>
; DI void transpose_item(const float* W, int K, int N, bf16_t* WT, int ldk, const float* g0, const float* g1, const float* g2, LAS float* scr, int item, int lane) {
;     const int nblk = N / 32, kb = item / nblk, nb = item % nblk, k0 = 64 * kb, n0 = 32 * nb;
;     f32x4 tv[8];
; #pragma unroll
;     for (int i = 0; i < 8; ++i) tv[i] = *(const f32x4*)(W + (size_t)(k0 + 8 * i + (lane >> 3)) * N + n0 + 4 * (lane & 7));
; #pragma unroll
;     for (int i = 0; i < 8; ++i) {
;         const int kk = 8 * i + (lane >> 3), k = k0 + kk;
;         float gn = 1.f;
;         if (KIND == 0 || KIND == 1 || KIND == 2 || KIND == 5 || KIND == 6) gn = g0[k];
;         if (KIND == 4) gn = k < 1024 ? g0[k] : (k < 1536 ? g1[k - 1024] : g2[k - 1536]);
;         LAS float* d = scr + kk * 33 + 4 * (lane & 7);
;         d[0] = tv[i][0] * gn; d[1] = tv[i][1] * gn; d[2] = tv[i][2] * gn; d[3] = tv[i][3] * gn;
;     }
;     asm volatile("s_waitcnt lgkmcnt(0)" ::: "memory");
; DI void convert_weights(PP p, LAS unsigned char* lds, int l, int worker, int nworkers) {
;     ...
;         if (r < I_UQ) { transpose_item<1>(p->in[4] + (size_t)l * 512 * 1536, 512, 1536, (bf16_t*)(wl + W_UQ), 512, p->in[3] + l * 512, nullptr, nullptr, scr, r, lane); continue; } r -= I_UQ;
.LBB0_140:
	s_andn2_saveexec_b64 s[6:7], s[58:59]
	s_cbranch_execz .LBB0_142
	v_add_u16_e32 v2, 0xf4c0, v1
	v_mul_u32_u24_e32 v3, 0xaaab, v2
	s_load_dwordx4 s[8:11], s[4:5], 0x18
	v_lshrrev_b32_e32 v3, 21, v3
	v_mul_lo_u16_e32 v4, 48, v3
	v_sub_u16_e32 v2, v2, v4
	v_lshlrev_b16_e32 v55, 6, v3
	v_lshlrev_b16_e32 v57, 5, v2
	v_or_b32_e32 v20, v34, v55
	v_lshlrev_b32_e32 v2, 2, v57
	v_mov_b32_e32 v3, v37
	s_waitcnt lgkmcnt(0)
	v_lshl_add_u64 v[2:3], s[10:11], 0, v[2:3]
	v_mul_u32_u24_e32 v4, 0x600, v20
	v_lshl_add_u64 v[2:3], v[2:3], 0, v[36:37]
	v_lshlrev_b32_e32 v4, 2, v4
	v_mov_b32_e32 v5, v37
	v_lshl_add_u64 v[30:31], v[2:3], 0, v[4:5]
	s_mov_b32 s10, 0xc000
	v_add_co_u32_e32 v6, vcc, s10, v30
	s_mov_b32 s10, 0x24000
	s_nop 0
	v_addc_co_u32_e32 v7, vcc, 0, v31, vcc
	v_add_co_u32_e32 v10, vcc, s82, v30
	v_lshlrev_b32_e32 v32, 2, v20
	s_nop 0
	v_addc_co_u32_e32 v11, vcc, 0, v31, vcc
	v_add_co_u32_e32 v14, vcc, s10, v30
	s_mov_b32 s10, 0x3c000
	s_nop 0
	v_addc_co_u32_e32 v15, vcc, 0, v31, vcc
	v_add_co_u32_e32 v18, vcc, s68, v30
	global_load_dwordx4 v[2:5], v[30:31], off nt
	s_nop 0
	global_load_dwordx4 v[6:9], v[6:7], off nt
	v_addc_co_u32_e32 v19, vcc, 0, v31, vcc
	v_add_co_u32_e32 v22, vcc, s10, v30
	s_mov_b32 s10, 0x48000
	s_nop 0
	v_addc_co_u32_e32 v23, vcc, 0, v31, vcc
	v_add_co_u32_e32 v26, vcc, s10, v30
	global_load_dwordx4 v[10:13], v[10:11], off nt
	s_nop 0
	global_load_dwordx4 v[14:17], v[14:15], off nt
	v_addc_co_u32_e32 v27, vcc, 0, v31, vcc
	global_load_dword v56, v32, s[8:9]
	s_mov_b32 s10, 0x54000
	v_add_co_u32_e32 v30, vcc, s10, v30
	global_load_dwordx4 v[18:21], v[18:19], off nt
	s_nop 0
	global_load_dwordx4 v[22:25], v[22:23], off nt
	s_nop 0
	global_load_dword v84, v32, s[8:9] offset:32
	global_load_dword v86, v32, s[8:9] offset:64
	global_load_dword v88, v32, s[8:9] offset:96
	global_load_dword v90, v32, s[8:9] offset:128
	global_load_dword v92, v32, s[8:9] offset:160
	s_nop 0
	global_load_dwordx4 v[26:29], v[26:27], off nt
	s_nop 0
	global_load_dword v94, v32, s[8:9] offset:192
	v_addc_co_u32_e32 v31, vcc, 0, v31, vcc
	global_load_dword v96, v32, s[8:9] offset:224
	s_nop 0
	global_load_dwordx4 v[30:33], v[30:31], off nt
	v_add_u32_e32 v85, v35, v61
	v_add_u32_e32 v87, 0x420, v85
	v_add_u32_e32 v89, 0x428, v85
	v_add_u32_e32 v91, 0x840, v85
	s_waitcnt vmcnt(11)
	v_pk_mul_f32 v[2:3], v[2:3], v[56:57] op_sel_hi:[1,0]
	v_pk_mul_f32 v[4:5], v[4:5], v[56:57] op_sel_hi:[1,0]
	ds_write2_b32 v65, v2, v3 offset1:1
	ds_write2_b32 v65, v4, v5 offset0:2 offset1:3
	s_waitcnt vmcnt(8)
	v_pk_mul_f32 v[2:3], v[6:7], v[84:85] op_sel_hi:[1,0]
	v_pk_mul_f32 v[4:5], v[8:9], v[84:85] op_sel_hi:[1,0]
	s_waitcnt vmcnt(7)
	v_pk_mul_f32 v[6:7], v[10:11], v[86:87] op_sel_hi:[1,0]
	v_pk_mul_f32 v[8:9], v[12:13], v[86:87] op_sel_hi:[1,0]
	s_waitcnt vmcnt(6)
	v_pk_mul_f32 v[10:11], v[14:15], v[88:89] op_sel_hi:[1,0]
	v_pk_mul_f32 v[12:13], v[16:17], v[88:89] op_sel_hi:[1,0]
	s_waitcnt vmcnt(5)
	v_pk_mul_f32 v[14:15], v[18:19], v[90:91] op_sel_hi:[1,0]
	v_pk_mul_f32 v[16:17], v[20:21], v[90:91] op_sel_hi:[1,0]
	s_waitcnt vmcnt(4)
	v_pk_mul_f32 v[18:19], v[22:23], v[92:93] op_sel_hi:[1,0]
	v_pk_mul_f32 v[20:21], v[24:25], v[92:93] op_sel_hi:[1,0]
	s_waitcnt vmcnt(2)
	v_pk_mul_f32 v[22:23], v[26:27], v[94:95] op_sel_hi:[1,0]
	v_pk_mul_f32 v[24:25], v[28:29], v[94:95] op_sel_hi:[1,0]
	ds_write2_b32 v66, v2, v3 offset1:1
	ds_write2_b32 v67, v4, v5 offset1:1
	ds_write2_b32 v68, v6, v7 offset1:1
	ds_write2_b32 v69, v8, v9 offset1:1
	ds_write2_b32 v70, v10, v11 offset1:1
	ds_write2_b32 v71, v12, v13 offset1:1
	ds_write2_b32 v85, v14, v15 offset1:1
	ds_write2_b32 v85, v16, v17 offset0:2 offset1:3
	ds_write2_b32 v87, v18, v19 offset1:1
	ds_write2_b32 v89, v20, v21 offset1:1
	ds_write2_b32 v91, v22, v23 offset1:1
	v_add_u32_e32 v2, 0x848, v85
	ds_write2_b32 v2, v24, v25 offset1:1
	s_waitcnt vmcnt(0)
; #define LAS __attribute__((address_space(3)))
; DI unsigned cvtpk(float lo, float hi) { f32x2 v = {lo, hi}; bf16x2_t b = __builtin_convertvector(v, bf16x2_t); return __builtin_bit_cast(unsigned, b); }
; template <int KIND> DI int map_n(int n) {
;     ...
;     if (KIND == 1) {
;         const int hd = n / 192, w = n % 192;
;         if (w < 128) return n;
;         const int j = w - 128; return hd * 192 + 128 + (j < 32 ? 2 * j : 2 * (j - 32) + 1);
;     }
; template <int KIND>
; DI void transpose_item(const float* W, int K, int N, bf16_t* WT, int ldk, const float* g0, const float* g1, const float* g2, LAS float* scr, int item, int lane) {
;     ...
;         LAS float* d = scr + kk * 33 + 4 * (lane & 7);
;         d[0] = tv[i][0] * gn; d[1] = tv[i][1] * gn; d[2] = tv[i][2] * gn; d[3] = tv[i][3] * gn;
;     }
;     asm volatile("s_waitcnt lgkmcnt(0)" ::: "memory");
;     int kd0 = k0;
;     if (KIND == 4) kd0 = k0 < 1024 ? k0 + 512 : (k0 < 1536 ? k0 - 1024 : k0);
;     const int c = lane & 7;
; #pragma unroll
;     for (int j = 0; j < 4; ++j) { const int n = (lane >> 3) + 8 * j; const LAS float* s = scr + (8 * c) * 33 + n;
;         u32x4 o; o.x = cvtpk(s[0 * 33], s[1 * 33]); o.y = cvtpk(s[2 * 33], s[3 * 33]); o.z = cvtpk(s[4 * 33], s[5 * 33]); o.w = cvtpk(s[6 * 33], s[7 * 33]);
;         *(u32x4*)(WT + (size_t)map_n<KIND>(n0 + n) * ldk + kd0 + 8 * c) = o; }
	v_pk_mul_f32 v[2:3], v[30:31], v[96:97] op_sel_hi:[1,0]
	v_add_u32_e32 v4, 0xc60, v85
	ds_write2_b32 v4, v2, v3 offset1:1
	v_pk_mul_f32 v[2:3], v[32:33], v[96:97] op_sel_hi:[1,0]
	v_add_u32_e32 v4, 0xc68, v85
	ds_write2_b32 v4, v2, v3 offset1:1
	s_waitcnt lgkmcnt(0)
	v_lshlrev_b32_e32 v2, 1, v55
	v_mov_b32_e32 v3, v37
	ds_read2_b32 v[6:7], v60 offset0:33 offset1:41
	ds_read2_b32 v[8:9], v60 offset1:8
	ds_read2_b32 v[10:11], v60 offset0:66 offset1:74
	ds_read2_b32 v[12:13], v60 offset0:99 offset1:107
	ds_read2_b32 v[14:15], v60 offset0:132 offset1:140
	ds_read2_b32 v[16:17], v60 offset0:165 offset1:173
	ds_read2_b32 v[18:19], v60 offset0:198 offset1:206
	ds_read2_b32 v[20:21], v60 offset0:231 offset1:239
	v_lshl_add_u64 v[22:23], v[48:49], 0, v[2:3]
	s_waitcnt lgkmcnt(6)
	v_cvt_pk_bf16_f32 v2, v8, v6
	v_or_b32_e32 v6, v34, v57
	v_mul_u32_u24_e32 v8, 0x2aab, v6
	v_lshrrev_b32_e32 v8, 21, v8
	v_mul_lo_u16_e32 v8, 0xc0, v8
	v_sub_u16_e32 v8, v6, v8
	s_waitcnt lgkmcnt(4)
	v_cvt_pk_bf16_f32 v3, v10, v12
	v_cmp_gt_u16_e32 vcc, s84, v8
	v_sub_u32_e32 v12, v6, v8
	v_lshl_add_u32 v12, v8, 1, v12
	v_cndmask_b32_e32 v10, v80, v81, vcc
	v_add3_u32 v10, v12, v10, s83
	v_cmp_gt_u16_e32 vcc, s83, v8
	s_waitcnt lgkmcnt(2)
	v_cvt_pk_bf16_f32 v4, v14, v16
	s_waitcnt lgkmcnt(0)
	v_cvt_pk_bf16_f32 v5, v18, v20
	v_cndmask_b32_e32 v24, v10, v6, vcc
	v_ashrrev_i32_e32 v25, 31, v24
	v_lshlrev_b64 v[24:25], 10, v[24:25]
	v_lshl_add_u64 v[24:25], v[22:23], 0, v[24:25]
	v_or_b32_e32 v6, v53, v57
	global_store_dwordx4 v[24:25], v[2:5], off nt
	s_nop 1
	v_cvt_pk_bf16_f32 v2, v9, v7
	v_mul_u32_u24_e32 v7, 0x2aab, v6
	v_lshrrev_b32_e32 v7, 21, v7
	v_mul_lo_u16_e32 v7, 0xc0, v7
	v_sub_u16_e32 v7, v6, v7
	v_cmp_gt_u16_e32 vcc, s84, v7
	v_sub_u32_e32 v9, v6, v7
	v_lshl_add_u32 v9, v7, 1, v9
	v_cndmask_b32_e32 v8, v80, v81, vcc
	v_add3_u32 v8, v9, v8, s83
	v_cmp_gt_u16_e32 vcc, s83, v7
	v_cvt_pk_bf16_f32 v3, v11, v13
	v_cvt_pk_bf16_f32 v4, v15, v17
	v_cndmask_b32_e32 v6, v8, v6, vcc
	v_ashrrev_i32_e32 v7, 31, v6
	v_lshlrev_b64 v[6:7], 10, v[6:7]
	v_cvt_pk_bf16_f32 v5, v19, v21
	v_lshl_add_u64 v[6:7], v[22:23], 0, v[6:7]
	ds_read2_b32 v[8:9], v60 offset0:16 offset1:24
	ds_read2_b32 v[10:11], v60 offset0:49 offset1:57
	ds_read2_b32 v[12:13], v60 offset0:82 offset1:90
	ds_read2_b32 v[14:15], v60 offset0:115 offset1:123
	ds_read2_b32 v[16:17], v60 offset0:148 offset1:156
	ds_read2_b32 v[18:19], v60 offset0:181 offset1:189
	ds_read2_b32 v[20:21], v60 offset0:214 offset1:222
	ds_read2_b32 v[24:25], v60 offset0:247 offset1:255
	global_store_dwordx4 v[6:7], v[2:5], off nt
	v_or_b32_e32 v6, v58, v57
	v_mul_u32_u24_e32 v7, 0x2aab, v6
	v_lshrrev_b32_e32 v7, 21, v7
	v_mul_lo_u16_e32 v7, 0xc0, v7
	v_sub_u16_e32 v7, v6, v7
	s_waitcnt lgkmcnt(6)
	v_cvt_pk_bf16_f32 v2, v8, v10
	v_cmp_gt_u16_e32 vcc, s84, v7
	v_sub_u32_e32 v10, v6, v7
	v_lshl_add_u32 v10, v7, 1, v10
	v_cndmask_b32_e32 v8, v80, v81, vcc
	v_add3_u32 v8, v10, v8, s83
	v_cmp_gt_u16_e32 vcc, s83, v7
	s_waitcnt lgkmcnt(4)
	v_cvt_pk_bf16_f32 v3, v12, v14
	s_waitcnt lgkmcnt(2)
	v_cvt_pk_bf16_f32 v4, v16, v18
	v_cndmask_b32_e32 v6, v8, v6, vcc
	v_ashrrev_i32_e32 v7, 31, v6
	v_lshlrev_b64 v[6:7], 10, v[6:7]
	s_waitcnt lgkmcnt(0)
	v_cvt_pk_bf16_f32 v5, v20, v24
	v_lshl_add_u64 v[6:7], v[22:23], 0, v[6:7]
	global_store_dwordx4 v[6:7], v[2:5], off nt
	v_or_b32_e32 v6, v59, v57
	v_mul_u32_u24_e32 v7, 0x2aab, v6
	v_lshrrev_b32_e32 v7, 21, v7
	v_mul_lo_u16_e32 v7, 0xc0, v7
	v_sub_u16_e32 v7, v6, v7
	v_cvt_pk_bf16_f32 v2, v9, v11
	v_cmp_gt_u16_e32 vcc, s84, v7
	v_sub_u32_e32 v9, v6, v7
	v_lshl_add_u32 v9, v7, 1, v9
	v_cndmask_b32_e32 v8, v80, v81, vcc
	v_add3_u32 v8, v9, v8, s83
	v_cmp_gt_u16_e32 vcc, s83, v7
	v_cvt_pk_bf16_f32 v3, v13, v15
	v_cvt_pk_bf16_f32 v4, v17, v19
	v_cndmask_b32_e32 v6, v8, v6, vcc
	v_ashrrev_i32_e32 v7, 31, v6
	v_lshlrev_b64 v[6:7], 10, v[6:7]
	v_cvt_pk_bf16_f32 v5, v21, v25
	v_lshl_add_u64 v[6:7], v[22:23], 0, v[6:7]
	global_store_dwordx4 v[6:7], v[2:5], off nt
	s_waitcnt lgkmcnt(0)

; #define LAS __attribute__((address_space(3)))
; DI unsigned cvtpk(float lo, float hi) { f32x2 v = {lo, hi}; bf16x2_t b = __builtin_convertvector(v, bf16x2_t); return __builtin_bit_cast(unsigned, b); }
; template <int KIND> DI int map_n(int n) {
;     if (KIND == 0) {
;         if (n < 768) return n;
;         if (n < 832) { const int j = n - 768; return 2816 + (j < 32 ? 2 * j : 2 * (j - 32) + 1); }
;         return n - 64;
;     }
; template <int KIND>
; DI void transpose_item(const float* W, int K, int N, bf16_t* WT, int ldk, const float* g0, const float* g1, const float* g2, LAS float* scr, int item, int lane) {
;     ...
; #pragma unroll
;     for (int j = 0; j < 4; ++j) { const int n = (lane >> 3) + 8 * j; const LAS float* s = scr + (8 * c) * 33 + n;
;         u32x4 o; o.x = cvtpk(s[0 * 33], s[1 * 33]); o.y = cvtpk(s[2 * 33], s[3 * 33]); o.z = cvtpk(s[4 * 33], s[5 * 33]); o.w = cvtpk(s[6 * 33], s[7 * 33]);
;         *(u32x4*)(WT + (size_t)map_n<KIND>(n0 + n) * ldk + kd0 + 8 * c) = o; }
.LBB0_150:
	s_or_b64 exec, exec, s[8:9]
	v_ashrrev_i32_e32 v15, 31, v14
	v_lshl_add_u64 v[4:5], v[4:5], 1, v[50:51]
	s_waitcnt lgkmcnt(3)
	v_cvt_pk_bf16_f32 v18, v6, v7
	v_lshlrev_b64 v[6:7], 12, v[14:15]
	s_waitcnt lgkmcnt(2)
	v_cvt_pk_bf16_f32 v19, v8, v9
	s_waitcnt lgkmcnt(1)
	v_cvt_pk_bf16_f32 v20, v10, v11
	s_waitcnt lgkmcnt(0)
	v_cvt_pk_bf16_f32 v21, v12, v13
	v_lshl_add_u64 v[14:15], v[4:5], 0, v[6:7]
	ds_read2_b32 v[6:7], v60 offset0:8 offset1:41
	ds_read2_b32 v[8:9], v60 offset0:74 offset1:107
	ds_read2_b32 v[10:11], v60 offset0:140 offset1:173
	ds_read2_b32 v[12:13], v60 offset0:206 offset1:239
	global_store_dwordx4 v[14:15], v[18:21], off nt
	v_add_u32_e32 v15, 8, v17
	v_or_b32_e32 v14, v3, v53
	v_cmp_lt_i32_e32 vcc, s86, v15
	s_and_saveexec_b64 s[8:9], vcc
	s_cbranch_execz .LBB0_156
	v_cmp_lt_u32_e32 vcc, s87, v2
	s_and_saveexec_b64 s[10:11], vcc
	s_xor_b64 s[10:11], exec, s[10:11]
	v_subrev_u32_e32 v14, 64, v14
	s_andn2_saveexec_b64 s[10:11], s[10:11]
	v_cmp_gt_u32_e32 vcc, s88, v2
	v_mul_lo_u32 v15, v16, s89
	s_movk_i32 s12, 0xb10
	v_cndmask_b32_e32 v14, v82, v83, vcc
	v_sub_u32_e32 v14, v14, v15
	v_add_u32_e32 v15, v62, v63
	v_add3_u32 v14, v15, v14, s12
	s_or_b64 exec, exec, s[10:11]
.LBB0_156:
	s_or_b64 exec, exec, s[8:9]
	v_ashrrev_i32_e32 v15, 31, v14
	s_waitcnt lgkmcnt(3)
	v_cvt_pk_bf16_f32 v18, v6, v7
	v_lshlrev_b64 v[6:7], 12, v[14:15]
	s_waitcnt lgkmcnt(2)
	v_cvt_pk_bf16_f32 v19, v8, v9
	s_waitcnt lgkmcnt(1)
	v_cvt_pk_bf16_f32 v20, v10, v11
	s_waitcnt lgkmcnt(0)
	v_cvt_pk_bf16_f32 v21, v12, v13
	v_lshl_add_u64 v[14:15], v[4:5], 0, v[6:7]
	ds_read2_b32 v[6:7], v60 offset0:16 offset1:49
	ds_read2_b32 v[8:9], v60 offset0:82 offset1:115
	ds_read2_b32 v[10:11], v60 offset0:148 offset1:181
	ds_read2_b32 v[12:13], v60 offset0:214 offset1:247
	global_store_dwordx4 v[14:15], v[18:21], off nt
	v_add_u32_e32 v15, 16, v17
	v_or_b32_e32 v14, v3, v58
	v_cmp_lt_i32_e32 vcc, s86, v15
	s_and_saveexec_b64 s[8:9], vcc
	s_cbranch_execz .LBB0_162
	v_cmp_lt_u32_e32 vcc, s87, v2
	s_and_saveexec_b64 s[10:11], vcc
	s_xor_b64 s[10:11], exec, s[10:11]
	v_subrev_u32_e32 v14, 64, v14
	s_andn2_saveexec_b64 s[10:11], s[10:11]
	v_cmp_gt_u32_e32 vcc, s88, v2
	v_mul_lo_u32 v15, v16, s89
	s_movk_i32 s12, 0xb20
	v_cndmask_b32_e32 v14, v82, v83, vcc
	v_sub_u32_e32 v14, v14, v15
	v_add_u32_e32 v15, v62, v63
	v_add3_u32 v14, v15, v14, s12
	s_or_b64 exec, exec, s[10:11]
.LBB0_162:
	s_or_b64 exec, exec, s[8:9]
	v_ashrrev_i32_e32 v15, 31, v14
	s_waitcnt lgkmcnt(3)
	v_cvt_pk_bf16_f32 v18, v6, v7
	v_lshlrev_b64 v[6:7], 12, v[14:15]
	s_waitcnt lgkmcnt(2)
	v_cvt_pk_bf16_f32 v19, v8, v9
	s_waitcnt lgkmcnt(1)
	v_cvt_pk_bf16_f32 v20, v10, v11
	s_waitcnt lgkmcnt(0)
	v_cvt_pk_bf16_f32 v21, v12, v13
	v_lshl_add_u64 v[14:15], v[4:5], 0, v[6:7]
	ds_read2_b32 v[6:7], v60 offset0:24 offset1:57
	ds_read2_b32 v[8:9], v60 offset0:90 offset1:123
	ds_read2_b32 v[10:11], v60 offset0:156 offset1:189
	ds_read2_b32 v[12:13], v60 offset0:222 offset1:255
	global_store_dwordx4 v[14:15], v[18:21], off nt
	v_or_b32_e32 v14, v3, v59
	v_add_u32_e32 v3, 24, v17
	v_cmp_lt_i32_e32 vcc, s86, v3
	s_and_saveexec_b64 s[8:9], vcc
	s_cbranch_execz .LBB0_51
	v_cmp_lt_u32_e32 vcc, s87, v2
	s_and_saveexec_b64 s[10:11], vcc
	s_xor_b64 s[10:11], exec, s[10:11]
	v_subrev_u32_e32 v14, 64, v14
	s_andn2_saveexec_b64 s[10:11], s[10:11]
	s_cbranch_execz .LBB0_50
	v_cmp_gt_u32_e32 vcc, s88, v2
	v_mul_lo_u32 v3, v16, s89
	s_movk_i32 s12, 0xb30
	v_cndmask_b32_e32 v2, v82, v83, vcc
	v_sub_u32_e32 v2, v2, v3
	v_add_u32_e32 v3, v62, v63
	v_add3_u32 v14, v3, v2, s12
	s_branch .LBB0_50

; #define LAS __attribute__((address_space(3)))
; DI unsigned cvtpk(float lo, float hi) { f32x2 v = {lo, hi}; bf16x2_t b = __builtin_convertvector(v, bf16x2_t); return __builtin_bit_cast(unsigned, b); }
; template <int KIND>
; DI void transpose_item(const float* W, int K, int N, bf16_t* WT, int ldk, const float* g0, const float* g1, const float* g2, LAS float* scr, int item, int lane) {
;     ...
; #pragma unroll
;     for (int j = 0; j < 4; ++j) { const int n = (lane >> 3) + 8 * j; const LAS float* s = scr + (8 * c) * 33 + n;
;         u32x4 o; o.x = cvtpk(s[0 * 33], s[1 * 33]); o.y = cvtpk(s[2 * 33], s[3 * 33]); o.z = cvtpk(s[4 * 33], s[5 * 33]); o.w = cvtpk(s[6 * 33], s[7 * 33]);
;         *(u32x4*)(WT + (size_t)map_n<KIND>(n0 + n) * ldk + kd0 + 8 * c) = o; }
.LBB0_622:
	s_or_b64 exec, exec, s[14:15]
	v_ashrrev_i32_e32 v13, 31, v12
	s_waitcnt lgkmcnt(3)
	v_cvt_pk_bf16_f32 v2, v2, v3
	s_waitcnt lgkmcnt(2)
	v_cvt_pk_bf16_f32 v3, v4, v5
	s_waitcnt lgkmcnt(1)
	v_cvt_pk_bf16_f32 v4, v6, v7
	v_lshlrev_b64 v[6:7], 12, v[12:13]
	s_waitcnt lgkmcnt(0)
	v_cvt_pk_bf16_f32 v5, v10, v11
	v_lshl_add_u64 v[0:1], v[0:1], 0, v[6:7]
	global_store_dwordx4 v[0:1], v[2:5], off nt
	s_waitcnt lgkmcnt(0)

; template <int KIND>
; DI void transpose_item(const float* W, int K, int N, bf16_t* WT, int ldk, const float* g0, const float* g1, const float* g2, LAS float* scr, int item, int lane) {
;     const int nblk = N / 32, kb = item / nblk, nb = item % nblk, k0 = 64 * kb, n0 = 32 * nb;
;     f32x4 tv[8];
; #pragma unroll
;     for (int i = 0; i < 8; ++i) tv[i] = *(const f32x4*)(W + (size_t)(k0 + 8 * i + (lane >> 3)) * N + n0 + 4 * (lane & 7));
; #pragma unroll
;     for (int i = 0; i < 8; ++i) {
;         const int kk = 8 * i + (lane >> 3), k = k0 + kk;
;         float gn = 1.f;
;         if (KIND == 0 || KIND == 1 || KIND == 2 || KIND == 5 || KIND == 6) gn = g0[k];
; DI void convert_weights(PP p, LAS unsigned char* lds, int l, int worker, int nworkers) {
;     ...
;     for (int it = worker; it < I_LAYER; it += nworkers) {
;         int r = it;
;         if (r < I_IN) { transpose_item<0>(p->in[2] + (size_t)l * 2048 * 2880, 2048, 2880, (bf16_t*)(wl + W_IN), 2048, p->in[1] + l * 2048, nullptr, nullptr, scr, r, lane); continue; } r -= I_IN;
;         if (r < I_UQ) { transpose_item<1>(p->in[4] + (size_t)l * 512 * 1536, 512, 1536, (bf16_t*)(wl + W_UQ), 512, p->in[3] + l * 512, nullptr, nullptr, scr, r, lane); continue; } r -= I_UQ;
;         if (r < I_UKV) { transpose_item<2>(p->in[6] + (size_t)l * 256 * 2048, 256, 2048, (bf16_t*)(wl + W_UKV), 256, p->in[5] + l * 256, nullptr, nullptr, scr, r, lane); continue; } r -= I_UKV;
;         if (r < I_GLU) { transpose_item<3>(p->in[15] + (size_t)l * 512 * 1024, 512, 1024, (bf16_t*)(wl + W_GLU), 512, nullptr, nullptr, nullptr, scr, r, lane); continue; } r -= I_GLU;
;         if (r < I_O) { transpose_item<4>(p->in[20] + (size_t)l * 2048 * 2048, 2048, 2048, (bf16_t*)(wl + W_O), 2048, p->in[17] + l * 1024, p->in[18] + l * 512, p->in[19] + l * 512, scr, r, lane); continue; } r -= I_O;
;         if (r < I_G) { transpose_item<5>(p->in[22] + (size_t)l * 2048 * DFF_, 2048, DFF_, (bf16_t*)(wl + W_GU), 2048, p->in[21] + l * 2048, nullptr, nullptr, scr, r, lane); continue; } r -= I_G;
;         if (r < I_G) { transpose_item<6>(p->in[23] + (size_t)l * 2048 * DFF_, 2048, DFF_, (bf16_t*)(wl + W_GU), 2048, p->in[21] + l * 2048, nullptr, nullptr, scr, r, lane); continue; } r -= I_G;
;         transpose_item<7>(p->in[24] + (size_t)l * DFF_ * 2048, DFF_, 2048, (bf16_t*)(wl + W_DN), DFF_, nullptr, nullptr, nullptr, scr, r, lane);
.LBB0_624:
	s_movk_i32 s4, 0xb3f
	v_cmp_lt_i32_e32 vcc, s4, v62
	s_and_saveexec_b64 s[6:7], vcc
	s_xor_b64 s[62:63], exec, s[6:7]
	s_cbranch_execz .LBB0_714
	s_movk_i32 s4, 0xcbf
	v_cmp_lt_u32_e32 vcc, s4, v62
	s_and_saveexec_b64 s[6:7], vcc
	s_xor_b64 s[64:65], exec, s[6:7]
	s_cbranch_execz .LBB0_711
	s_movk_i32 s4, 0xdbf
	v_cmp_lt_u32_e32 vcc, s4, v62
	s_and_saveexec_b64 s[6:7], vcc
	s_xor_b64 s[66:67], exec, s[6:7]
	s_cbranch_execz .LBB0_708
	s_movk_i32 s4, 0xebf
	v_cmp_lt_u32_e32 vcc, s4, v62
	s_and_saveexec_b64 s[6:7], vcc
	s_xor_b64 s[68:69], exec, s[6:7]
	s_cbranch_execz .LBB0_705
	s_movk_i32 s4, 0x16bf
	v_cmp_lt_u32_e32 vcc, s4, v62
	s_and_saveexec_b64 s[6:7], vcc
	s_xor_b64 s[6:7], exec, s[6:7]
	s_cbranch_execz .LBB0_638
	s_movk_i32 s4, 0x2cbf
	v_cmp_lt_u32_e32 vcc, s4, v62
	s_and_saveexec_b64 s[14:15], vcc
	s_xor_b64 s[14:15], exec, s[14:15]
	s_cbranch_execz .LBB0_635
	s_movk_i32 s4, 0x42bf
	v_cmp_lt_u32_e32 vcc, s4, v62
	s_and_saveexec_b64 s[16:17], vcc
	s_xor_b64 s[16:17], exec, s[16:17]
	s_cbranch_execz .LBB0_632
	s_load_dwordx2 s[18:19], s[8:9], 0xc0
	v_add_u32_e32 v0, 0xffffbd40, v62
	v_and_b32_e32 v53, 0x1fc0, v0
	v_add_u32_e32 v0, 0xfff7a800, v50
	v_and_b32_e32 v54, 0x7c0, v0
	s_waitcnt lgkmcnt(0)
	s_add_u32 s18, s18, s1
	s_addc_u32 s19, s19, s0
	v_lshlrev_b32_e32 v128, 2, v54
	v_or_b32_e32 v2, v53, v32
	v_lshl_add_u64 v[0:1], s[18:19], 0, v[128:129]
	v_lshlrev_b32_e32 v128, 2, v34
	v_lshl_add_u64 v[0:1], v[0:1], 0, v[128:129]
	v_lshlrev_b32_e32 v128, 13, v2
	v_lshl_add_u64 v[28:29], v[0:1], 0, v[128:129]
	s_mov_b32 s4, 0x10000
	v_add_co_u32_e32 v4, vcc, s4, v28
	global_load_dwordx4 v[0:3], v[28:29], off nt
	s_nop 0
	v_addc_co_u32_e32 v5, vcc, 0, v29, vcc
	s_mov_b32 s4, 0x20000
	global_load_dwordx4 v[4:7], v[4:5], off nt
	v_add_co_u32_e32 v8, vcc, s4, v28
	s_mov_b32 s4, 0x30000
	s_nop 0
	v_addc_co_u32_e32 v9, vcc, 0, v29, vcc
	global_load_dwordx4 v[8:11], v[8:9], off nt
	v_add_co_u32_e32 v12, vcc, s4, v28
	s_mov_b32 s4, 0x50000
	s_nop 0
	v_addc_co_u32_e32 v13, vcc, 0, v29, vcc
	global_load_dwordx4 v[12:15], v[12:13], off nt
	v_add_co_u32_e32 v16, vcc, s89, v28
	v_add_u32_e32 v55, v33, v35
	s_nop 0
	v_addc_co_u32_e32 v17, vcc, 0, v29, vcc
	global_load_dwordx4 v[16:19], v[16:17], off nt
	v_add_co_u32_e32 v20, vcc, s4, v28
	s_mov_b32 s4, 0x60000
	s_nop 0
	v_addc_co_u32_e32 v21, vcc, 0, v29, vcc
	global_load_dwordx4 v[20:23], v[20:21], off nt
	v_add_co_u32_e32 v24, vcc, s4, v28
	s_mov_b32 s4, 0x70000
	s_nop 0
	v_addc_co_u32_e32 v25, vcc, 0, v29, vcc
	global_load_dwordx4 v[24:27], v[24:25], off nt
	v_add_co_u32_e32 v28, vcc, s4, v28
	v_lshlrev_b32_e32 v128, 1, v53
	s_nop 0
	v_addc_co_u32_e32 v29, vcc, 0, v29, vcc
	global_load_dwordx4 v[28:31], v[28:29], off nt
	s_waitcnt vmcnt(7)
	ds_write2_b32 v55, v0, v1 offset1:1
	ds_write2_b32 v55, v2, v3 offset0:2 offset1:3
	v_add_u32_e32 v0, 0x420, v55
	s_waitcnt vmcnt(6)
	ds_write2_b32 v0, v4, v5 offset1:1
	v_add_u32_e32 v0, 0x428, v55
	ds_write2_b32 v0, v6, v7 offset1:1
	v_add_u32_e32 v0, 0x840, v55
	s_waitcnt vmcnt(5)
	ds_write2_b32 v0, v8, v9 offset1:1
	v_add_u32_e32 v0, 0x848, v55
	ds_write2_b32 v0, v10, v11 offset1:1
	v_add_u32_e32 v0, 0xc60, v55
	s_waitcnt vmcnt(4)
	ds_write2_b32 v0, v12, v13 offset1:1
	v_add_u32_e32 v0, 0xc68, v55
	ds_write2_b32 v0, v14, v15 offset1:1
	v_add_u32_e32 v0, 0x1080, v55
	s_waitcnt vmcnt(3)
	ds_write2_b32 v0, v16, v17 offset1:1
	v_add_u32_e32 v0, 0x1088, v55
	ds_write2_b32 v0, v18, v19 offset1:1
	v_add_u32_e32 v0, 0x14a0, v55
	s_waitcnt vmcnt(2)
	ds_write2_b32 v0, v20, v21 offset1:1
	v_add_u32_e32 v0, 0x14a8, v55
	ds_write2_b32 v0, v22, v23 offset1:1
	v_add_u32_e32 v0, 0x18c0, v55
	s_waitcnt vmcnt(1)
	ds_write2_b32 v0, v24, v25 offset1:1
	v_add_u32_e32 v0, 0x18c8, v55
	ds_write2_b32 v0, v26, v27 offset1:1
	v_add_u32_e32 v0, 0x1ce0, v55
	s_waitcnt vmcnt(0)
	ds_write2_b32 v0, v28, v29 offset1:1
	v_add_u32_e32 v0, 0x1ce8, v55
	ds_write2_b32 v0, v30, v31 offset1:1
	s_waitcnt lgkmcnt(0)
	ds_read2_b32 v[6:7], v58 offset0:33 offset1:41
	ds_read2_b32 v[8:9], v58 offset1:8
	ds_read2_b32 v[10:11], v58 offset0:66 offset1:74
	ds_read2_b32 v[12:13], v58 offset0:99 offset1:107
	ds_read2_b32 v[14:15], v58 offset0:132 offset1:140
	ds_read2_b32 v[16:17], v58 offset0:165 offset1:173
	ds_read2_b32 v[18:19], v58 offset0:198 offset1:206
	ds_read2_b32 v[20:21], v58 offset0:231 offset1:239
	v_lshl_add_u64 v[0:1], v[36:37], 0, v[128:129]
	s_waitcnt lgkmcnt(6)
	v_cvt_pk_bf16_f32 v2, v8, v6
	v_or_b32_e32 v6, v54, v32
	v_mul_u32_u24_e32 v128, 0x2c00, v6
	v_or_b32_e32 v6, v54, v51
	s_waitcnt lgkmcnt(4)
	v_cvt_pk_bf16_f32 v3, v10, v12
	s_waitcnt lgkmcnt(2)
	v_cvt_pk_bf16_f32 v4, v14, v16
	s_waitcnt lgkmcnt(0)
	v_cvt_pk_bf16_f32 v5, v18, v20
	v_lshl_add_u64 v[22:23], v[0:1], 0, v[128:129]
	v_mul_u32_u24_e32 v128, 0x2c00, v6
	global_store_dwordx4 v[22:23], v[2:5], off nt
	s_nop 1
	v_cvt_pk_bf16_f32 v2, v9, v7
	v_cvt_pk_bf16_f32 v3, v11, v13
	v_cvt_pk_bf16_f32 v4, v15, v17
	v_cvt_pk_bf16_f32 v5, v19, v21
	v_lshl_add_u64 v[6:7], v[0:1], 0, v[128:129]
	global_store_dwordx4 v[6:7], v[2:5], off nt
	ds_read2_b32 v[6:7], v58 offset0:16 offset1:24
	ds_read2_b32 v[8:9], v58 offset0:49 offset1:57
	ds_read2_b32 v[10:11], v58 offset0:82 offset1:90
	ds_read2_b32 v[12:13], v58 offset0:115 offset1:123
	ds_read2_b32 v[14:15], v58 offset0:148 offset1:156
	ds_read2_b32 v[16:17], v58 offset0:181 offset1:189
	ds_read2_b32 v[18:19], v58 offset0:214 offset1:222
	ds_read2_b32 v[20:21], v58 offset0:247 offset1:255
	s_waitcnt lgkmcnt(6)
	v_cvt_pk_bf16_f32 v2, v6, v8
	v_or_b32_e32 v6, v54, v56
	v_mul_u32_u24_e32 v128, 0x2c00, v6
	v_or_b32_e32 v6, v54, v57
	s_waitcnt lgkmcnt(4)
	v_cvt_pk_bf16_f32 v3, v10, v12
	s_waitcnt lgkmcnt(2)
	v_cvt_pk_bf16_f32 v4, v14, v16
	s_waitcnt lgkmcnt(0)
	v_cvt_pk_bf16_f32 v5, v18, v20
	v_lshl_add_u64 v[22:23], v[0:1], 0, v[128:129]
	v_mul_u32_u24_e32 v128, 0x2c00, v6
	global_store_dwordx4 v[22:23], v[2:5], off nt
	v_lshl_add_u64 v[0:1], v[0:1], 0, v[128:129]
	s_nop 0
	v_cvt_pk_bf16_f32 v2, v7, v9
	v_cvt_pk_bf16_f32 v3, v11, v13
	v_cvt_pk_bf16_f32 v4, v15, v17
	v_cvt_pk_bf16_f32 v5, v19, v21
	global_store_dwordx4 v[0:1], v[2:5], off nt
	s_waitcnt lgkmcnt(0)
; #define LAS __attribute__((address_space(3)))
; template <int KIND>
; DI void transpose_item(const float* W, int K, int N, bf16_t* WT, int ldk, const float* g0, const float* g1, const float* g2, LAS float* scr, int item, int lane) {
;     const int nblk = N / 32, kb = item / nblk, nb = item % nblk, k0 = 64 * kb, n0 = 32 * nb;
;     f32x4 tv[8];
; #pragma unroll
;     for (int i = 0; i < 8; ++i) tv[i] = *(const f32x4*)(W + (size_t)(k0 + 8 * i + (lane >> 3)) * N + n0 + 4 * (lane & 7));
; #pragma unroll
;     for (int i = 0; i < 8; ++i) {
;         const int kk = 8 * i + (lane >> 3), k = k0 + kk;
;         float gn = 1.f;
;         if (KIND == 0 || KIND == 1 || KIND == 2 || KIND == 5 || KIND == 6) gn = g0[k];
;         if (KIND == 4) gn = k < 1024 ? g0[k] : (k < 1536 ? g1[k - 1024] : g2[k - 1536]);
;         LAS float* d = scr + kk * 33 + 4 * (lane & 7);
;         d[0] = tv[i][0] * gn; d[1] = tv[i][1] * gn; d[2] = tv[i][2] * gn; d[3] = tv[i][3] * gn;
;     }
;     asm volatile("s_waitcnt lgkmcnt(0)" ::: "memory");
; DI void convert_weights(PP p, LAS unsigned char* lds, int l, int worker, int nworkers) {
;     ...
;         if (r < I_G) { transpose_item<6>(p->in[23] + (size_t)l * 2048 * DFF_, 2048, DFF_, (bf16_t*)(wl + W_GU), 2048, p->in[21] + l * 2048, nullptr, nullptr, scr, r, lane); continue; } r -= I_G;
.LBB0_632:
	s_andn2_saveexec_b64 s[16:17], s[16:17]
	s_cbranch_execz .LBB0_634
	s_load_dwordx2 s[18:19], s[8:9], 0xa8
	s_load_dwordx2 s[22:23], s[8:9], 0xb8
	v_add_u16_e32 v0, 0xd340, v62
	v_mul_u32_u24_e32 v1, 0xba2f, v0
	v_lshrrev_b32_e32 v1, 23, v1
	v_mul_lo_u16_e32 v2, 0xb0, v1
	v_sub_u16_e32 v0, v0, v2
	s_waitcnt lgkmcnt(0)
	s_add_u32 s22, s22, s1
	v_lshlrev_b16_e32 v13, 6, v1
	v_lshlrev_b16_e32 v12, 5, v0
	s_addc_u32 s23, s23, s0
	v_or_b32_e32 v30, v32, v13
	v_lshlrev_b32_e32 v128, 2, v12
	s_lshl_b64 s[34:35], s[38:39], 2
	v_lshl_add_u64 v[0:1], s[22:23], 0, v[128:129]
	v_lshlrev_b32_e32 v128, 2, v34
	v_mul_u32_u24_e32 v2, 0x1600, v30
	s_add_u32 s18, s18, s34
	v_lshl_add_u64 v[0:1], v[0:1], 0, v[128:129]
	v_lshlrev_b32_e32 v128, 2, v2
	s_addc_u32 s19, s19, s35
	v_lshl_add_u64 v[0:1], v[0:1], 0, v[128:129]
	v_lshlrev_b32_e32 v31, 2, v30
	global_load_dwordx4 v[14:17], v[0:1], off nt
	global_load_dword v30, v31, s[18:19]
	s_mov_b32 s4, 0x2c000
	v_add_co_u32_e32 v2, vcc, s4, v0
	v_add_u32_e32 v53, v33, v35
	s_nop 0
	v_addc_co_u32_e32 v3, vcc, 0, v1, vcc
	global_load_dwordx4 v[18:21], v[2:3], off nt
	s_mov_b32 s4, 0x58000
	v_add_co_u32_e32 v2, vcc, s4, v0
	s_mov_b32 s4, 0x84000
	s_nop 0
	v_addc_co_u32_e32 v3, vcc, 0, v1, vcc
	global_load_dwordx4 v[22:25], v[2:3], off nt
	v_add_co_u32_e32 v2, vcc, s4, v0
	s_mov_b32 s4, 0xb0000
	s_nop 0
	v_addc_co_u32_e32 v3, vcc, 0, v1, vcc
	global_load_dwordx4 v[26:29], v[2:3], off nt
	v_add_co_u32_e32 v2, vcc, s4, v0
	s_mov_b32 s4, 0xdc000
	s_nop 0
	v_addc_co_u32_e32 v3, vcc, 0, v1, vcc
	global_load_dwordx4 v[64:67], v[2:3], off nt
	v_add_co_u32_e32 v2, vcc, s4, v0
	s_mov_b32 s4, 0x108000
	s_nop 0
	v_addc_co_u32_e32 v3, vcc, 0, v1, vcc
	global_load_dwordx4 v[8:11], v[2:3], off nt
	v_add_co_u32_e32 v2, vcc, s4, v0
	s_mov_b32 s4, 0x134000
	s_nop 0
	v_addc_co_u32_e32 v3, vcc, 0, v1, vcc
	global_load_dwordx4 v[4:7], v[2:3], off nt
	v_add_co_u32_e32 v0, vcc, s4, v0
	s_movk_i32 s4, 0x1000
	s_nop 0
	v_addc_co_u32_e32 v1, vcc, 0, v1, vcc
	global_load_dwordx4 v[0:3], v[0:1], off nt
	s_waitcnt vmcnt(7)
	v_pk_mul_f32 v[14:15], v[14:15], v[30:31] op_sel_hi:[1,0]
	ds_write2_b32 v53, v14, v15 offset1:1
	v_pk_mul_f32 v[14:15], v[16:17], v[30:31] op_sel_hi:[1,0]
	ds_write2_b32 v53, v14, v15 offset0:2 offset1:3
	global_load_dword v14, v31, s[18:19] offset:32
	s_waitcnt vmcnt(0)
	v_pk_mul_f32 v[16:17], v[18:19], v[14:15] op_sel_hi:[1,0]
	v_add_u32_e32 v15, 0x420, v53
	ds_write2_b32 v15, v16, v17 offset1:1
	v_pk_mul_f32 v[14:15], v[20:21], v[14:15] op_sel_hi:[1,0]
	v_add_u32_e32 v16, 0x428, v53
	ds_write2_b32 v16, v14, v15 offset1:1
	global_load_dword v14, v31, s[18:19] offset:64
	v_add_u32_e32 v18, v33, v59
	s_waitcnt vmcnt(0)
	v_pk_mul_f32 v[16:17], v[22:23], v[14:15] op_sel_hi:[1,0]
	v_add_u32_e32 v15, 0x840, v53
	ds_write2_b32 v15, v16, v17 offset1:1
	v_pk_mul_f32 v[14:15], v[24:25], v[14:15] op_sel_hi:[1,0]
	v_add_u32_e32 v16, 0x848, v53
	ds_write2_b32 v16, v14, v15 offset1:1
	global_load_dword v14, v31, s[18:19] offset:96
	s_waitcnt vmcnt(0)
	v_pk_mul_f32 v[16:17], v[26:27], v[14:15] op_sel_hi:[1,0]
	v_add_u32_e32 v15, 0xc60, v53
	ds_write2_b32 v15, v16, v17 offset1:1
	v_pk_mul_f32 v[14:15], v[28:29], v[14:15] op_sel_hi:[1,0]
	v_add_u32_e32 v16, 0xc68, v53
	ds_write2_b32 v16, v14, v15 offset1:1
	global_load_dword v14, v31, s[18:19] offset:128
	v_mov_b32_e32 v53, v129
	s_waitcnt vmcnt(0)
	v_pk_mul_f32 v[16:17], v[64:65], v[14:15] op_sel_hi:[1,0]
	v_pk_mul_f32 v[14:15], v[66:67], v[14:15] op_sel_hi:[1,0]
	ds_write2_b32 v18, v14, v15 offset0:2 offset1:3
	global_load_dword v14, v31, s[18:19] offset:160
	ds_write2_b32 v18, v16, v17 offset1:1
	s_waitcnt vmcnt(0)
; #define LAS __attribute__((address_space(3)))
; DI unsigned cvtpk(float lo, float hi) { f32x2 v = {lo, hi}; bf16x2_t b = __builtin_convertvector(v, bf16x2_t); return __builtin_bit_cast(unsigned, b); }
; template <int KIND>
; DI void transpose_item(const float* W, int K, int N, bf16_t* WT, int ldk, const float* g0, const float* g1, const float* g2, LAS float* scr, int item, int lane) {
;     ...
;     for (int i = 0; i < 8; ++i) {
;         const int kk = 8 * i + (lane >> 3), k = k0 + kk;
;         float gn = 1.f;
;         if (KIND == 0 || KIND == 1 || KIND == 2 || KIND == 5 || KIND == 6) gn = g0[k];
;         if (KIND == 4) gn = k < 1024 ? g0[k] : (k < 1536 ? g1[k - 1024] : g2[k - 1536]);
;         LAS float* d = scr + kk * 33 + 4 * (lane & 7);
;         d[0] = tv[i][0] * gn; d[1] = tv[i][1] * gn; d[2] = tv[i][2] * gn; d[3] = tv[i][3] * gn;
;     }
;     asm volatile("s_waitcnt lgkmcnt(0)" ::: "memory");
;     int kd0 = k0;
;     if (KIND == 4) kd0 = k0 < 1024 ? k0 + 512 : (k0 < 1536 ? k0 - 1024 : k0);
;     const int c = lane & 7;
; #pragma unroll
;     for (int j = 0; j < 4; ++j) { const int n = (lane >> 3) + 8 * j; const LAS float* s = scr + (8 * c) * 33 + n;
;         u32x4 o; o.x = cvtpk(s[0 * 33], s[1 * 33]); o.y = cvtpk(s[2 * 33], s[3 * 33]); o.z = cvtpk(s[4 * 33], s[5 * 33]); o.w = cvtpk(s[6 * 33], s[7 * 33]);
;         *(u32x4*)(WT + (size_t)map_n<KIND>(n0 + n) * ldk + kd0 + 8 * c) = o; }
	v_pk_mul_f32 v[8:9], v[8:9], v[14:15] op_sel_hi:[1,0]
	v_add_u32_e32 v15, 0x420, v18
	ds_write2_b32 v15, v8, v9 offset1:1
	v_pk_mul_f32 v[8:9], v[10:11], v[14:15] op_sel_hi:[1,0]
	v_add_u32_e32 v10, 0x428, v18
	ds_write2_b32 v10, v8, v9 offset1:1
	global_load_dword v8, v31, s[18:19] offset:192
	s_waitcnt vmcnt(0)
	v_pk_mul_f32 v[4:5], v[4:5], v[8:9] op_sel_hi:[1,0]
	v_add_u32_e32 v9, 0x840, v18
	ds_write2_b32 v9, v4, v5 offset1:1
	v_pk_mul_f32 v[4:5], v[6:7], v[8:9] op_sel_hi:[1,0]
	v_add_u32_e32 v6, 0x848, v18
	ds_write2_b32 v6, v4, v5 offset1:1
	global_load_dword v4, v31, s[18:19] offset:224
	s_waitcnt vmcnt(0)
	v_pk_mul_f32 v[0:1], v[0:1], v[4:5] op_sel_hi:[1,0]
	v_add_u32_e32 v5, 0xc60, v18
	ds_write2_b32 v5, v0, v1 offset1:1
	v_pk_mul_f32 v[0:1], v[2:3], v[4:5] op_sel_hi:[1,0]
	v_add_u32_e32 v2, 0xc68, v18
	ds_write2_b32 v2, v0, v1 offset1:1
	s_waitcnt lgkmcnt(0)
	ds_read2_b32 v[4:5], v58 offset0:33 offset1:41
	ds_read2_b32 v[6:7], v58 offset1:8
	ds_read2_b32 v[8:9], v58 offset0:66 offset1:74
	ds_read2_b32 v[10:11], v58 offset0:99 offset1:107
	ds_read2_b32 v[14:15], v58 offset0:132 offset1:140
	ds_read2_b32 v[16:17], v58 offset0:165 offset1:173
	ds_read2_b32 v[18:19], v58 offset0:198 offset1:206
	ds_read2_b32 v[20:21], v58 offset0:231 offset1:239
	s_waitcnt lgkmcnt(6)
	v_cvt_pk_bf16_f32 v0, v6, v4
	v_or_b32_e32 v4, v32, v12
	v_lshlrev_b32_e32 v128, 13, v4
	v_lshl_add_u64 v[22:23], s[12:13], 0, v[128:129]
	v_lshlrev_b32_e32 v128, 1, v13
	v_lshl_add_u64 v[22:23], v[22:23], 0, v[128:129]
	v_lshl_add_u64 v[22:23], v[22:23], 0, v[52:53]
	v_add_co_u32_e32 v22, vcc, s4, v22
	s_waitcnt lgkmcnt(4)
	v_cvt_pk_bf16_f32 v1, v8, v10
	s_waitcnt lgkmcnt(2)
	v_cvt_pk_bf16_f32 v2, v14, v16
	s_waitcnt lgkmcnt(0)
	v_cvt_pk_bf16_f32 v3, v18, v20
	v_addc_co_u32_e32 v23, vcc, 0, v23, vcc
	v_or_b32_e32 v4, v51, v12
	global_store_dwordx4 v[22:23], v[0:3], off nt
	v_lshlrev_b32_e32 v4, 13, v4
	v_mov_b32_e32 v23, v129
	v_cvt_pk_bf16_f32 v0, v7, v5
	v_mov_b32_e32 v5, v129
	v_lshl_add_u64 v[4:5], s[12:13], 0, v[4:5]
	v_lshl_add_u64 v[4:5], v[4:5], 0, v[128:129]
	v_lshl_add_u64 v[4:5], v[4:5], 0, v[52:53]
	v_add_co_u32_e32 v4, vcc, s4, v4
	v_cvt_pk_bf16_f32 v1, v9, v11
	v_cvt_pk_bf16_f32 v2, v15, v17
	v_cvt_pk_bf16_f32 v3, v19, v21
	v_addc_co_u32_e32 v5, vcc, 0, v5, vcc
	global_store_dwordx4 v[4:5], v[0:3], off nt
	ds_read2_b32 v[4:5], v58 offset0:49 offset1:57
	ds_read2_b32 v[6:7], v58 offset0:16 offset1:24
	ds_read2_b32 v[8:9], v58 offset0:82 offset1:90
	ds_read2_b32 v[10:11], v58 offset0:115 offset1:123
	ds_read2_b32 v[14:15], v58 offset0:148 offset1:156
	ds_read2_b32 v[16:17], v58 offset0:181 offset1:189
	ds_read2_b32 v[18:19], v58 offset0:214 offset1:222
	ds_read2_b32 v[20:21], v58 offset0:247 offset1:255
	s_waitcnt lgkmcnt(6)
	v_cvt_pk_bf16_f32 v0, v6, v4
	v_or_b32_e32 v4, v56, v12
	v_lshlrev_b32_e32 v22, 13, v4
	v_lshl_add_u64 v[22:23], s[12:13], 0, v[22:23]
	v_lshl_add_u64 v[22:23], v[22:23], 0, v[128:129]
	v_lshl_add_u64 v[22:23], v[22:23], 0, v[52:53]
	v_add_co_u32_e32 v22, vcc, s4, v22
	s_waitcnt lgkmcnt(4)
	v_cvt_pk_bf16_f32 v1, v8, v10
	s_waitcnt lgkmcnt(2)
	v_cvt_pk_bf16_f32 v2, v14, v16
	s_waitcnt lgkmcnt(0)
	v_cvt_pk_bf16_f32 v3, v18, v20
	v_addc_co_u32_e32 v23, vcc, 0, v23, vcc
	v_or_b32_e32 v4, v57, v12
	global_store_dwordx4 v[22:23], v[0:3], off nt
	v_lshlrev_b32_e32 v4, 13, v4
	s_nop 0
	v_cvt_pk_bf16_f32 v0, v7, v5
	v_mov_b32_e32 v5, v129
	v_lshl_add_u64 v[4:5], s[12:13], 0, v[4:5]
	v_lshl_add_u64 v[4:5], v[4:5], 0, v[128:129]
	v_lshl_add_u64 v[4:5], v[4:5], 0, v[52:53]
	v_add_co_u32_e32 v4, vcc, 0x1000, v4
	v_cvt_pk_bf16_f32 v1, v9, v11
	v_cvt_pk_bf16_f32 v2, v15, v17
	v_cvt_pk_bf16_f32 v3, v19, v21
	v_addc_co_u32_e32 v5, vcc, 0, v5, vcc
	global_store_dwordx4 v[4:5], v[0:3], off nt
	s_waitcnt lgkmcnt(0)

; #define LAS __attribute__((address_space(3)))
; DI unsigned cvtpk(float lo, float hi) { f32x2 v = {lo, hi}; bf16x2_t b = __builtin_convertvector(v, bf16x2_t); return __builtin_bit_cast(unsigned, b); }
; template <int KIND>
; DI void transpose_item(const float* W, int K, int N, bf16_t* WT, int ldk, const float* g0, const float* g1, const float* g2, LAS float* scr, int item, int lane) {
;     const int nblk = N / 32, kb = item / nblk, nb = item % nblk, k0 = 64 * kb, n0 = 32 * nb;
;     f32x4 tv[8];
; #pragma unroll
;     for (int i = 0; i < 8; ++i) tv[i] = *(const f32x4*)(W + (size_t)(k0 + 8 * i + (lane >> 3)) * N + n0 + 4 * (lane & 7));
; #pragma unroll
;     for (int i = 0; i < 8; ++i) {
;         const int kk = 8 * i + (lane >> 3), k = k0 + kk;
;         float gn = 1.f;
;         if (KIND == 0 || KIND == 1 || KIND == 2 || KIND == 5 || KIND == 6) gn = g0[k];
;         if (KIND == 4) gn = k < 1024 ? g0[k] : (k < 1536 ? g1[k - 1024] : g2[k - 1536]);
;         LAS float* d = scr + kk * 33 + 4 * (lane & 7);
;         d[0] = tv[i][0] * gn; d[1] = tv[i][1] * gn; d[2] = tv[i][2] * gn; d[3] = tv[i][3] * gn;
;     }
;     asm volatile("s_waitcnt lgkmcnt(0)" ::: "memory");
;     int kd0 = k0;
;     if (KIND == 4) kd0 = k0 < 1024 ? k0 + 512 : (k0 < 1536 ? k0 - 1024 : k0);
;     const int c = lane & 7;
; #pragma unroll
;     for (int j = 0; j < 4; ++j) { const int n = (lane >> 3) + 8 * j; const LAS float* s = scr + (8 * c) * 33 + n;
;         u32x4 o; o.x = cvtpk(s[0 * 33], s[1 * 33]); o.y = cvtpk(s[2 * 33], s[3 * 33]); o.z = cvtpk(s[4 * 33], s[5 * 33]); o.w = cvtpk(s[6 * 33], s[7 * 33]);
;         *(u32x4*)(WT + (size_t)map_n<KIND>(n0 + n) * ldk + kd0 + 8 * c) = o; }
.LBB0_635:
	s_andn2_saveexec_b64 s[14:15], s[14:15]
	s_cbranch_execz .LBB0_637
	s_load_dwordx4 s[16:19], s[8:9], 0xa8
	v_add_u16_e32 v0, 0xe940, v62
	v_mul_u32_u24_e32 v1, 0xba2f, v0
	v_lshrrev_b32_e32 v1, 23, v1
	v_mul_lo_u16_e32 v2, 0xb0, v1
	v_sub_u16_e32 v0, v0, v2
	s_waitcnt lgkmcnt(0)
	s_add_u32 s18, s18, s1
	v_lshlrev_b16_e32 v13, 6, v1
	v_lshlrev_b16_e32 v12, 5, v0
	s_addc_u32 s19, s19, s0
	v_or_b32_e32 v30, v32, v13
	v_lshlrev_b32_e32 v128, 2, v12
	s_lshl_b64 s[22:23], s[38:39], 2
	v_lshl_add_u64 v[0:1], s[18:19], 0, v[128:129]
	v_lshlrev_b32_e32 v128, 2, v34
	v_mul_u32_u24_e32 v2, 0x1600, v30
	s_add_u32 s16, s16, s22
	v_lshl_add_u64 v[0:1], v[0:1], 0, v[128:129]
	v_lshlrev_b32_e32 v128, 2, v2
	s_addc_u32 s17, s17, s23
	v_lshl_add_u64 v[0:1], v[0:1], 0, v[128:129]
	v_lshlrev_b32_e32 v31, 2, v30
	global_load_dwordx4 v[14:17], v[0:1], off nt
	global_load_dword v30, v31, s[16:17]
	s_mov_b32 s4, 0x2c000
	v_add_co_u32_e32 v2, vcc, s4, v0
	v_add_u32_e32 v53, v33, v35
	s_nop 0
	v_addc_co_u32_e32 v3, vcc, 0, v1, vcc
	global_load_dwordx4 v[18:21], v[2:3], off nt
	s_mov_b32 s4, 0x58000
	v_add_co_u32_e32 v2, vcc, s4, v0
	s_mov_b32 s4, 0x84000
	s_nop 0
	v_addc_co_u32_e32 v3, vcc, 0, v1, vcc
	global_load_dwordx4 v[22:25], v[2:3], off nt
	v_add_co_u32_e32 v2, vcc, s4, v0
	s_mov_b32 s4, 0xb0000
	s_nop 0
	v_addc_co_u32_e32 v3, vcc, 0, v1, vcc
	global_load_dwordx4 v[26:29], v[2:3], off nt
	v_add_co_u32_e32 v2, vcc, s4, v0
	s_mov_b32 s4, 0xdc000
	s_nop 0
	v_addc_co_u32_e32 v3, vcc, 0, v1, vcc
	global_load_dwordx4 v[64:67], v[2:3], off nt
	v_add_co_u32_e32 v2, vcc, s4, v0
	s_mov_b32 s4, 0x108000
	s_nop 0
	v_addc_co_u32_e32 v3, vcc, 0, v1, vcc
	global_load_dwordx4 v[8:11], v[2:3], off nt
	v_add_co_u32_e32 v2, vcc, s4, v0
	s_mov_b32 s4, 0x134000
	s_nop 0
	v_addc_co_u32_e32 v3, vcc, 0, v1, vcc
	global_load_dwordx4 v[4:7], v[2:3], off nt
	v_add_co_u32_e32 v0, vcc, s4, v0
	v_lshlrev_b32_e32 v128, 1, v13
	s_nop 0
	v_addc_co_u32_e32 v1, vcc, 0, v1, vcc
	global_load_dwordx4 v[0:3], v[0:1], off nt
	s_waitcnt vmcnt(7)
	v_pk_mul_f32 v[14:15], v[14:15], v[30:31] op_sel_hi:[1,0]
	ds_write2_b32 v53, v14, v15 offset1:1
	v_pk_mul_f32 v[14:15], v[16:17], v[30:31] op_sel_hi:[1,0]
	ds_write2_b32 v53, v14, v15 offset0:2 offset1:3
	global_load_dword v14, v31, s[16:17] offset:32
	s_waitcnt vmcnt(0)
	v_pk_mul_f32 v[16:17], v[18:19], v[14:15] op_sel_hi:[1,0]
	v_add_u32_e32 v15, 0x420, v53
	ds_write2_b32 v15, v16, v17 offset1:1
	v_pk_mul_f32 v[14:15], v[20:21], v[14:15] op_sel_hi:[1,0]
	v_add_u32_e32 v16, 0x428, v53
	ds_write2_b32 v16, v14, v15 offset1:1
	global_load_dword v14, v31, s[16:17] offset:64
	v_add_u32_e32 v18, v33, v59
	s_waitcnt vmcnt(0)
	v_pk_mul_f32 v[16:17], v[22:23], v[14:15] op_sel_hi:[1,0]
	v_add_u32_e32 v15, 0x840, v53
	ds_write2_b32 v15, v16, v17 offset1:1
	v_pk_mul_f32 v[14:15], v[24:25], v[14:15] op_sel_hi:[1,0]
	v_add_u32_e32 v16, 0x848, v53
	ds_write2_b32 v16, v14, v15 offset1:1
	global_load_dword v14, v31, s[16:17] offset:96
	s_waitcnt vmcnt(0)
	v_pk_mul_f32 v[16:17], v[26:27], v[14:15] op_sel_hi:[1,0]
	v_add_u32_e32 v15, 0xc60, v53
	ds_write2_b32 v15, v16, v17 offset1:1
	v_pk_mul_f32 v[14:15], v[28:29], v[14:15] op_sel_hi:[1,0]
	v_add_u32_e32 v16, 0xc68, v53
	ds_write2_b32 v16, v14, v15 offset1:1
	global_load_dword v14, v31, s[16:17] offset:128
	s_waitcnt vmcnt(0)
	v_pk_mul_f32 v[16:17], v[64:65], v[14:15] op_sel_hi:[1,0]
	v_pk_mul_f32 v[14:15], v[66:67], v[14:15] op_sel_hi:[1,0]
	ds_write2_b32 v18, v14, v15 offset0:2 offset1:3
	global_load_dword v14, v31, s[16:17] offset:160
	ds_write2_b32 v18, v16, v17 offset1:1
	s_waitcnt vmcnt(0)
	v_pk_mul_f32 v[8:9], v[8:9], v[14:15] op_sel_hi:[1,0]
	v_add_u32_e32 v15, 0x420, v18
	ds_write2_b32 v15, v8, v9 offset1:1
	v_pk_mul_f32 v[8:9], v[10:11], v[14:15] op_sel_hi:[1,0]
	v_add_u32_e32 v10, 0x428, v18
	ds_write2_b32 v10, v8, v9 offset1:1
	global_load_dword v8, v31, s[16:17] offset:192
	s_waitcnt vmcnt(0)
	v_pk_mul_f32 v[4:5], v[4:5], v[8:9] op_sel_hi:[1,0]
	v_add_u32_e32 v9, 0x840, v18
	ds_write2_b32 v9, v4, v5 offset1:1
	v_pk_mul_f32 v[4:5], v[6:7], v[8:9] op_sel_hi:[1,0]
	v_add_u32_e32 v6, 0x848, v18
	ds_write2_b32 v6, v4, v5 offset1:1
	global_load_dword v4, v31, s[16:17] offset:224
	s_waitcnt vmcnt(0)
	v_pk_mul_f32 v[0:1], v[0:1], v[4:5] op_sel_hi:[1,0]
	v_add_u32_e32 v5, 0xc60, v18
	ds_write2_b32 v5, v0, v1 offset1:1
	v_pk_mul_f32 v[0:1], v[2:3], v[4:5] op_sel_hi:[1,0]
	v_add_u32_e32 v2, 0xc68, v18
	ds_write2_b32 v2, v0, v1 offset1:1
	s_waitcnt lgkmcnt(0)
	ds_read2_b32 v[6:7], v58 offset0:33 offset1:41
	ds_read2_b32 v[8:9], v58 offset1:8
	ds_read2_b32 v[10:11], v58 offset0:66 offset1:74
	ds_read2_b32 v[14:15], v58 offset0:99 offset1:107
	ds_read2_b32 v[16:17], v58 offset0:132 offset1:140
	ds_read2_b32 v[18:19], v58 offset0:165 offset1:173
	ds_read2_b32 v[20:21], v58 offset0:198 offset1:206
	ds_read2_b32 v[22:23], v58 offset0:231 offset1:239
	v_lshl_add_u64 v[4:5], v[38:39], 0, v[128:129]
	s_waitcnt lgkmcnt(6)
	v_cvt_pk_bf16_f32 v0, v8, v6
	v_or_b32_e32 v6, v32, v12
	v_lshlrev_b32_e32 v128, 13, v6
	v_or_b32_e32 v6, v51, v12
	s_waitcnt lgkmcnt(4)
	v_cvt_pk_bf16_f32 v1, v10, v14
	s_waitcnt lgkmcnt(2)
	v_cvt_pk_bf16_f32 v2, v16, v18
	s_waitcnt lgkmcnt(0)
	v_cvt_pk_bf16_f32 v3, v20, v22
	v_lshl_add_u64 v[24:25], v[4:5], 0, v[128:129]
	v_lshlrev_b32_e32 v128, 13, v6
	global_store_dwordx4 v[24:25], v[0:3], off nt
	s_nop 1
	v_cvt_pk_bf16_f32 v0, v9, v7
	v_cvt_pk_bf16_f32 v1, v11, v15
	v_cvt_pk_bf16_f32 v2, v17, v19
	v_cvt_pk_bf16_f32 v3, v21, v23
	v_lshl_add_u64 v[6:7], v[4:5], 0, v[128:129]
	global_store_dwordx4 v[6:7], v[0:3], off nt
	ds_read2_b32 v[6:7], v58 offset0:49 offset1:57
	ds_read2_b32 v[8:9], v58 offset0:16 offset1:24
	ds_read2_b32 v[10:11], v58 offset0:82 offset1:90
	ds_read2_b32 v[14:15], v58 offset0:115 offset1:123
	ds_read2_b32 v[16:17], v58 offset0:148 offset1:156
	ds_read2_b32 v[18:19], v58 offset0:181 offset1:189
	ds_read2_b32 v[20:21], v58 offset0:214 offset1:222
	ds_read2_b32 v[22:23], v58 offset0:247 offset1:255
	s_waitcnt lgkmcnt(6)
	v_cvt_pk_bf16_f32 v0, v8, v6
	v_or_b32_e32 v6, v56, v12
	v_lshlrev_b32_e32 v128, 13, v6
	v_or_b32_e32 v6, v57, v12
	s_waitcnt lgkmcnt(4)
	v_cvt_pk_bf16_f32 v1, v10, v14
	s_waitcnt lgkmcnt(2)
	v_cvt_pk_bf16_f32 v2, v16, v18
	s_waitcnt lgkmcnt(0)
	v_cvt_pk_bf16_f32 v3, v20, v22
	v_lshl_add_u64 v[24:25], v[4:5], 0, v[128:129]
	v_lshlrev_b32_e32 v128, 13, v6
	global_store_dwordx4 v[24:25], v[0:3], off nt
	v_lshl_add_u64 v[4:5], v[4:5], 0, v[128:129]
	s_nop 0
	v_cvt_pk_bf16_f32 v0, v9, v7
	v_cvt_pk_bf16_f32 v1, v11, v15
	v_cvt_pk_bf16_f32 v2, v17, v19
	v_cvt_pk_bf16_f32 v3, v21, v23
	global_store_dwordx4 v[4:5], v[0:3], off nt
	s_waitcnt lgkmcnt(0)

; #define LAS __attribute__((address_space(3)))
; DI unsigned cvtpk(float lo, float hi) { f32x2 v = {lo, hi}; bf16x2_t b = __builtin_convertvector(v, bf16x2_t); return __builtin_bit_cast(unsigned, b); }
; template <int KIND>
; DI void transpose_item(const float* W, int K, int N, bf16_t* WT, int ldk, const float* g0, const float* g1, const float* g2, LAS float* scr, int item, int lane) {
;     ...
;         LAS float* d = scr + kk * 33 + 4 * (lane & 7);
;         d[0] = tv[i][0] * gn; d[1] = tv[i][1] * gn; d[2] = tv[i][2] * gn; d[3] = tv[i][3] * gn;
;     }
;     asm volatile("s_waitcnt lgkmcnt(0)" ::: "memory");
;     int kd0 = k0;
;     if (KIND == 4) kd0 = k0 < 1024 ? k0 + 512 : (k0 < 1536 ? k0 - 1024 : k0);
;     const int c = lane & 7;
; #pragma unroll
;     for (int j = 0; j < 4; ++j) { const int n = (lane >> 3) + 8 * j; const LAS float* s = scr + (8 * c) * 33 + n;
;         u32x4 o; o.x = cvtpk(s[0 * 33], s[1 * 33]); o.y = cvtpk(s[2 * 33], s[3 * 33]); o.z = cvtpk(s[4 * 33], s[5 * 33]); o.w = cvtpk(s[6 * 33], s[7 * 33]);
;         *(u32x4*)(WT + (size_t)map_n<KIND>(n0 + n) * ldk + kd0 + 8 * c) = o; }
.LBB0_701:
	s_andn2_saveexec_b64 s[6:7], s[34:35]
	v_lshl_add_u64 v[4:5], s[16:17], 0, v[128:129]
	s_mov_b64 s[16:17], 0xe0
	v_lshl_add_u64 v[4:5], v[4:5], 0, s[16:17]
	s_or_b64 exec, exec, s[6:7]
	global_load_dword v4, v[4:5], off
	s_movk_i32 s4, 0x600
	v_cmp_gt_u32_e64 s[6:7], s4, v63
	s_waitcnt vmcnt(0)
	v_pk_mul_f32 v[0:1], v[0:1], v[4:5] op_sel_hi:[1,0]
	v_add_u32_e32 v5, 0xc60, v16
	ds_write2_b32 v5, v0, v1 offset1:1
	v_pk_mul_f32 v[0:1], v[2:3], v[4:5] op_sel_hi:[1,0]
	v_add_u32_e32 v2, 0xc68, v16
	ds_write2_b32 v2, v0, v1 offset1:1
	s_waitcnt lgkmcnt(0)
	ds_read2_b32 v[6:7], v58 offset0:33 offset1:41
	ds_read2_b32 v[8:9], v58 offset1:8
	ds_read2_b32 v[10:11], v58 offset0:66 offset1:74
	ds_read2_b32 v[12:13], v58 offset0:99 offset1:107
	ds_read2_b32 v[14:15], v58 offset0:132 offset1:140
	ds_read2_b32 v[16:17], v58 offset0:165 offset1:173
	ds_read2_b32 v[18:19], v58 offset0:198 offset1:206
	ds_read2_b32 v[20:21], v58 offset0:231 offset1:239
	v_add_u32_e32 v1, 0xfffffc00, v64
	v_add_u32_e32 v0, 0x200, v64
	v_cndmask_b32_e64 v1, v64, v1, s[6:7]
	v_cndmask_b32_e32 v128, v1, v0, vcc
	s_waitcnt lgkmcnt(6)
	v_cvt_pk_bf16_f32 v2, v8, v6
	v_or_b32_e32 v6, v53, v32
	v_lshl_add_u64 v[0:1], v[128:129], 1, v[40:41]
	v_lshlrev_b32_e32 v128, 12, v6
	v_or_b32_e32 v6, v53, v51
	s_waitcnt lgkmcnt(4)
	v_cvt_pk_bf16_f32 v3, v10, v12
	s_waitcnt lgkmcnt(2)
	v_cvt_pk_bf16_f32 v4, v14, v16
	s_waitcnt lgkmcnt(0)
	v_cvt_pk_bf16_f32 v5, v18, v20
	v_lshl_add_u64 v[22:23], v[0:1], 0, v[128:129]
	v_lshlrev_b32_e32 v128, 12, v6
	global_store_dwordx4 v[22:23], v[2:5], off nt
	s_nop 1
	v_cvt_pk_bf16_f32 v2, v9, v7
	v_cvt_pk_bf16_f32 v3, v11, v13
	v_cvt_pk_bf16_f32 v4, v15, v17
	v_cvt_pk_bf16_f32 v5, v19, v21
	v_lshl_add_u64 v[6:7], v[0:1], 0, v[128:129]
	global_store_dwordx4 v[6:7], v[2:5], off nt
	ds_read2_b32 v[6:7], v58 offset0:49 offset1:57
	ds_read2_b32 v[8:9], v58 offset0:16 offset1:24
	ds_read2_b32 v[10:11], v58 offset0:82 offset1:90
	ds_read2_b32 v[12:13], v58 offset0:115 offset1:123
	ds_read2_b32 v[14:15], v58 offset0:148 offset1:156
	ds_read2_b32 v[16:17], v58 offset0:181 offset1:189
	ds_read2_b32 v[18:19], v58 offset0:214 offset1:222
	ds_read2_b32 v[20:21], v58 offset0:247 offset1:255
	s_waitcnt lgkmcnt(6)
	v_cvt_pk_bf16_f32 v2, v8, v6
	v_or_b32_e32 v6, v53, v56
	v_lshlrev_b32_e32 v128, 12, v6
	v_or_b32_e32 v6, v53, v57
	s_waitcnt lgkmcnt(4)
	v_cvt_pk_bf16_f32 v3, v10, v12
	s_waitcnt lgkmcnt(2)
	v_cvt_pk_bf16_f32 v4, v14, v16
	s_waitcnt lgkmcnt(0)
	v_cvt_pk_bf16_f32 v5, v18, v20
	v_lshl_add_u64 v[22:23], v[0:1], 0, v[128:129]
	v_lshlrev_b32_e32 v128, 12, v6
	global_store_dwordx4 v[22:23], v[2:5], off nt
	v_lshl_add_u64 v[0:1], v[0:1], 0, v[128:129]
	s_nop 0
	v_cvt_pk_bf16_f32 v2, v9, v7
	v_cvt_pk_bf16_f32 v3, v11, v13
	v_cvt_pk_bf16_f32 v4, v15, v17
	v_cvt_pk_bf16_f32 v5, v19, v21
	global_store_dwordx4 v[0:1], v[2:5], off nt
	s_waitcnt lgkmcnt(0)

; #define LAS __attribute__((address_space(3)))
; DI unsigned cvtpk(float lo, float hi) { f32x2 v = {lo, hi}; bf16x2_t b = __builtin_convertvector(v, bf16x2_t); return __builtin_bit_cast(unsigned, b); }
; template <int KIND>
; DI void transpose_item(const float* W, int K, int N, bf16_t* WT, int ldk, const float* g0, const float* g1, const float* g2, LAS float* scr, int item, int lane) {
;     const int nblk = N / 32, kb = item / nblk, nb = item % nblk, k0 = 64 * kb, n0 = 32 * nb;
;     f32x4 tv[8];
; #pragma unroll
;     for (int i = 0; i < 8; ++i) tv[i] = *(const f32x4*)(W + (size_t)(k0 + 8 * i + (lane >> 3)) * N + n0 + 4 * (lane & 7));
; #pragma unroll
;     for (int i = 0; i < 8; ++i) {
;         const int kk = 8 * i + (lane >> 3), k = k0 + kk;
;         float gn = 1.f;
;         if (KIND == 0 || KIND == 1 || KIND == 2 || KIND == 5 || KIND == 6) gn = g0[k];
;         if (KIND == 4) gn = k < 1024 ? g0[k] : (k < 1536 ? g1[k - 1024] : g2[k - 1536]);
;         LAS float* d = scr + kk * 33 + 4 * (lane & 7);
;         d[0] = tv[i][0] * gn; d[1] = tv[i][1] * gn; d[2] = tv[i][2] * gn; d[3] = tv[i][3] * gn;
;     }
;     asm volatile("s_waitcnt lgkmcnt(0)" ::: "memory");
;     int kd0 = k0;
;     if (KIND == 4) kd0 = k0 < 1024 ? k0 + 512 : (k0 < 1536 ? k0 - 1024 : k0);
;     const int c = lane & 7;
; #pragma unroll
;     for (int j = 0; j < 4; ++j) { const int n = (lane >> 3) + 8 * j; const LAS float* s = scr + (8 * c) * 33 + n;
;         u32x4 o; o.x = cvtpk(s[0 * 33], s[1 * 33]); o.y = cvtpk(s[2 * 33], s[3 * 33]); o.z = cvtpk(s[4 * 33], s[5 * 33]); o.w = cvtpk(s[6 * 33], s[7 * 33]);
;         *(u32x4*)(WT + (size_t)map_n<KIND>(n0 + n) * ldk + kd0 + 8 * c) = o; }
.LBB0_705:
	s_andn2_saveexec_b64 s[6:7], s[68:69]
	s_cbranch_execz .LBB0_707
	s_load_dwordx2 s[14:15], s[8:9], 0x78
	v_add_u32_e32 v0, 0xfffe4800, v50
	v_and_b32_e32 v54, 0x3c0, v0
	v_and_b32_e32 v53, 0x1c0, v61
	v_lshlrev_b32_e32 v128, 2, v54
	s_waitcnt lgkmcnt(0)
	s_add_u32 s14, s14, s54
	s_addc_u32 s15, s15, s55
	v_or_b32_e32 v2, v53, v32
	v_lshl_add_u64 v[0:1], s[14:15], 0, v[128:129]
	v_lshlrev_b32_e32 v128, 2, v34
	v_lshl_add_u64 v[0:1], v[0:1], 0, v[128:129]
	v_lshlrev_b32_e32 v128, 12, v2
	v_lshl_add_u64 v[28:29], v[0:1], 0, v[128:129]
	s_mov_b32 s4, 0x8000
	v_add_co_u32_e32 v4, vcc, s4, v28
	global_load_dwordx4 v[0:3], v[28:29], off nt
	s_nop 0
	v_addc_co_u32_e32 v5, vcc, 0, v29, vcc
	s_mov_b32 s4, 0x10000
	global_load_dwordx4 v[4:7], v[4:5], off nt
	v_add_co_u32_e32 v8, vcc, s4, v28
	s_mov_b32 s4, 0x18000
	s_nop 0
	v_addc_co_u32_e32 v9, vcc, 0, v29, vcc
	global_load_dwordx4 v[8:11], v[8:9], off nt
	v_add_co_u32_e32 v12, vcc, s4, v28
	s_mov_b32 s4, 0x20000
	s_nop 0
	v_addc_co_u32_e32 v13, vcc, 0, v29, vcc
	global_load_dwordx4 v[12:15], v[12:13], off nt
	v_add_co_u32_e32 v16, vcc, s4, v28
	s_mov_b32 s4, 0x28000
	s_nop 0
	v_addc_co_u32_e32 v17, vcc, 0, v29, vcc
	global_load_dwordx4 v[16:19], v[16:17], off nt
	v_add_co_u32_e32 v20, vcc, s4, v28
	s_mov_b32 s4, 0x30000
	s_nop 0
	v_addc_co_u32_e32 v21, vcc, 0, v29, vcc
	global_load_dwordx4 v[20:23], v[20:21], off nt
	v_add_co_u32_e32 v24, vcc, s4, v28
	s_mov_b32 s4, 0x38000
	s_nop 0
	v_addc_co_u32_e32 v25, vcc, 0, v29, vcc
	global_load_dwordx4 v[24:27], v[24:25], off nt
	v_add_co_u32_e32 v28, vcc, s4, v28
	v_add_u32_e32 v55, v33, v35
	s_nop 0
	v_addc_co_u32_e32 v29, vcc, 0, v29, vcc
	global_load_dwordx4 v[28:31], v[28:29], off nt
	s_movk_i32 s4, 0x200
	v_cmp_gt_u32_e32 vcc, s4, v54
	v_lshlrev_b32_e32 v128, 1, v53
	s_waitcnt vmcnt(7)
	ds_write2_b32 v55, v0, v1 offset1:1
	ds_write2_b32 v55, v2, v3 offset0:2 offset1:3
	v_add_u32_e32 v0, 0x420, v55
	s_waitcnt vmcnt(6)
	ds_write2_b32 v0, v4, v5 offset1:1
	v_add_u32_e32 v0, 0x428, v55
	ds_write2_b32 v0, v6, v7 offset1:1
	v_add_u32_e32 v0, 0x840, v55
	s_waitcnt vmcnt(5)
	ds_write2_b32 v0, v8, v9 offset1:1
	v_add_u32_e32 v0, 0x848, v55
	ds_write2_b32 v0, v10, v11 offset1:1
	v_add_u32_e32 v0, 0xc60, v55
	s_waitcnt vmcnt(4)
	ds_write2_b32 v0, v12, v13 offset1:1
	v_add_u32_e32 v0, 0xc68, v55
	ds_write2_b32 v0, v14, v15 offset1:1
	v_add_u32_e32 v0, 0x1080, v55
	s_waitcnt vmcnt(3)
	ds_write2_b32 v0, v16, v17 offset1:1
	v_add_u32_e32 v0, 0x1088, v55
	ds_write2_b32 v0, v18, v19 offset1:1
	v_add_u32_e32 v0, 0x14a0, v55
	s_waitcnt vmcnt(2)
	ds_write2_b32 v0, v20, v21 offset1:1
	v_add_u32_e32 v0, 0x14a8, v55
	ds_write2_b32 v0, v22, v23 offset1:1
	v_add_u32_e32 v0, 0x18c0, v55
	s_waitcnt vmcnt(1)
	ds_write2_b32 v0, v24, v25 offset1:1
	v_add_u32_e32 v0, 0x18c8, v55
	ds_write2_b32 v0, v26, v27 offset1:1
	v_add_u32_e32 v0, 0x1ce0, v55
	s_waitcnt vmcnt(0)
	ds_write2_b32 v0, v28, v29 offset1:1
	v_add_u32_e32 v0, 0x1ce8, v55
	ds_write2_b32 v0, v30, v31 offset1:1
	s_waitcnt lgkmcnt(0)
	ds_read2_b32 v[6:7], v58 offset0:33 offset1:41
	ds_read2_b32 v[8:9], v58 offset1:8
	ds_read2_b32 v[10:11], v58 offset0:66 offset1:74
	ds_read2_b32 v[12:13], v58 offset0:99 offset1:107
	ds_read2_b32 v[14:15], v58 offset0:132 offset1:140
	ds_read2_b32 v[16:17], v58 offset0:165 offset1:173
	ds_read2_b32 v[18:19], v58 offset0:198 offset1:206
	ds_read2_b32 v[20:21], v58 offset0:231 offset1:239
	v_lshl_add_u64 v[0:1], v[42:43], 0, v[128:129]
	s_waitcnt lgkmcnt(6)
	v_cvt_pk_bf16_f32 v2, v8, v6
	v_or_b32_e32 v6, v54, v32
	v_lshlrev_b32_e32 v6, 1, v6
	v_add_u32_e32 v8, 0xfffffc01, v6
	v_cndmask_b32_e32 v22, v8, v6, vcc
	v_ashrrev_i32_e32 v23, 31, v22
	v_lshlrev_b64 v[22:23], 10, v[22:23]
	v_or_b32_e32 v6, v54, v51
	s_waitcnt lgkmcnt(4)
	v_cvt_pk_bf16_f32 v3, v10, v12
	s_waitcnt lgkmcnt(2)
	v_cvt_pk_bf16_f32 v4, v14, v16
	s_waitcnt lgkmcnt(0)
	v_cvt_pk_bf16_f32 v5, v18, v20
	v_lshl_add_u64 v[22:23], v[0:1], 0, v[22:23]
	v_lshlrev_b32_e32 v6, 1, v6
	global_store_dwordx4 v[22:23], v[2:5], off nt
	s_nop 1
	v_cvt_pk_bf16_f32 v2, v9, v7
	v_add_u32_e32 v7, 0xfffffc01, v6
	v_cndmask_b32_e32 v6, v7, v6, vcc
	v_ashrrev_i32_e32 v7, 31, v6
	v_lshlrev_b64 v[6:7], 10, v[6:7]
	v_cvt_pk_bf16_f32 v3, v11, v13
	v_cvt_pk_bf16_f32 v4, v15, v17
	v_cvt_pk_bf16_f32 v5, v19, v21
	v_lshl_add_u64 v[6:7], v[0:1], 0, v[6:7]
	global_store_dwordx4 v[6:7], v[2:5], off nt
	ds_read2_b32 v[6:7], v58 offset0:49 offset1:57
	ds_read2_b32 v[8:9], v58 offset0:16 offset1:24
	ds_read2_b32 v[10:11], v58 offset0:82 offset1:90
	ds_read2_b32 v[12:13], v58 offset0:115 offset1:123
	ds_read2_b32 v[14:15], v58 offset0:148 offset1:156
	ds_read2_b32 v[16:17], v58 offset0:181 offset1:189
	ds_read2_b32 v[18:19], v58 offset0:214 offset1:222
	ds_read2_b32 v[20:21], v58 offset0:247 offset1:255
	s_waitcnt lgkmcnt(6)
	v_cvt_pk_bf16_f32 v2, v8, v6
	v_or_b32_e32 v6, v54, v56
	v_lshlrev_b32_e32 v6, 1, v6
	v_add_u32_e32 v8, 0xfffffc01, v6
	v_cndmask_b32_e32 v22, v8, v6, vcc
	v_ashrrev_i32_e32 v23, 31, v22
	v_lshlrev_b64 v[22:23], 10, v[22:23]
	v_or_b32_e32 v6, v54, v57
	s_waitcnt lgkmcnt(4)
	v_cvt_pk_bf16_f32 v3, v10, v12
	s_waitcnt lgkmcnt(2)
	v_cvt_pk_bf16_f32 v4, v14, v16
	s_waitcnt lgkmcnt(0)
	v_cvt_pk_bf16_f32 v5, v18, v20
	v_lshl_add_u64 v[22:23], v[0:1], 0, v[22:23]
	v_lshlrev_b32_e32 v6, 1, v6
	global_store_dwordx4 v[22:23], v[2:5], off nt
	s_nop 1
	v_cvt_pk_bf16_f32 v2, v9, v7
	v_add_u32_e32 v7, 0xfffffc01, v6
	v_cndmask_b32_e32 v6, v7, v6, vcc
	v_ashrrev_i32_e32 v7, 31, v6
	v_lshlrev_b64 v[6:7], 10, v[6:7]
	v_cvt_pk_bf16_f32 v3, v11, v13
	v_cvt_pk_bf16_f32 v4, v15, v17
	v_cvt_pk_bf16_f32 v5, v19, v21
	v_lshl_add_u64 v[0:1], v[0:1], 0, v[6:7]
	global_store_dwordx4 v[0:1], v[2:5], off nt
	s_waitcnt lgkmcnt(0)

; #define LAS __attribute__((address_space(3)))
; DI unsigned cvtpk(float lo, float hi) { f32x2 v = {lo, hi}; bf16x2_t b = __builtin_convertvector(v, bf16x2_t); return __builtin_bit_cast(unsigned, b); }
; template <int KIND>
; DI void transpose_item(const float* W, int K, int N, bf16_t* WT, int ldk, const float* g0, const float* g1, const float* g2, LAS float* scr, int item, int lane) {
;     const int nblk = N / 32, kb = item / nblk, nb = item % nblk, k0 = 64 * kb, n0 = 32 * nb;
;     f32x4 tv[8];
; #pragma unroll
;     for (int i = 0; i < 8; ++i) tv[i] = *(const f32x4*)(W + (size_t)(k0 + 8 * i + (lane >> 3)) * N + n0 + 4 * (lane & 7));
; #pragma unroll
;     for (int i = 0; i < 8; ++i) {
;         const int kk = 8 * i + (lane >> 3), k = k0 + kk;
;         float gn = 1.f;
;         if (KIND == 0 || KIND == 1 || KIND == 2 || KIND == 5 || KIND == 6) gn = g0[k];
;         if (KIND == 4) gn = k < 1024 ? g0[k] : (k < 1536 ? g1[k - 1024] : g2[k - 1536]);
;         LAS float* d = scr + kk * 33 + 4 * (lane & 7);
;         d[0] = tv[i][0] * gn; d[1] = tv[i][1] * gn; d[2] = tv[i][2] * gn; d[3] = tv[i][3] * gn;
;     }
;     asm volatile("s_waitcnt lgkmcnt(0)" ::: "memory");
;     int kd0 = k0;
;     if (KIND == 4) kd0 = k0 < 1024 ? k0 + 512 : (k0 < 1536 ? k0 - 1024 : k0);
;     const int c = lane & 7;
; #pragma unroll
;     for (int j = 0; j < 4; ++j) { const int n = (lane >> 3) + 8 * j; const LAS float* s = scr + (8 * c) * 33 + n;
;         u32x4 o; o.x = cvtpk(s[0 * 33], s[1 * 33]); o.y = cvtpk(s[2 * 33], s[3 * 33]); o.z = cvtpk(s[4 * 33], s[5 * 33]); o.w = cvtpk(s[6 * 33], s[7 * 33]);
;         *(u32x4*)(WT + (size_t)map_n<KIND>(n0 + n) * ldk + kd0 + 8 * c) = o; }
.LBB0_708:
	s_andn2_saveexec_b64 s[6:7], s[66:67]
	s_cbranch_execz .LBB0_710
	s_load_dwordx4 s[16:19], s[8:9], 0x28
	v_add_u32_e32 v0, 0xfffff340, v62
	v_and_b32_e32 v13, 0xc0, v0
	v_add_u32_e32 v0, 0xfffe6800, v50
	v_and_b32_e32 v12, 0x7c0, v0
	s_waitcnt lgkmcnt(0)
	s_add_u32 s18, s18, s54
	s_addc_u32 s19, s19, s55
	v_lshlrev_b32_e32 v128, 2, v12
	v_or_b32_e32 v30, v13, v32
	v_lshl_add_u64 v[0:1], s[18:19], 0, v[128:129]
	v_lshlrev_b32_e32 v128, 2, v34
	s_add_u32 s14, s16, s60
	v_lshl_add_u64 v[0:1], v[0:1], 0, v[128:129]
	v_lshlrev_b32_e32 v128, 13, v30
	s_addc_u32 s15, s17, s61
	v_lshl_add_u64 v[0:1], v[0:1], 0, v[128:129]
	v_lshlrev_b32_e32 v31, 2, v30
	global_load_dwordx4 v[14:17], v[0:1], off nt
	global_load_dword v30, v31, s[14:15]
	s_mov_b32 s4, 0x10000
	v_add_co_u32_e32 v2, vcc, s4, v0
	v_add_u32_e32 v53, v33, v35
	s_nop 0
	v_addc_co_u32_e32 v3, vcc, 0, v1, vcc
	global_load_dwordx4 v[18:21], v[2:3], off nt
	s_mov_b32 s4, 0x20000
	v_add_co_u32_e32 v2, vcc, s4, v0
	s_mov_b32 s4, 0x30000
	s_nop 0
	v_addc_co_u32_e32 v3, vcc, 0, v1, vcc
	global_load_dwordx4 v[22:25], v[2:3], off nt
	v_add_co_u32_e32 v2, vcc, s4, v0
	s_mov_b32 s4, 0x50000
	s_nop 0
	v_addc_co_u32_e32 v3, vcc, 0, v1, vcc
	global_load_dwordx4 v[26:29], v[2:3], off nt
	v_add_co_u32_e32 v2, vcc, s89, v0
	v_lshlrev_b32_e32 v128, 1, v13
	s_nop 0
	v_addc_co_u32_e32 v3, vcc, 0, v1, vcc
	global_load_dwordx4 v[64:67], v[2:3], off nt
	v_add_co_u32_e32 v2, vcc, s4, v0
	s_mov_b32 s4, 0x60000
	s_nop 0
	v_addc_co_u32_e32 v3, vcc, 0, v1, vcc
	global_load_dwordx4 v[8:11], v[2:3], off nt
	v_add_co_u32_e32 v2, vcc, s4, v0
	s_mov_b32 s4, 0x70000
	s_nop 0
	v_addc_co_u32_e32 v3, vcc, 0, v1, vcc
	global_load_dwordx4 v[4:7], v[2:3], off nt
	v_add_co_u32_e32 v0, vcc, s4, v0
	s_waitcnt vmcnt(6)
	v_pk_mul_f32 v[14:15], v[14:15], v[30:31] op_sel_hi:[1,0]
	ds_write2_b32 v53, v14, v15 offset1:1
	v_pk_mul_f32 v[14:15], v[16:17], v[30:31] op_sel_hi:[1,0]
	ds_write2_b32 v53, v14, v15 offset0:2 offset1:3
	global_load_dword v14, v31, s[14:15] offset:32
	v_addc_co_u32_e32 v1, vcc, 0, v1, vcc
	global_load_dwordx4 v[0:3], v[0:1], off nt
	s_waitcnt vmcnt(1)
	v_pk_mul_f32 v[16:17], v[18:19], v[14:15] op_sel_hi:[1,0]
	v_add_u32_e32 v15, 0x420, v53
	ds_write2_b32 v15, v16, v17 offset1:1
	v_pk_mul_f32 v[14:15], v[20:21], v[14:15] op_sel_hi:[1,0]
	v_add_u32_e32 v16, 0x428, v53
	ds_write2_b32 v16, v14, v15 offset1:1
	global_load_dword v14, v31, s[14:15] offset:64
	v_add_u32_e32 v18, v33, v59
	s_waitcnt vmcnt(0)
	v_pk_mul_f32 v[16:17], v[22:23], v[14:15] op_sel_hi:[1,0]
	v_add_u32_e32 v15, 0x840, v53
	ds_write2_b32 v15, v16, v17 offset1:1
	v_pk_mul_f32 v[14:15], v[24:25], v[14:15] op_sel_hi:[1,0]
	v_add_u32_e32 v16, 0x848, v53
	ds_write2_b32 v16, v14, v15 offset1:1
	global_load_dword v14, v31, s[14:15] offset:96
	s_waitcnt vmcnt(0)
	v_pk_mul_f32 v[16:17], v[26:27], v[14:15] op_sel_hi:[1,0]
	v_add_u32_e32 v15, 0xc60, v53
	ds_write2_b32 v15, v16, v17 offset1:1
	v_pk_mul_f32 v[14:15], v[28:29], v[14:15] op_sel_hi:[1,0]
	v_add_u32_e32 v16, 0xc68, v53
	ds_write2_b32 v16, v14, v15 offset1:1
	global_load_dword v14, v31, s[14:15] offset:128
	s_waitcnt vmcnt(0)
	v_pk_mul_f32 v[16:17], v[64:65], v[14:15] op_sel_hi:[1,0]
	v_pk_mul_f32 v[14:15], v[66:67], v[14:15] op_sel_hi:[1,0]
	ds_write2_b32 v18, v14, v15 offset0:2 offset1:3
	global_load_dword v14, v31, s[14:15] offset:160
	ds_write2_b32 v18, v16, v17 offset1:1
	s_waitcnt vmcnt(0)
	v_pk_mul_f32 v[8:9], v[8:9], v[14:15] op_sel_hi:[1,0]
	v_add_u32_e32 v15, 0x420, v18
	ds_write2_b32 v15, v8, v9 offset1:1
	v_pk_mul_f32 v[8:9], v[10:11], v[14:15] op_sel_hi:[1,0]
	v_add_u32_e32 v10, 0x428, v18
	ds_write2_b32 v10, v8, v9 offset1:1
	global_load_dword v8, v31, s[14:15] offset:192
	s_waitcnt vmcnt(0)
	v_pk_mul_f32 v[4:5], v[4:5], v[8:9] op_sel_hi:[1,0]
	v_add_u32_e32 v9, 0x840, v18
	ds_write2_b32 v9, v4, v5 offset1:1
	v_pk_mul_f32 v[4:5], v[6:7], v[8:9] op_sel_hi:[1,0]
	v_add_u32_e32 v6, 0x848, v18
	ds_write2_b32 v6, v4, v5 offset1:1
	global_load_dword v4, v31, s[14:15] offset:224
	s_waitcnt vmcnt(0)
	v_pk_mul_f32 v[0:1], v[0:1], v[4:5] op_sel_hi:[1,0]
	v_add_u32_e32 v5, 0xc60, v18
	ds_write2_b32 v5, v0, v1 offset1:1
	v_pk_mul_f32 v[0:1], v[2:3], v[4:5] op_sel_hi:[1,0]
	v_add_u32_e32 v2, 0xc68, v18
	ds_write2_b32 v2, v0, v1 offset1:1
	s_waitcnt lgkmcnt(0)
	ds_read2_b32 v[6:7], v58 offset0:33 offset1:41
	ds_read2_b32 v[8:9], v58 offset1:8
	ds_read2_b32 v[10:11], v58 offset0:66 offset1:74
	ds_read2_b32 v[14:15], v58 offset0:99 offset1:107
	ds_read2_b32 v[16:17], v58 offset0:132 offset1:140
	ds_read2_b32 v[18:19], v58 offset0:165 offset1:173
	ds_read2_b32 v[20:21], v58 offset0:198 offset1:206
	ds_read2_b32 v[22:23], v58 offset0:231 offset1:239
	v_lshl_add_u64 v[4:5], v[44:45], 0, v[128:129]
	s_waitcnt lgkmcnt(6)
	v_cvt_pk_bf16_f32 v0, v8, v6
	v_or_b32_e32 v6, v12, v32
	v_lshlrev_b32_e32 v128, 9, v6
	v_or_b32_e32 v6, v12, v51
	s_waitcnt lgkmcnt(4)
	v_cvt_pk_bf16_f32 v1, v10, v14
	s_waitcnt lgkmcnt(2)
	v_cvt_pk_bf16_f32 v2, v16, v18
	s_waitcnt lgkmcnt(0)
	v_cvt_pk_bf16_f32 v3, v20, v22
	v_lshl_add_u64 v[24:25], v[4:5], 0, v[128:129]
	v_lshlrev_b32_e32 v128, 9, v6
	global_store_dwordx4 v[24:25], v[0:3], off nt
	s_nop 1
	v_cvt_pk_bf16_f32 v0, v9, v7
	v_cvt_pk_bf16_f32 v1, v11, v15
	v_cvt_pk_bf16_f32 v2, v17, v19
	v_cvt_pk_bf16_f32 v3, v21, v23
	v_lshl_add_u64 v[6:7], v[4:5], 0, v[128:129]
	global_store_dwordx4 v[6:7], v[0:3], off nt
	ds_read2_b32 v[6:7], v58 offset0:49 offset1:57
	ds_read2_b32 v[8:9], v58 offset0:16 offset1:24
	ds_read2_b32 v[10:11], v58 offset0:82 offset1:90
	ds_read2_b32 v[14:15], v58 offset0:115 offset1:123
	ds_read2_b32 v[16:17], v58 offset0:148 offset1:156
	ds_read2_b32 v[18:19], v58 offset0:181 offset1:189
	ds_read2_b32 v[20:21], v58 offset0:214 offset1:222
	ds_read2_b32 v[22:23], v58 offset0:247 offset1:255
	s_waitcnt lgkmcnt(6)
	v_cvt_pk_bf16_f32 v0, v8, v6
	v_or_b32_e32 v6, v12, v56
	v_lshlrev_b32_e32 v128, 9, v6
	v_or_b32_e32 v6, v12, v57
	s_waitcnt lgkmcnt(4)
	v_cvt_pk_bf16_f32 v1, v10, v14
	s_waitcnt lgkmcnt(2)
	v_cvt_pk_bf16_f32 v2, v16, v18
	s_waitcnt lgkmcnt(0)
	v_cvt_pk_bf16_f32 v3, v20, v22
	v_lshl_add_u64 v[24:25], v[4:5], 0, v[128:129]
	v_lshlrev_b32_e32 v128, 9, v6
	global_store_dwordx4 v[24:25], v[0:3], off nt
	v_lshl_add_u64 v[4:5], v[4:5], 0, v[128:129]
	s_nop 0
	v_cvt_pk_bf16_f32 v0, v9, v7
	v_cvt_pk_bf16_f32 v1, v11, v15
	v_cvt_pk_bf16_f32 v2, v17, v19
	v_cvt_pk_bf16_f32 v3, v21, v23
	global_store_dwordx4 v[4:5], v[0:3], off nt
	s_waitcnt lgkmcnt(0)

; #define LAS __attribute__((address_space(3)))
; template <int KIND>
; DI void transpose_item(const float* W, int K, int N, bf16_t* WT, int ldk, const float* g0, const float* g1, const float* g2, LAS float* scr, int item, int lane) {
;     const int nblk = N / 32, kb = item / nblk, nb = item % nblk, k0 = 64 * kb, n0 = 32 * nb;
;     f32x4 tv[8];
; #pragma unroll
;     for (int i = 0; i < 8; ++i) tv[i] = *(const f32x4*)(W + (size_t)(k0 + 8 * i + (lane >> 3)) * N + n0 + 4 * (lane & 7));
; #pragma unroll
;     for (int i = 0; i < 8; ++i) {
;         const int kk = 8 * i + (lane >> 3), k = k0 + kk;
;         float gn = 1.f;
;         if (KIND == 0 || KIND == 1 || KIND == 2 || KIND == 5 || KIND == 6) gn = g0[k];
;         if (KIND == 4) gn = k < 1024 ? g0[k] : (k < 1536 ? g1[k - 1024] : g2[k - 1536]);
;         LAS float* d = scr + kk * 33 + 4 * (lane & 7);
;         d[0] = tv[i][0] * gn; d[1] = tv[i][1] * gn; d[2] = tv[i][2] * gn; d[3] = tv[i][3] * gn;
.LBB0_711:
	s_andn2_saveexec_b64 s[14:15], s[64:65]
	s_cbranch_execz .LBB0_713
	s_load_dwordx4 s[16:19], s[8:9], 0x18
	v_add_u16_e32 v0, 0xf4c0, v62
	v_mul_u32_u24_e32 v1, 0xaaab, v0
	v_lshrrev_b32_e32 v1, 21, v1
	v_readlane_b32 s6, v255, 1
	v_mul_lo_u16_e32 v2, 48, v1
	s_mul_i32 s4, s6, 0x300000
	v_sub_u16_e32 v0, v0, v2
	s_waitcnt lgkmcnt(0)
	s_add_u32 s18, s18, s4
	s_mul_hi_u32 s4, s6, 0x300000
	v_lshlrev_b16_e32 v13, 6, v1
	v_lshlrev_b16_e32 v12, 5, v0
	v_readlane_b32 s7, v255, 2
	s_addc_u32 s19, s19, s4
	v_or_b32_e32 v30, v32, v13
	v_lshlrev_b32_e32 v128, 2, v12
	s_lshl_b64 s[6:7], s[52:53], 2
	v_lshl_add_u64 v[0:1], s[18:19], 0, v[128:129]
	v_lshlrev_b32_e32 v128, 2, v34
	v_mul_u32_u24_e32 v2, 0x600, v30
	s_add_u32 s6, s16, s6
	v_lshl_add_u64 v[0:1], v[0:1], 0, v[128:129]
	v_lshlrev_b32_e32 v128, 2, v2
	s_addc_u32 s7, s17, s7
	v_lshl_add_u64 v[0:1], v[0:1], 0, v[128:129]
	v_lshlrev_b32_e32 v31, 2, v30
	global_load_dwordx4 v[14:17], v[0:1], off nt
	global_load_dword v30, v31, s[6:7]
	s_mov_b32 s4, 0xc000
	v_add_co_u32_e32 v2, vcc, s4, v0
	v_add_u32_e32 v53, v33, v35
	s_nop 0
	v_addc_co_u32_e32 v3, vcc, 0, v1, vcc
	global_load_dwordx4 v[18:21], v[2:3], off nt
	s_mov_b32 s4, 0x18000
	v_add_co_u32_e32 v2, vcc, s4, v0
	s_mov_b32 s4, 0x24000
	s_nop 0
	v_addc_co_u32_e32 v3, vcc, 0, v1, vcc
	global_load_dwordx4 v[22:25], v[2:3], off nt
	v_add_co_u32_e32 v2, vcc, s4, v0
	s_mov_b32 s4, 0x30000
	s_nop 0
	v_addc_co_u32_e32 v3, vcc, 0, v1, vcc
	global_load_dwordx4 v[26:29], v[2:3], off nt
	v_add_co_u32_e32 v2, vcc, s4, v0
	s_mov_b32 s4, 0x3c000
	s_nop 0
	v_addc_co_u32_e32 v3, vcc, 0, v1, vcc
	global_load_dwordx4 v[64:67], v[2:3], off nt
	v_add_co_u32_e32 v2, vcc, s4, v0
	s_mov_b32 s4, 0x48000
	s_nop 0
	v_addc_co_u32_e32 v3, vcc, 0, v1, vcc
	global_load_dwordx4 v[8:11], v[2:3], off nt
	v_add_co_u32_e32 v2, vcc, s4, v0
	s_mov_b32 s4, 0x54000
	s_nop 0
	v_addc_co_u32_e32 v3, vcc, 0, v1, vcc
	global_load_dwordx4 v[4:7], v[2:3], off nt
	v_add_co_u32_e32 v0, vcc, s4, v0
	s_movk_i32 s16, 0xa0
	s_nop 0
	v_addc_co_u32_e32 v1, vcc, 0, v1, vcc
	global_load_dwordx4 v[0:3], v[0:1], off nt
	v_lshlrev_b32_e32 v128, 1, v13
	s_movk_i32 s4, 0x80
	s_waitcnt vmcnt(7)
	v_pk_mul_f32 v[14:15], v[14:15], v[30:31] op_sel_hi:[1,0]
	ds_write2_b32 v53, v14, v15 offset1:1
	v_pk_mul_f32 v[14:15], v[16:17], v[30:31] op_sel_hi:[1,0]
	ds_write2_b32 v53, v14, v15 offset0:2 offset1:3
	global_load_dword v14, v31, s[6:7] offset:32
	s_waitcnt vmcnt(0)
	v_pk_mul_f32 v[16:17], v[18:19], v[14:15] op_sel_hi:[1,0]
	v_add_u32_e32 v15, 0x420, v53
	ds_write2_b32 v15, v16, v17 offset1:1
	v_pk_mul_f32 v[14:15], v[20:21], v[14:15] op_sel_hi:[1,0]
	v_add_u32_e32 v16, 0x428, v53
	ds_write2_b32 v16, v14, v15 offset1:1
	global_load_dword v14, v31, s[6:7] offset:64
	v_add_u32_e32 v18, v33, v59
	s_waitcnt vmcnt(0)
	v_pk_mul_f32 v[16:17], v[22:23], v[14:15] op_sel_hi:[1,0]
	v_add_u32_e32 v15, 0x840, v53
	ds_write2_b32 v15, v16, v17 offset1:1
	v_pk_mul_f32 v[14:15], v[24:25], v[14:15] op_sel_hi:[1,0]
	v_add_u32_e32 v16, 0x848, v53
	ds_write2_b32 v16, v14, v15 offset1:1
	global_load_dword v14, v31, s[6:7] offset:96
	s_waitcnt vmcnt(0)
	v_pk_mul_f32 v[16:17], v[26:27], v[14:15] op_sel_hi:[1,0]
	v_add_u32_e32 v15, 0xc60, v53
	ds_write2_b32 v15, v16, v17 offset1:1
	v_pk_mul_f32 v[14:15], v[28:29], v[14:15] op_sel_hi:[1,0]
	v_add_u32_e32 v16, 0xc68, v53
	ds_write2_b32 v16, v14, v15 offset1:1
	global_load_dword v14, v31, s[6:7] offset:128
	s_waitcnt vmcnt(0)
	v_pk_mul_f32 v[16:17], v[64:65], v[14:15] op_sel_hi:[1,0]
	v_pk_mul_f32 v[14:15], v[66:67], v[14:15] op_sel_hi:[1,0]
	ds_write2_b32 v18, v14, v15 offset0:2 offset1:3
	global_load_dword v14, v31, s[6:7] offset:160
	ds_write2_b32 v18, v16, v17 offset1:1
	s_waitcnt vmcnt(0)
	v_pk_mul_f32 v[8:9], v[8:9], v[14:15] op_sel_hi:[1,0]
	v_add_u32_e32 v15, 0x420, v18
	ds_write2_b32 v15, v8, v9 offset1:1
	v_pk_mul_f32 v[8:9], v[10:11], v[14:15] op_sel_hi:[1,0]
	v_add_u32_e32 v10, 0x428, v18
	ds_write2_b32 v10, v8, v9 offset1:1
	global_load_dword v8, v31, s[6:7] offset:192
	s_waitcnt vmcnt(0)
; #define LAS __attribute__((address_space(3)))
; DI unsigned cvtpk(float lo, float hi) { f32x2 v = {lo, hi}; bf16x2_t b = __builtin_convertvector(v, bf16x2_t); return __builtin_bit_cast(unsigned, b); }
; template <int KIND> DI int map_n(int n) {
;     ...
;     if (KIND == 1) {
;         const int hd = n / 192, w = n % 192;
;         if (w < 128) return n;
;         const int j = w - 128; return hd * 192 + 128 + (j < 32 ? 2 * j : 2 * (j - 32) + 1);
;     }
; template <int KIND>
; DI void transpose_item(const float* W, int K, int N, bf16_t* WT, int ldk, const float* g0, const float* g1, const float* g2, LAS float* scr, int item, int lane) {
;     ...
;     asm volatile("s_waitcnt lgkmcnt(0)" ::: "memory");
;     int kd0 = k0;
;     if (KIND == 4) kd0 = k0 < 1024 ? k0 + 512 : (k0 < 1536 ? k0 - 1024 : k0);
;     const int c = lane & 7;
; #pragma unroll
;     for (int j = 0; j < 4; ++j) { const int n = (lane >> 3) + 8 * j; const LAS float* s = scr + (8 * c) * 33 + n;
;         u32x4 o; o.x = cvtpk(s[0 * 33], s[1 * 33]); o.y = cvtpk(s[2 * 33], s[3 * 33]); o.z = cvtpk(s[4 * 33], s[5 * 33]); o.w = cvtpk(s[6 * 33], s[7 * 33]);
;         *(u32x4*)(WT + (size_t)map_n<KIND>(n0 + n) * ldk + kd0 + 8 * c) = o; }
	v_pk_mul_f32 v[4:5], v[4:5], v[8:9] op_sel_hi:[1,0]
	v_add_u32_e32 v9, 0x840, v18
	ds_write2_b32 v9, v4, v5 offset1:1
	v_pk_mul_f32 v[4:5], v[6:7], v[8:9] op_sel_hi:[1,0]
	v_add_u32_e32 v6, 0x848, v18
	ds_write2_b32 v6, v4, v5 offset1:1
	global_load_dword v4, v31, s[6:7] offset:224
	s_waitcnt vmcnt(0)
	v_pk_mul_f32 v[0:1], v[0:1], v[4:5] op_sel_hi:[1,0]
	v_add_u32_e32 v5, 0xc60, v18
	ds_write2_b32 v5, v0, v1 offset1:1
	v_pk_mul_f32 v[0:1], v[2:3], v[4:5] op_sel_hi:[1,0]
	v_add_u32_e32 v2, 0xc68, v18
	ds_write2_b32 v2, v0, v1 offset1:1
	s_waitcnt lgkmcnt(0)
	ds_read2_b32 v[6:7], v58 offset0:33 offset1:41
	ds_read2_b32 v[8:9], v58 offset1:8
	ds_read2_b32 v[10:11], v58 offset0:66 offset1:74
	ds_read2_b32 v[14:15], v58 offset0:99 offset1:107
	ds_read2_b32 v[16:17], v58 offset0:132 offset1:140
	ds_read2_b32 v[18:19], v58 offset0:165 offset1:173
	ds_read2_b32 v[20:21], v58 offset0:198 offset1:206
	ds_read2_b32 v[22:23], v58 offset0:231 offset1:239
	v_lshl_add_u64 v[4:5], v[46:47], 0, v[128:129]
	s_waitcnt lgkmcnt(6)
	v_cvt_pk_bf16_f32 v0, v8, v6
	v_or_b32_e32 v6, v32, v12
	v_mul_u32_u24_e32 v8, 0x2aab, v6
	v_lshrrev_b32_e32 v8, 21, v8
	v_mul_lo_u16_e32 v8, 0xc0, v8
	v_sub_u16_e32 v8, v6, v8
	v_cmp_gt_u16_e64 s[6:7], s16, v8
	v_sub_u32_e32 v13, v6, v8
	s_waitcnt lgkmcnt(4)
	v_cvt_pk_bf16_f32 v1, v10, v14
	v_cmp_gt_u16_e32 vcc, s4, v8
	v_cndmask_b32_e64 v10, v201, v202, s[6:7]
	v_lshl_add_u32 v8, v8, 1, v13
	v_add3_u32 v8, v8, v10, s4
	v_cndmask_b32_e32 v24, v8, v6, vcc
	v_ashrrev_i32_e32 v25, 31, v24
	v_lshlrev_b64 v[24:25], 10, v[24:25]
	s_waitcnt lgkmcnt(2)
	v_cvt_pk_bf16_f32 v2, v16, v18
	s_waitcnt lgkmcnt(0)
	v_cvt_pk_bf16_f32 v3, v20, v22
	v_lshl_add_u64 v[24:25], v[4:5], 0, v[24:25]
	v_or_b32_e32 v6, v51, v12
	global_store_dwordx4 v[24:25], v[0:3], off nt
	s_nop 1
	v_cvt_pk_bf16_f32 v0, v9, v7
	v_mul_u32_u24_e32 v7, 0x2aab, v6
	v_lshrrev_b32_e32 v7, 21, v7
	v_mul_lo_u16_e32 v7, 0xc0, v7
	v_sub_u16_e32 v7, v6, v7
	v_cmp_gt_u16_e64 s[6:7], s16, v7
	v_sub_u32_e32 v9, v6, v7
	v_cmp_gt_u16_e32 vcc, s4, v7
	v_cndmask_b32_e64 v8, v201, v202, s[6:7]
	v_lshl_add_u32 v7, v7, 1, v9
	v_add3_u32 v7, v7, v8, s4
	v_cndmask_b32_e32 v6, v7, v6, vcc
	v_ashrrev_i32_e32 v7, 31, v6
	v_lshlrev_b64 v[6:7], 10, v[6:7]
	v_cvt_pk_bf16_f32 v1, v11, v15
	v_cvt_pk_bf16_f32 v2, v17, v19
	v_cvt_pk_bf16_f32 v3, v21, v23
	v_lshl_add_u64 v[6:7], v[4:5], 0, v[6:7]
	global_store_dwordx4 v[6:7], v[0:3], off nt
	ds_read2_b32 v[6:7], v58 offset0:16 offset1:24
	ds_read2_b32 v[8:9], v58 offset0:49 offset1:57
	ds_read2_b32 v[10:11], v58 offset0:82 offset1:90
	ds_read2_b32 v[14:15], v58 offset0:115 offset1:123
	ds_read2_b32 v[16:17], v58 offset0:148 offset1:156
	ds_read2_b32 v[18:19], v58 offset0:181 offset1:189
	ds_read2_b32 v[20:21], v58 offset0:214 offset1:222
	ds_read2_b32 v[22:23], v58 offset0:247 offset1:255
	s_waitcnt lgkmcnt(6)
	v_cvt_pk_bf16_f32 v0, v6, v8
	v_or_b32_e32 v6, v56, v12
	v_mul_u32_u24_e32 v8, 0x2aab, v6
	v_lshrrev_b32_e32 v8, 21, v8
	v_mul_lo_u16_e32 v8, 0xc0, v8
	v_sub_u16_e32 v8, v6, v8
	v_cmp_gt_u16_e64 s[6:7], s16, v8
	v_sub_u32_e32 v13, v6, v8
	s_waitcnt lgkmcnt(4)
	v_cvt_pk_bf16_f32 v1, v10, v14
	v_cmp_gt_u16_e32 vcc, s4, v8
	v_cndmask_b32_e64 v10, v201, v202, s[6:7]
	v_lshl_add_u32 v8, v8, 1, v13
	v_add3_u32 v8, v8, v10, s4
	v_cndmask_b32_e32 v24, v8, v6, vcc
	v_ashrrev_i32_e32 v25, 31, v24
	v_lshlrev_b64 v[24:25], 10, v[24:25]
	s_waitcnt lgkmcnt(2)
	v_cvt_pk_bf16_f32 v2, v16, v18
	s_waitcnt lgkmcnt(0)
	v_cvt_pk_bf16_f32 v3, v20, v22
	v_lshl_add_u64 v[24:25], v[4:5], 0, v[24:25]
	v_or_b32_e32 v6, v57, v12
	global_store_dwordx4 v[24:25], v[0:3], off nt
	s_nop 1
	v_cvt_pk_bf16_f32 v0, v7, v9
	v_mul_u32_u24_e32 v7, 0x2aab, v6
	v_lshrrev_b32_e32 v7, 21, v7
	v_mul_lo_u16_e32 v7, 0xc0, v7
	v_sub_u16_e32 v7, v6, v7
	v_cmp_gt_u16_e64 s[6:7], s16, v7
	v_sub_u32_e32 v9, v6, v7
	v_cmp_gt_u16_e32 vcc, s4, v7
	v_cndmask_b32_e64 v8, v201, v202, s[6:7]
	v_lshl_add_u32 v7, v7, 1, v9
	v_add3_u32 v7, v7, v8, s4
	v_cndmask_b32_e32 v6, v7, v6, vcc
	v_ashrrev_i32_e32 v7, 31, v6
	v_lshlrev_b64 v[6:7], 10, v[6:7]
	v_cvt_pk_bf16_f32 v1, v11, v15
	v_cvt_pk_bf16_f32 v2, v17, v19
	v_cvt_pk_bf16_f32 v3, v21, v23
	v_lshl_add_u64 v[4:5], v[4:5], 0, v[6:7]
	global_store_dwordx4 v[4:5], v[0:3], off nt
	s_waitcnt lgkmcnt(0)

; #define LAS __attribute__((address_space(3)))
; DI unsigned cvtpk(float lo, float hi) { f32x2 v = {lo, hi}; bf16x2_t b = __builtin_convertvector(v, bf16x2_t); return __builtin_bit_cast(unsigned, b); }
; template <int KIND> DI int map_n(int n) {
;     if (KIND == 0) {
;         if (n < 768) return n;
;         if (n < 832) { const int j = n - 768; return 2816 + (j < 32 ? 2 * j : 2 * (j - 32) + 1); }
;         return n - 64;
;     }
; template <int KIND>
; DI void transpose_item(const float* W, int K, int N, bf16_t* WT, int ldk, const float* g0, const float* g1, const float* g2, LAS float* scr, int item, int lane) {
;     ...
;     for (int j = 0; j < 4; ++j) { const int n = (lane >> 3) + 8 * j; const LAS float* s = scr + (8 * c) * 33 + n;
;         u32x4 o; o.x = cvtpk(s[0 * 33], s[1 * 33]); o.y = cvtpk(s[2 * 33], s[3 * 33]); o.z = cvtpk(s[4 * 33], s[5 * 33]); o.w = cvtpk(s[6 * 33], s[7 * 33]);
;         *(u32x4*)(WT + (size_t)map_n<KIND>(n0 + n) * ldk + kd0 + 8 * c) = o; }
.LBB0_721:
	s_or_b64 exec, exec, s[14:15]
	v_ashrrev_i32_e32 v15, 31, v14
	v_lshl_add_u64 v[0:1], v[10:11], 1, v[48:49]
	s_waitcnt lgkmcnt(3)
	v_cvt_pk_bf16_f32 v2, v2, v3
	s_waitcnt lgkmcnt(2)
	v_cvt_pk_bf16_f32 v3, v4, v5
	s_waitcnt lgkmcnt(1)
	v_cvt_pk_bf16_f32 v4, v6, v7
	v_lshlrev_b64 v[6:7], 12, v[14:15]
	s_waitcnt lgkmcnt(0)
	v_cvt_pk_bf16_f32 v5, v12, v13
	v_lshl_add_u64 v[6:7], v[0:1], 0, v[6:7]
	global_store_dwordx4 v[6:7], v[2:5], off nt
	ds_read2_b32 v[2:3], v58 offset0:8 offset1:41
	ds_read2_b32 v[4:5], v58 offset0:74 offset1:107
	ds_read2_b32 v[6:7], v58 offset0:140 offset1:173
	ds_read2_b32 v[10:11], v58 offset0:206 offset1:239
	v_add_u32_e32 v13, 8, v9
	s_movk_i32 s4, 0x2ff
	v_or_b32_e32 v12, v17, v51
	v_cmp_lt_i32_e32 vcc, s4, v13
	s_and_saveexec_b64 s[14:15], vcc
	s_cbranch_execz .LBB0_727
	s_movk_i32 s4, 0x33f
	v_cmp_lt_u32_e32 vcc, s4, v8
	s_and_saveexec_b64 s[16:17], vcc
	s_xor_b64 s[16:17], exec, s[16:17]
	v_subrev_u32_e32 v12, 64, v12
	s_andn2_saveexec_b64 s[16:17], s[16:17]
	s_movk_i32 s4, 0x320
	v_cmp_gt_u32_e32 vcc, s4, v8
	s_movk_i32 s4, 0x1680
	v_mul_lo_u32 v13, v16, s4
	v_cndmask_b32_e32 v12, v203, v204, vcc
	v_sub_u32_e32 v12, v12, v13
	s_movk_i32 s4, 0xffe0
	v_add3_u32 v12, v60, v12, s4
	s_or_b64 exec, exec, s[16:17]
.LBB0_727:
	s_or_b64 exec, exec, s[14:15]
	v_ashrrev_i32_e32 v13, 31, v12
	s_waitcnt lgkmcnt(3)
	v_cvt_pk_bf16_f32 v2, v2, v3
	s_waitcnt lgkmcnt(2)
	v_cvt_pk_bf16_f32 v3, v4, v5
	s_waitcnt lgkmcnt(1)
	v_cvt_pk_bf16_f32 v4, v6, v7
	v_lshlrev_b64 v[6:7], 12, v[12:13]
	s_waitcnt lgkmcnt(0)
	v_cvt_pk_bf16_f32 v5, v10, v11
	v_lshl_add_u64 v[6:7], v[0:1], 0, v[6:7]
	global_store_dwordx4 v[6:7], v[2:5], off nt
	ds_read2_b32 v[2:3], v58 offset0:16 offset1:49
	ds_read2_b32 v[4:5], v58 offset0:82 offset1:115
	ds_read2_b32 v[6:7], v58 offset0:148 offset1:181
	ds_read2_b32 v[10:11], v58 offset0:214 offset1:247
	v_add_u32_e32 v13, 16, v9
	s_movk_i32 s4, 0x2ff
	v_or_b32_e32 v12, v17, v56
	v_cmp_lt_i32_e32 vcc, s4, v13
	s_and_saveexec_b64 s[14:15], vcc
	s_cbranch_execz .LBB0_733
	s_movk_i32 s4, 0x33f
	v_cmp_lt_u32_e32 vcc, s4, v8
	s_and_saveexec_b64 s[16:17], vcc
	s_xor_b64 s[16:17], exec, s[16:17]
	v_subrev_u32_e32 v12, 64, v12
	s_andn2_saveexec_b64 s[16:17], s[16:17]
	s_movk_i32 s4, 0x320
	v_cmp_gt_u32_e32 vcc, s4, v8
	s_movk_i32 s4, 0x1680
	v_mul_lo_u32 v13, v16, s4
	v_cndmask_b32_e32 v12, v203, v204, vcc
	v_sub_u32_e32 v12, v12, v13
	v_add3_u32 v12, v60, v12, -16
	s_or_b64 exec, exec, s[16:17]
.LBB0_733:
	s_or_b64 exec, exec, s[14:15]
	v_ashrrev_i32_e32 v13, 31, v12
	s_waitcnt lgkmcnt(3)
	v_cvt_pk_bf16_f32 v2, v2, v3
	s_waitcnt lgkmcnt(2)
	v_cvt_pk_bf16_f32 v3, v4, v5
	s_waitcnt lgkmcnt(1)
	v_cvt_pk_bf16_f32 v4, v6, v7
	v_lshlrev_b64 v[6:7], 12, v[12:13]
	s_waitcnt lgkmcnt(0)
	v_cvt_pk_bf16_f32 v5, v10, v11
	v_lshl_add_u64 v[6:7], v[0:1], 0, v[6:7]
	global_store_dwordx4 v[6:7], v[2:5], off nt
	ds_read2_b32 v[2:3], v58 offset0:24 offset1:57
	ds_read2_b32 v[4:5], v58 offset0:90 offset1:123
	ds_read2_b32 v[6:7], v58 offset0:156 offset1:189
	ds_read2_b32 v[10:11], v58 offset0:222 offset1:255
	v_add_u32_e32 v9, 24, v9
	s_movk_i32 s4, 0x2ff
	v_or_b32_e32 v12, v17, v57
	v_cmp_lt_i32_e32 vcc, s4, v9
	s_and_saveexec_b64 s[14:15], vcc
	s_cbranch_execz .LBB0_622
	s_movk_i32 s4, 0x33f
	v_cmp_lt_u32_e32 vcc, s4, v8
	s_and_saveexec_b64 s[16:17], vcc
	s_xor_b64 s[16:17], exec, s[16:17]
	v_subrev_u32_e32 v12, 64, v12
	s_andn2_saveexec_b64 s[16:17], s[16:17]
	s_cbranch_execz .LBB0_621
	s_movk_i32 s4, 0x320
	v_cmp_gt_u32_e32 vcc, s4, v8
	s_movk_i32 s4, 0x1680
	v_mul_lo_u32 v9, v16, s4
	v_cndmask_b32_e32 v8, v203, v204, vcc
	v_sub_u32_e32 v8, v8, v9
	v_add_u32_e32 v12, v60, v8
	s_branch .LBB0_621

; #define LAS __attribute__((address_space(3)))
; template <int KIND>
; DI void transpose_item(const float* W, int K, int N, bf16_t* WT, int ldk, const float* g0, const float* g1, const float* g2, LAS float* scr, int item, int lane) {
;     const int nblk = N / 32, kb = item / nblk, nb = item % nblk, k0 = 64 * kb, n0 = 32 * nb;
;     f32x4 tv[8];
; #pragma unroll
;     for (int i = 0; i < 8; ++i) tv[i] = *(const f32x4*)(W + (size_t)(k0 + 8 * i + (lane >> 3)) * N + n0 + 4 * (lane & 7));
; #pragma unroll
;     for (int i = 0; i < 8; ++i) {
;         const int kk = 8 * i + (lane >> 3), k = k0 + kk;
;         float gn = 1.f;
;         if (KIND == 0 || KIND == 1 || KIND == 2 || KIND == 5 || KIND == 6) gn = g0[k];
;         if (KIND == 4) gn = k < 1024 ? g0[k] : (k < 1536 ? g1[k - 1024] : g2[k - 1536]);
;         LAS float* d = scr + kk * 33 + 4 * (lane & 7);
;         d[0] = tv[i][0] * gn; d[1] = tv[i][1] * gn; d[2] = tv[i][2] * gn; d[3] = tv[i][3] * gn;
;     }
;     asm volatile("s_waitcnt lgkmcnt(0)" ::: "memory");
;     int kd0 = k0;
;     if (KIND == 4) kd0 = k0 < 1024 ? k0 + 512 : (k0 < 1536 ? k0 - 1024 : k0);
;     const int c = lane & 7;
; #pragma unroll
;     for (int j = 0; j < 4; ++j) { const int n = (lane >> 3) + 8 * j; const LAS float* s = scr + (8 * c) * 33 + n;
;         u32x4 o; o.x = cvtpk(s[0 * 33], s[1 * 33]); o.y = cvtpk(s[2 * 33], s[3 * 33]); o.z = cvtpk(s[4 * 33], s[5 * 33]); o.w = cvtpk(s[6 * 33], s[7 * 33]);
;         *(u32x4*)(WT + (size_t)map_n<KIND>(n0 + n) * ldk + kd0 + 8 * c) = o; }
; DI void convert_weights(PP p, LAS unsigned char* lds, int l, int worker, int nworkers) {
;     ...
;     for (int it = worker; it < I_LAYER; it += nworkers) {
;         int r = it;
;         if (r < I_IN) { transpose_item<0>(p->in[2] + (size_t)l * 2048 * 2880, 2048, 2880, (bf16_t*)(wl + W_IN), 2048, p->in[1] + l * 2048, nullptr, nullptr, scr, r, lane); continue; } r -= I_IN;
;         if (r < I_UQ) { transpose_item<1>(p->in[4] + (size_t)l * 512 * 1536, 512, 1536, (bf16_t*)(wl + W_UQ), 512, p->in[3] + l * 512, nullptr, nullptr, scr, r, lane); continue; } r -= I_UQ;
;         if (r < I_UKV) { transpose_item<2>(p->in[6] + (size_t)l * 256 * 2048, 256, 2048, (bf16_t*)(wl + W_UKV), 256, p->in[5] + l * 256, nullptr, nullptr, scr, r, lane); continue; } r -= I_UKV;
.LBB0_1379:
	s_movk_i32 s4, 0xb3f
	v_cmp_lt_i32_e32 vcc, s4, v62
	s_and_saveexec_b64 s[6:7], vcc
	s_xor_b64 s[64:65], exec, s[6:7]
	s_cbranch_execz .LBB0_1469
	s_movk_i32 s4, 0xcbf
	v_cmp_lt_u32_e32 vcc, s4, v62
	s_and_saveexec_b64 s[6:7], vcc
	s_xor_b64 s[66:67], exec, s[6:7]
	s_cbranch_execz .LBB0_1466
	s_movk_i32 s4, 0xdbf
	v_cmp_lt_u32_e32 vcc, s4, v62
	s_and_saveexec_b64 s[6:7], vcc
	s_xor_b64 s[68:69], exec, s[6:7]
	s_cbranch_execz .LBB0_1463
	s_movk_i32 s4, 0xebf
	v_cmp_lt_u32_e32 vcc, s4, v62
	s_and_saveexec_b64 s[6:7], vcc
	s_xor_b64 s[70:71], exec, s[6:7]
	s_cbranch_execz .LBB0_1460
	s_movk_i32 s4, 0x16bf
	v_cmp_lt_u32_e32 vcc, s4, v62
	s_and_saveexec_b64 s[6:7], vcc
	s_xor_b64 s[6:7], exec, s[6:7]
	s_cbranch_execz .LBB0_1393
	s_movk_i32 s4, 0x2cbf
	v_cmp_lt_u32_e32 vcc, s4, v62
	s_and_saveexec_b64 s[14:15], vcc
	s_xor_b64 s[14:15], exec, s[14:15]
	s_cbranch_execz .LBB0_1390
	s_movk_i32 s4, 0x42bf
	v_cmp_lt_u32_e32 vcc, s4, v62
	s_and_saveexec_b64 s[16:17], vcc
	s_xor_b64 s[16:17], exec, s[16:17]
	s_cbranch_execz .LBB0_1387
	s_load_dwordx2 s[18:19], s[8:9], 0xc0
	v_add_u32_e32 v0, 0xffffbd40, v62
	v_and_b32_e32 v53, 0x1fc0, v0
	v_add_u32_e32 v0, 0xfff7a800, v50
	v_and_b32_e32 v54, 0x7e0, v0
	s_waitcnt lgkmcnt(0)
	s_add_u32 s18, s18, s1
	s_addc_u32 s19, s19, s0
	v_lshlrev_b32_e32 v128, 2, v54
	v_or_b32_e32 v2, v53, v32
	v_lshl_add_u64 v[0:1], s[18:19], 0, v[128:129]
	v_lshlrev_b32_e32 v128, 2, v34
	v_lshl_add_u64 v[0:1], v[0:1], 0, v[128:129]
	v_lshlrev_b32_e32 v128, 13, v2
	v_lshl_add_u64 v[28:29], v[0:1], 0, v[128:129]
	s_mov_b32 s4, 0x10000
	v_add_co_u32_e32 v4, vcc, s4, v28
	global_load_dwordx4 v[0:3], v[28:29], off nt
	s_nop 0
	v_addc_co_u32_e32 v5, vcc, 0, v29, vcc
	s_mov_b32 s4, 0x20000
	global_load_dwordx4 v[4:7], v[4:5], off nt
	v_add_co_u32_e32 v8, vcc, s4, v28
	s_mov_b32 s4, 0x30000
	s_nop 0
	v_addc_co_u32_e32 v9, vcc, 0, v29, vcc
	global_load_dwordx4 v[8:11], v[8:9], off nt
	v_add_co_u32_e32 v12, vcc, s4, v28
	s_mov_b32 s4, 0x50000
	s_nop 0
	v_addc_co_u32_e32 v13, vcc, 0, v29, vcc
	global_load_dwordx4 v[12:15], v[12:13], off nt
	v_add_co_u32_e32 v16, vcc, s89, v28
	v_add_u32_e32 v55, v33, v35
	s_nop 0
	v_addc_co_u32_e32 v17, vcc, 0, v29, vcc
	global_load_dwordx4 v[16:19], v[16:17], off nt
	v_add_co_u32_e32 v20, vcc, s4, v28
	s_mov_b32 s4, 0x60000
	s_nop 0
	v_addc_co_u32_e32 v21, vcc, 0, v29, vcc
	global_load_dwordx4 v[20:23], v[20:21], off nt
	v_add_co_u32_e32 v24, vcc, s4, v28
	s_mov_b32 s4, 0x70000
	s_nop 0
	v_addc_co_u32_e32 v25, vcc, 0, v29, vcc
	global_load_dwordx4 v[24:27], v[24:25], off nt
	v_add_co_u32_e32 v28, vcc, s4, v28
	v_lshlrev_b32_e32 v128, 1, v53
	s_nop 0
	v_addc_co_u32_e32 v29, vcc, 0, v29, vcc
	global_load_dwordx4 v[28:31], v[28:29], off nt
	s_waitcnt vmcnt(7)
	ds_write2_b32 v55, v0, v1 offset1:1
	ds_write2_b32 v55, v2, v3 offset0:2 offset1:3
	v_add_u32_e32 v0, 0x420, v55
	s_waitcnt vmcnt(6)
	ds_write2_b32 v0, v4, v5 offset1:1
	v_add_u32_e32 v0, 0x428, v55
	ds_write2_b32 v0, v6, v7 offset1:1
	v_add_u32_e32 v0, 0x840, v55
	s_waitcnt vmcnt(5)
	ds_write2_b32 v0, v8, v9 offset1:1
	v_add_u32_e32 v0, 0x848, v55
	ds_write2_b32 v0, v10, v11 offset1:1
	v_add_u32_e32 v0, 0xc60, v55
	s_waitcnt vmcnt(4)
	ds_write2_b32 v0, v12, v13 offset1:1
	v_add_u32_e32 v0, 0xc68, v55
	ds_write2_b32 v0, v14, v15 offset1:1
	v_add_u32_e32 v0, 0x1080, v55
	s_waitcnt vmcnt(3)
	ds_write2_b32 v0, v16, v17 offset1:1
	v_add_u32_e32 v0, 0x1088, v55
	ds_write2_b32 v0, v18, v19 offset1:1
	v_add_u32_e32 v0, 0x14a0, v55
	s_waitcnt vmcnt(2)
	ds_write2_b32 v0, v20, v21 offset1:1
	v_add_u32_e32 v0, 0x14a8, v55
	ds_write2_b32 v0, v22, v23 offset1:1
	v_add_u32_e32 v0, 0x18c0, v55
	s_waitcnt vmcnt(1)
	ds_write2_b32 v0, v24, v25 offset1:1
	v_add_u32_e32 v0, 0x18c8, v55
	ds_write2_b32 v0, v26, v27 offset1:1
	v_add_u32_e32 v0, 0x1ce0, v55
	s_waitcnt vmcnt(0)
	ds_write2_b32 v0, v28, v29 offset1:1
	v_add_u32_e32 v0, 0x1ce8, v55
	ds_write2_b32 v0, v30, v31 offset1:1
	s_waitcnt lgkmcnt(0)
	ds_read2_b32 v[6:7], v58 offset0:33 offset1:41
	ds_read2_b32 v[8:9], v58 offset1:8
	ds_read2_b32 v[10:11], v58 offset0:66 offset1:74
	ds_read2_b32 v[12:13], v58 offset0:99 offset1:107
	ds_read2_b32 v[14:15], v58 offset0:132 offset1:140
	ds_read2_b32 v[16:17], v58 offset0:165 offset1:173
	ds_read2_b32 v[18:19], v58 offset0:198 offset1:206
	ds_read2_b32 v[20:21], v58 offset0:231 offset1:239
	v_lshl_add_u64 v[0:1], v[36:37], 0, v[128:129]
	s_waitcnt lgkmcnt(6)
	v_cvt_pk_bf16_f32 v2, v8, v6
	v_or_b32_e32 v6, v54, v32
	v_mul_u32_u24_e32 v128, 0x2c00, v6
	v_or_b32_e32 v6, v54, v51
	s_waitcnt lgkmcnt(4)
	v_cvt_pk_bf16_f32 v3, v10, v12
	s_waitcnt lgkmcnt(2)
	v_cvt_pk_bf16_f32 v4, v14, v16
	s_waitcnt lgkmcnt(0)
	v_cvt_pk_bf16_f32 v5, v18, v20
	v_lshl_add_u64 v[22:23], v[0:1], 0, v[128:129]
	v_mul_u32_u24_e32 v128, 0x2c00, v6
	global_store_dwordx4 v[22:23], v[2:5], off nt
	s_nop 1
	v_cvt_pk_bf16_f32 v2, v9, v7
	v_cvt_pk_bf16_f32 v3, v11, v13
	v_cvt_pk_bf16_f32 v4, v15, v17
	v_cvt_pk_bf16_f32 v5, v19, v21
	v_lshl_add_u64 v[6:7], v[0:1], 0, v[128:129]
	global_store_dwordx4 v[6:7], v[2:5], off nt
	ds_read2_b32 v[6:7], v58 offset0:16 offset1:24
	ds_read2_b32 v[8:9], v58 offset0:49 offset1:57
	ds_read2_b32 v[10:11], v58 offset0:82 offset1:90
	ds_read2_b32 v[12:13], v58 offset0:115 offset1:123
	ds_read2_b32 v[14:15], v58 offset0:148 offset1:156
	ds_read2_b32 v[16:17], v58 offset0:181 offset1:189
	ds_read2_b32 v[18:19], v58 offset0:214 offset1:222
	ds_read2_b32 v[20:21], v58 offset0:247 offset1:255
	s_waitcnt lgkmcnt(6)
	v_cvt_pk_bf16_f32 v2, v6, v8
	v_or_b32_e32 v6, v54, v56
	v_mul_u32_u24_e32 v128, 0x2c00, v6
	v_or_b32_e32 v6, v54, v57
	s_waitcnt lgkmcnt(4)
	v_cvt_pk_bf16_f32 v3, v10, v12
	s_waitcnt lgkmcnt(2)
	v_cvt_pk_bf16_f32 v4, v14, v16
	s_waitcnt lgkmcnt(0)
	v_cvt_pk_bf16_f32 v5, v18, v20
	v_lshl_add_u64 v[22:23], v[0:1], 0, v[128:129]
	v_mul_u32_u24_e32 v128, 0x2c00, v6
	global_store_dwordx4 v[22:23], v[2:5], off nt
	v_lshl_add_u64 v[0:1], v[0:1], 0, v[128:129]
	s_nop 0
	v_cvt_pk_bf16_f32 v2, v7, v9
	v_cvt_pk_bf16_f32 v3, v11, v13
	v_cvt_pk_bf16_f32 v4, v15, v17
	v_cvt_pk_bf16_f32 v5, v19, v21
	global_store_dwordx4 v[0:1], v[2:5], off nt
	s_waitcnt lgkmcnt(0)

; #define LAS __attribute__((address_space(3)))
; DI unsigned cvtpk(float lo, float hi) { f32x2 v = {lo, hi}; bf16x2_t b = __builtin_convertvector(v, bf16x2_t); return __builtin_bit_cast(unsigned, b); }
; template <int KIND>
; DI void transpose_item(const float* W, int K, int N, bf16_t* WT, int ldk, const float* g0, const float* g1, const float* g2, LAS float* scr, int item, int lane) {
;     const int nblk = N / 32, kb = item / nblk, nb = item % nblk, k0 = 64 * kb, n0 = 32 * nb;
;     f32x4 tv[8];
; #pragma unroll
;     for (int i = 0; i < 8; ++i) tv[i] = *(const f32x4*)(W + (size_t)(k0 + 8 * i + (lane >> 3)) * N + n0 + 4 * (lane & 7));
; #pragma unroll
;     for (int i = 0; i < 8; ++i) {
;         const int kk = 8 * i + (lane >> 3), k = k0 + kk;
;         float gn = 1.f;
;         if (KIND == 0 || KIND == 1 || KIND == 2 || KIND == 5 || KIND == 6) gn = g0[k];
;         if (KIND == 4) gn = k < 1024 ? g0[k] : (k < 1536 ? g1[k - 1024] : g2[k - 1536]);
;         LAS float* d = scr + kk * 33 + 4 * (lane & 7);
;         d[0] = tv[i][0] * gn; d[1] = tv[i][1] * gn; d[2] = tv[i][2] * gn; d[3] = tv[i][3] * gn;
;     }
;     asm volatile("s_waitcnt lgkmcnt(0)" ::: "memory");
;     int kd0 = k0;
;     if (KIND == 4) kd0 = k0 < 1024 ? k0 + 512 : (k0 < 1536 ? k0 - 1024 : k0);
;     const int c = lane & 7;
; #pragma unroll
;     for (int j = 0; j < 4; ++j) { const int n = (lane >> 3) + 8 * j; const LAS float* s = scr + (8 * c) * 33 + n;
;         u32x4 o; o.x = cvtpk(s[0 * 33], s[1 * 33]); o.y = cvtpk(s[2 * 33], s[3 * 33]); o.z = cvtpk(s[4 * 33], s[5 * 33]); o.w = cvtpk(s[6 * 33], s[7 * 33]);
;         *(u32x4*)(WT + (size_t)map_n<KIND>(n0 + n) * ldk + kd0 + 8 * c) = o; }
.LBB0_1460:
	s_andn2_saveexec_b64 s[6:7], s[70:71]
	s_cbranch_execz .LBB0_1462
	s_load_dwordx2 s[14:15], s[8:9], 0x78
	v_add_u32_e32 v0, 0xfffe4800, v50
	v_and_b32_e32 v54, 0x3e0, v0
	v_and_b32_e32 v53, 0x1c0, v61
	v_lshlrev_b32_e32 v128, 2, v54
	s_waitcnt lgkmcnt(0)
	s_add_u32 s14, s14, s56
	s_addc_u32 s15, s15, s57
	v_or_b32_e32 v2, v53, v32
	v_lshl_add_u64 v[0:1], s[14:15], 0, v[128:129]
	v_lshlrev_b32_e32 v128, 2, v34
	v_lshl_add_u64 v[0:1], v[0:1], 0, v[128:129]
	v_lshlrev_b32_e32 v128, 12, v2
	v_lshl_add_u64 v[28:29], v[0:1], 0, v[128:129]
	s_mov_b32 s4, 0x8000
	v_add_co_u32_e32 v4, vcc, s4, v28
	global_load_dwordx4 v[0:3], v[28:29], off nt
	s_nop 0
	v_addc_co_u32_e32 v5, vcc, 0, v29, vcc
	s_mov_b32 s4, 0x10000
	global_load_dwordx4 v[4:7], v[4:5], off nt
	v_add_co_u32_e32 v8, vcc, s4, v28
	s_mov_b32 s4, 0x18000
	s_nop 0
	v_addc_co_u32_e32 v9, vcc, 0, v29, vcc
	global_load_dwordx4 v[8:11], v[8:9], off nt
	v_add_co_u32_e32 v12, vcc, s4, v28
	s_mov_b32 s4, 0x20000
	s_nop 0
	v_addc_co_u32_e32 v13, vcc, 0, v29, vcc
	global_load_dwordx4 v[12:15], v[12:13], off nt
	v_add_co_u32_e32 v16, vcc, s4, v28
	s_mov_b32 s4, 0x28000
	s_nop 0
	v_addc_co_u32_e32 v17, vcc, 0, v29, vcc
	global_load_dwordx4 v[16:19], v[16:17], off nt
	v_add_co_u32_e32 v20, vcc, s4, v28
	s_mov_b32 s4, 0x30000
	s_nop 0
	v_addc_co_u32_e32 v21, vcc, 0, v29, vcc
	global_load_dwordx4 v[20:23], v[20:21], off nt
	v_add_co_u32_e32 v24, vcc, s4, v28
	s_mov_b32 s4, 0x38000
	s_nop 0
	v_addc_co_u32_e32 v25, vcc, 0, v29, vcc
	global_load_dwordx4 v[24:27], v[24:25], off nt
	v_add_co_u32_e32 v28, vcc, s4, v28
	v_add_u32_e32 v55, v33, v35
	s_nop 0
	v_addc_co_u32_e32 v29, vcc, 0, v29, vcc
	global_load_dwordx4 v[28:31], v[28:29], off nt
	s_movk_i32 s4, 0x200
	v_cmp_gt_u32_e32 vcc, s4, v54
	v_lshlrev_b32_e32 v128, 1, v53
	s_waitcnt vmcnt(7)
	ds_write2_b32 v55, v0, v1 offset1:1
	ds_write2_b32 v55, v2, v3 offset0:2 offset1:3
	v_add_u32_e32 v0, 0x420, v55
	s_waitcnt vmcnt(6)
	ds_write2_b32 v0, v4, v5 offset1:1
	v_add_u32_e32 v0, 0x428, v55
	ds_write2_b32 v0, v6, v7 offset1:1
	v_add_u32_e32 v0, 0x840, v55
	s_waitcnt vmcnt(5)
	ds_write2_b32 v0, v8, v9 offset1:1
	v_add_u32_e32 v0, 0x848, v55
	ds_write2_b32 v0, v10, v11 offset1:1
	v_add_u32_e32 v0, 0xc60, v55
	s_waitcnt vmcnt(4)
	ds_write2_b32 v0, v12, v13 offset1:1
	v_add_u32_e32 v0, 0xc68, v55
	ds_write2_b32 v0, v14, v15 offset1:1
	v_add_u32_e32 v0, 0x1080, v55
	s_waitcnt vmcnt(3)
	ds_write2_b32 v0, v16, v17 offset1:1
	v_add_u32_e32 v0, 0x1088, v55
	ds_write2_b32 v0, v18, v19 offset1:1
	v_add_u32_e32 v0, 0x14a0, v55
	s_waitcnt vmcnt(2)
	ds_write2_b32 v0, v20, v21 offset1:1
	v_add_u32_e32 v0, 0x14a8, v55
	ds_write2_b32 v0, v22, v23 offset1:1
	v_add_u32_e32 v0, 0x18c0, v55
	s_waitcnt vmcnt(1)
	ds_write2_b32 v0, v24, v25 offset1:1
	v_add_u32_e32 v0, 0x18c8, v55
	ds_write2_b32 v0, v26, v27 offset1:1
	v_add_u32_e32 v0, 0x1ce0, v55
	s_waitcnt vmcnt(0)
	ds_write2_b32 v0, v28, v29 offset1:1
	v_add_u32_e32 v0, 0x1ce8, v55
	ds_write2_b32 v0, v30, v31 offset1:1
	s_waitcnt lgkmcnt(0)
	ds_read2_b32 v[6:7], v58 offset0:33 offset1:41
	ds_read2_b32 v[8:9], v58 offset1:8
	ds_read2_b32 v[10:11], v58 offset0:66 offset1:74
	ds_read2_b32 v[12:13], v58 offset0:99 offset1:107
	ds_read2_b32 v[14:15], v58 offset0:132 offset1:140
	ds_read2_b32 v[16:17], v58 offset0:165 offset1:173
	ds_read2_b32 v[18:19], v58 offset0:198 offset1:206
	ds_read2_b32 v[20:21], v58 offset0:231 offset1:239
	v_lshl_add_u64 v[0:1], v[42:43], 0, v[128:129]
	s_waitcnt lgkmcnt(6)
	v_cvt_pk_bf16_f32 v2, v8, v6
	v_or_b32_e32 v6, v54, v32
	v_lshlrev_b32_e32 v6, 1, v6
	v_add_u32_e32 v8, 0xfffffc01, v6
	v_cndmask_b32_e32 v22, v8, v6, vcc
	v_ashrrev_i32_e32 v23, 31, v22
	v_lshlrev_b64 v[22:23], 10, v[22:23]
	v_or_b32_e32 v6, v54, v51
	s_waitcnt lgkmcnt(4)
	v_cvt_pk_bf16_f32 v3, v10, v12
	s_waitcnt lgkmcnt(2)
	v_cvt_pk_bf16_f32 v4, v14, v16
	s_waitcnt lgkmcnt(0)
	v_cvt_pk_bf16_f32 v5, v18, v20
	v_lshl_add_u64 v[22:23], v[0:1], 0, v[22:23]
	v_lshlrev_b32_e32 v6, 1, v6
	global_store_dwordx4 v[22:23], v[2:5], off nt
	s_nop 1
	v_cvt_pk_bf16_f32 v2, v9, v7
	v_add_u32_e32 v7, 0xfffffc01, v6
	v_cndmask_b32_e32 v6, v7, v6, vcc
	v_ashrrev_i32_e32 v7, 31, v6
	v_lshlrev_b64 v[6:7], 10, v[6:7]
	v_cvt_pk_bf16_f32 v3, v11, v13
	v_cvt_pk_bf16_f32 v4, v15, v17
	v_cvt_pk_bf16_f32 v5, v19, v21
	v_lshl_add_u64 v[6:7], v[0:1], 0, v[6:7]
	global_store_dwordx4 v[6:7], v[2:5], off nt
	ds_read2_b32 v[6:7], v58 offset0:49 offset1:57
	ds_read2_b32 v[8:9], v58 offset0:16 offset1:24
	ds_read2_b32 v[10:11], v58 offset0:82 offset1:90
	ds_read2_b32 v[12:13], v58 offset0:115 offset1:123
	ds_read2_b32 v[14:15], v58 offset0:148 offset1:156
	ds_read2_b32 v[16:17], v58 offset0:181 offset1:189
	ds_read2_b32 v[18:19], v58 offset0:214 offset1:222
	ds_read2_b32 v[20:21], v58 offset0:247 offset1:255
	s_waitcnt lgkmcnt(6)
	v_cvt_pk_bf16_f32 v2, v8, v6
	v_or_b32_e32 v6, v54, v56
	v_lshlrev_b32_e32 v6, 1, v6
	v_add_u32_e32 v8, 0xfffffc01, v6
	v_cndmask_b32_e32 v22, v8, v6, vcc
	v_ashrrev_i32_e32 v23, 31, v22
	v_lshlrev_b64 v[22:23], 10, v[22:23]
	v_or_b32_e32 v6, v54, v57
	s_waitcnt lgkmcnt(4)
	v_cvt_pk_bf16_f32 v3, v10, v12
	s_waitcnt lgkmcnt(2)
	v_cvt_pk_bf16_f32 v4, v14, v16
	s_waitcnt lgkmcnt(0)
	v_cvt_pk_bf16_f32 v5, v18, v20
	v_lshl_add_u64 v[22:23], v[0:1], 0, v[22:23]
	v_lshlrev_b32_e32 v6, 1, v6
	global_store_dwordx4 v[22:23], v[2:5], off nt
	s_nop 1
	v_cvt_pk_bf16_f32 v2, v9, v7
	v_add_u32_e32 v7, 0xfffffc01, v6
	v_cndmask_b32_e32 v6, v7, v6, vcc
	v_ashrrev_i32_e32 v7, 31, v6
	v_lshlrev_b64 v[6:7], 10, v[6:7]
	v_cvt_pk_bf16_f32 v3, v11, v13
	v_cvt_pk_bf16_f32 v4, v15, v17
	v_cvt_pk_bf16_f32 v5, v19, v21
	v_lshl_add_u64 v[0:1], v[0:1], 0, v[6:7]
	global_store_dwordx4 v[0:1], v[2:5], off nt
	s_waitcnt lgkmcnt(0)

; #define LAS __attribute__((address_space(3)))
; DI unsigned cvtpk(float lo, float hi) { f32x2 v = {lo, hi}; bf16x2_t b = __builtin_convertvector(v, bf16x2_t); return __builtin_bit_cast(unsigned, b); }
; template <int KIND>
; DI void transpose_item(const float* W, int K, int N, bf16_t* WT, int ldk, const float* g0, const float* g1, const float* g2, LAS float* scr, int item, int lane) {
;     const int nblk = N / 32, kb = item / nblk, nb = item % nblk, k0 = 64 * kb, n0 = 32 * nb;
;     f32x4 tv[8];
; #pragma unroll
;     for (int i = 0; i < 8; ++i) tv[i] = *(const f32x4*)(W + (size_t)(k0 + 8 * i + (lane >> 3)) * N + n0 + 4 * (lane & 7));
; #pragma unroll
;     for (int i = 0; i < 8; ++i) {
;         const int kk = 8 * i + (lane >> 3), k = k0 + kk;
;         float gn = 1.f;
;         if (KIND == 0 || KIND == 1 || KIND == 2 || KIND == 5 || KIND == 6) gn = g0[k];
;         if (KIND == 4) gn = k < 1024 ? g0[k] : (k < 1536 ? g1[k - 1024] : g2[k - 1536]);
;         LAS float* d = scr + kk * 33 + 4 * (lane & 7);
;         d[0] = tv[i][0] * gn; d[1] = tv[i][1] * gn; d[2] = tv[i][2] * gn; d[3] = tv[i][3] * gn;
;     }
;     asm volatile("s_waitcnt lgkmcnt(0)" ::: "memory");
;     int kd0 = k0;
;     if (KIND == 4) kd0 = k0 < 1024 ? k0 + 512 : (k0 < 1536 ? k0 - 1024 : k0);
;     const int c = lane & 7;
; #pragma unroll
;     for (int j = 0; j < 4; ++j) { const int n = (lane >> 3) + 8 * j; const LAS float* s = scr + (8 * c) * 33 + n;
;         u32x4 o; o.x = cvtpk(s[0 * 33], s[1 * 33]); o.y = cvtpk(s[2 * 33], s[3 * 33]); o.z = cvtpk(s[4 * 33], s[5 * 33]); o.w = cvtpk(s[6 * 33], s[7 * 33]);
;         *(u32x4*)(WT + (size_t)map_n<KIND>(n0 + n) * ldk + kd0 + 8 * c) = o; }
.LBB0_1463:
	s_andn2_saveexec_b64 s[6:7], s[68:69]
	s_cbranch_execz .LBB0_1465
	s_load_dwordx4 s[16:19], s[8:9], 0x28
	v_add_u32_e32 v0, 0xfffff340, v62
	v_and_b32_e32 v13, 0xc0, v0
	v_add_u32_e32 v0, 0xfffe6800, v50
	v_and_b32_e32 v12, 0x7e0, v0
	s_waitcnt lgkmcnt(0)
	s_add_u32 s18, s18, s56
	s_addc_u32 s19, s19, s57
	v_lshlrev_b32_e32 v128, 2, v12
	v_or_b32_e32 v30, v13, v32
	v_lshl_add_u64 v[0:1], s[18:19], 0, v[128:129]
	v_lshlrev_b32_e32 v128, 2, v34
	s_add_u32 s14, s16, s62
	v_lshl_add_u64 v[0:1], v[0:1], 0, v[128:129]
	v_lshlrev_b32_e32 v128, 13, v30
	s_addc_u32 s15, s17, s63
	v_lshl_add_u64 v[0:1], v[0:1], 0, v[128:129]
	v_lshlrev_b32_e32 v31, 2, v30
	global_load_dwordx4 v[14:17], v[0:1], off nt
	global_load_dword v30, v31, s[14:15]
	s_mov_b32 s4, 0x10000
	v_add_co_u32_e32 v2, vcc, s4, v0
	v_add_u32_e32 v53, v33, v35
	s_nop 0
	v_addc_co_u32_e32 v3, vcc, 0, v1, vcc
	global_load_dwordx4 v[18:21], v[2:3], off nt
	s_mov_b32 s4, 0x20000
	v_add_co_u32_e32 v2, vcc, s4, v0
	s_mov_b32 s4, 0x30000
	s_nop 0
	v_addc_co_u32_e32 v3, vcc, 0, v1, vcc
	global_load_dwordx4 v[22:25], v[2:3], off nt
	v_add_co_u32_e32 v2, vcc, s4, v0
	s_mov_b32 s4, 0x50000
	s_nop 0
	v_addc_co_u32_e32 v3, vcc, 0, v1, vcc
	global_load_dwordx4 v[26:29], v[2:3], off nt
	v_add_co_u32_e32 v2, vcc, s89, v0
	v_lshlrev_b32_e32 v128, 1, v13
	s_nop 0
	v_addc_co_u32_e32 v3, vcc, 0, v1, vcc
	global_load_dwordx4 v[64:67], v[2:3], off nt
	v_add_co_u32_e32 v2, vcc, s4, v0
	s_mov_b32 s4, 0x60000
	s_nop 0
	v_addc_co_u32_e32 v3, vcc, 0, v1, vcc
	global_load_dwordx4 v[8:11], v[2:3], off nt
	v_add_co_u32_e32 v2, vcc, s4, v0
	s_mov_b32 s4, 0x70000
	s_nop 0
	v_addc_co_u32_e32 v3, vcc, 0, v1, vcc
	global_load_dwordx4 v[4:7], v[2:3], off nt
	v_add_co_u32_e32 v0, vcc, s4, v0
	s_waitcnt vmcnt(6)
	v_pk_mul_f32 v[14:15], v[14:15], v[30:31] op_sel_hi:[1,0]
	ds_write2_b32 v53, v14, v15 offset1:1
	v_pk_mul_f32 v[14:15], v[16:17], v[30:31] op_sel_hi:[1,0]
	ds_write2_b32 v53, v14, v15 offset0:2 offset1:3
	global_load_dword v14, v31, s[14:15] offset:32
	v_addc_co_u32_e32 v1, vcc, 0, v1, vcc
	global_load_dwordx4 v[0:3], v[0:1], off nt
	s_waitcnt vmcnt(1)
	v_pk_mul_f32 v[16:17], v[18:19], v[14:15] op_sel_hi:[1,0]
	v_add_u32_e32 v15, 0x420, v53
	ds_write2_b32 v15, v16, v17 offset1:1
	v_pk_mul_f32 v[14:15], v[20:21], v[14:15] op_sel_hi:[1,0]
	v_add_u32_e32 v16, 0x428, v53
	ds_write2_b32 v16, v14, v15 offset1:1
	global_load_dword v14, v31, s[14:15] offset:64
	v_add_u32_e32 v18, v33, v59
	s_waitcnt vmcnt(0)
	v_pk_mul_f32 v[16:17], v[22:23], v[14:15] op_sel_hi:[1,0]
	v_add_u32_e32 v15, 0x840, v53
	ds_write2_b32 v15, v16, v17 offset1:1
	v_pk_mul_f32 v[14:15], v[24:25], v[14:15] op_sel_hi:[1,0]
	v_add_u32_e32 v16, 0x848, v53
	ds_write2_b32 v16, v14, v15 offset1:1
	global_load_dword v14, v31, s[14:15] offset:96
	s_waitcnt vmcnt(0)
	v_pk_mul_f32 v[16:17], v[26:27], v[14:15] op_sel_hi:[1,0]
	v_add_u32_e32 v15, 0xc60, v53
	ds_write2_b32 v15, v16, v17 offset1:1
	v_pk_mul_f32 v[14:15], v[28:29], v[14:15] op_sel_hi:[1,0]
	v_add_u32_e32 v16, 0xc68, v53
	ds_write2_b32 v16, v14, v15 offset1:1
	global_load_dword v14, v31, s[14:15] offset:128
	s_waitcnt vmcnt(0)
	v_pk_mul_f32 v[16:17], v[64:65], v[14:15] op_sel_hi:[1,0]
	v_pk_mul_f32 v[14:15], v[66:67], v[14:15] op_sel_hi:[1,0]
	ds_write2_b32 v18, v14, v15 offset0:2 offset1:3
	global_load_dword v14, v31, s[14:15] offset:160
	ds_write2_b32 v18, v16, v17 offset1:1
	s_waitcnt vmcnt(0)
	v_pk_mul_f32 v[8:9], v[8:9], v[14:15] op_sel_hi:[1,0]
	v_add_u32_e32 v15, 0x420, v18
	ds_write2_b32 v15, v8, v9 offset1:1
	v_pk_mul_f32 v[8:9], v[10:11], v[14:15] op_sel_hi:[1,0]
	v_add_u32_e32 v10, 0x428, v18
	ds_write2_b32 v10, v8, v9 offset1:1
	global_load_dword v8, v31, s[14:15] offset:192
	s_waitcnt vmcnt(0)
	v_pk_mul_f32 v[4:5], v[4:5], v[8:9] op_sel_hi:[1,0]
	v_add_u32_e32 v9, 0x840, v18
	ds_write2_b32 v9, v4, v5 offset1:1
	v_pk_mul_f32 v[4:5], v[6:7], v[8:9] op_sel_hi:[1,0]
	v_add_u32_e32 v6, 0x848, v18
	ds_write2_b32 v6, v4, v5 offset1:1
	global_load_dword v4, v31, s[14:15] offset:224
	s_waitcnt vmcnt(0)
	v_pk_mul_f32 v[0:1], v[0:1], v[4:5] op_sel_hi:[1,0]
	v_add_u32_e32 v5, 0xc60, v18
	ds_write2_b32 v5, v0, v1 offset1:1
	v_pk_mul_f32 v[0:1], v[2:3], v[4:5] op_sel_hi:[1,0]
	v_add_u32_e32 v2, 0xc68, v18
	ds_write2_b32 v2, v0, v1 offset1:1
	s_waitcnt lgkmcnt(0)
	ds_read2_b32 v[6:7], v58 offset0:33 offset1:41
	ds_read2_b32 v[8:9], v58 offset1:8
	ds_read2_b32 v[10:11], v58 offset0:66 offset1:74
	ds_read2_b32 v[14:15], v58 offset0:99 offset1:107
	ds_read2_b32 v[16:17], v58 offset0:132 offset1:140
	ds_read2_b32 v[18:19], v58 offset0:165 offset1:173
	ds_read2_b32 v[20:21], v58 offset0:198 offset1:206
	ds_read2_b32 v[22:23], v58 offset0:231 offset1:239
	v_lshl_add_u64 v[4:5], v[44:45], 0, v[128:129]
	s_waitcnt lgkmcnt(6)
	v_cvt_pk_bf16_f32 v0, v8, v6
	v_or_b32_e32 v6, v12, v32
	v_lshlrev_b32_e32 v128, 9, v6
	v_or_b32_e32 v6, v12, v51
	s_waitcnt lgkmcnt(4)
	v_cvt_pk_bf16_f32 v1, v10, v14
	s_waitcnt lgkmcnt(2)
	v_cvt_pk_bf16_f32 v2, v16, v18
	s_waitcnt lgkmcnt(0)
	v_cvt_pk_bf16_f32 v3, v20, v22
	v_lshl_add_u64 v[24:25], v[4:5], 0, v[128:129]
	v_lshlrev_b32_e32 v128, 9, v6
	global_store_dwordx4 v[24:25], v[0:3], off nt
	s_nop 1
	v_cvt_pk_bf16_f32 v0, v9, v7
	v_cvt_pk_bf16_f32 v1, v11, v15
	v_cvt_pk_bf16_f32 v2, v17, v19
	v_cvt_pk_bf16_f32 v3, v21, v23
	v_lshl_add_u64 v[6:7], v[4:5], 0, v[128:129]
	global_store_dwordx4 v[6:7], v[0:3], off nt
	ds_read2_b32 v[6:7], v58 offset0:49 offset1:57
	ds_read2_b32 v[8:9], v58 offset0:16 offset1:24
	ds_read2_b32 v[10:11], v58 offset0:82 offset1:90
	ds_read2_b32 v[14:15], v58 offset0:115 offset1:123
	ds_read2_b32 v[16:17], v58 offset0:148 offset1:156
	ds_read2_b32 v[18:19], v58 offset0:181 offset1:189
	ds_read2_b32 v[20:21], v58 offset0:214 offset1:222
	ds_read2_b32 v[22:23], v58 offset0:247 offset1:255
	s_waitcnt lgkmcnt(6)
	v_cvt_pk_bf16_f32 v0, v8, v6
	v_or_b32_e32 v6, v12, v56
	v_lshlrev_b32_e32 v128, 9, v6
	v_or_b32_e32 v6, v12, v57
	s_waitcnt lgkmcnt(4)
	v_cvt_pk_bf16_f32 v1, v10, v14
	s_waitcnt lgkmcnt(2)
	v_cvt_pk_bf16_f32 v2, v16, v18
	s_waitcnt lgkmcnt(0)
	v_cvt_pk_bf16_f32 v3, v20, v22
	v_lshl_add_u64 v[24:25], v[4:5], 0, v[128:129]
	v_lshlrev_b32_e32 v128, 9, v6
	global_store_dwordx4 v[24:25], v[0:3], off nt
	v_lshl_add_u64 v[4:5], v[4:5], 0, v[128:129]
	s_nop 0
	v_cvt_pk_bf16_f32 v0, v9, v7
	v_cvt_pk_bf16_f32 v1, v11, v15
	v_cvt_pk_bf16_f32 v2, v17, v19
	v_cvt_pk_bf16_f32 v3, v21, v23
	global_store_dwordx4 v[4:5], v[0:3], off nt
	s_waitcnt lgkmcnt(0)

; #define LAS __attribute__((address_space(3)))
; template <int KIND>
; DI void transpose_item(const float* W, int K, int N, bf16_t* WT, int ldk, const float* g0, const float* g1, const float* g2, LAS float* scr, int item, int lane) {
;     const int nblk = N / 32, kb = item / nblk, nb = item % nblk, k0 = 64 * kb, n0 = 32 * nb;
;     f32x4 tv[8];
; #pragma unroll
;     for (int i = 0; i < 8; ++i) tv[i] = *(const f32x4*)(W + (size_t)(k0 + 8 * i + (lane >> 3)) * N + n0 + 4 * (lane & 7));
; #pragma unroll
;     for (int i = 0; i < 8; ++i) {
;         const int kk = 8 * i + (lane >> 3), k = k0 + kk;
;         float gn = 1.f;
;         if (KIND == 0 || KIND == 1 || KIND == 2 || KIND == 5 || KIND == 6) gn = g0[k];
;         if (KIND == 4) gn = k < 1024 ? g0[k] : (k < 1536 ? g1[k - 1024] : g2[k - 1536]);
;         LAS float* d = scr + kk * 33 + 4 * (lane & 7);
;         d[0] = tv[i][0] * gn; d[1] = tv[i][1] * gn; d[2] = tv[i][2] * gn; d[3] = tv[i][3] * gn;
.LBB0_1466:
	s_andn2_saveexec_b64 s[14:15], s[66:67]
	s_cbranch_execz .LBB0_1468
	s_load_dwordx4 s[16:19], s[8:9], 0x18
	v_add_u16_e32 v0, 0xf4c0, v62
	v_mul_u32_u24_e32 v1, 0xaaab, v0
	v_lshrrev_b32_e32 v1, 21, v1
	v_readlane_b32 s6, v255, 1
	v_mul_lo_u16_e32 v2, 48, v1
	s_mul_i32 s4, s6, 0x300000
	v_sub_u16_e32 v0, v0, v2
	s_waitcnt lgkmcnt(0)
	s_add_u32 s18, s18, s4
	s_mul_hi_u32 s4, s6, 0x300000
	v_lshlrev_b16_e32 v13, 6, v1
	v_lshlrev_b16_e32 v12, 5, v0
	v_readlane_b32 s7, v255, 2
	s_addc_u32 s19, s19, s4
	v_or_b32_e32 v30, v32, v13
	v_lshlrev_b32_e32 v128, 2, v12
	s_lshl_b64 s[6:7], s[44:45], 2
	v_lshl_add_u64 v[0:1], s[18:19], 0, v[128:129]
	v_lshlrev_b32_e32 v128, 2, v34
	v_mul_u32_u24_e32 v2, 0x600, v30
	s_add_u32 s6, s16, s6
	v_lshl_add_u64 v[0:1], v[0:1], 0, v[128:129]
	v_lshlrev_b32_e32 v128, 2, v2
	s_addc_u32 s7, s17, s7
	v_lshl_add_u64 v[0:1], v[0:1], 0, v[128:129]
	v_lshlrev_b32_e32 v31, 2, v30
	global_load_dwordx4 v[14:17], v[0:1], off nt
	global_load_dword v30, v31, s[6:7]
	s_mov_b32 s4, 0xc000
	v_add_co_u32_e32 v2, vcc, s4, v0
	v_add_u32_e32 v53, v33, v35
	s_nop 0
	v_addc_co_u32_e32 v3, vcc, 0, v1, vcc
	global_load_dwordx4 v[18:21], v[2:3], off nt
	s_mov_b32 s4, 0x18000
	v_add_co_u32_e32 v2, vcc, s4, v0
	s_mov_b32 s4, 0x24000
	s_nop 0
	v_addc_co_u32_e32 v3, vcc, 0, v1, vcc
	global_load_dwordx4 v[22:25], v[2:3], off nt
	v_add_co_u32_e32 v2, vcc, s4, v0
	s_mov_b32 s4, 0x30000
	s_nop 0
	v_addc_co_u32_e32 v3, vcc, 0, v1, vcc
	global_load_dwordx4 v[26:29], v[2:3], off nt
	v_add_co_u32_e32 v2, vcc, s4, v0
	s_mov_b32 s4, 0x3c000
	s_nop 0
	v_addc_co_u32_e32 v3, vcc, 0, v1, vcc
	global_load_dwordx4 v[64:67], v[2:3], off nt
	v_add_co_u32_e32 v2, vcc, s4, v0
	s_mov_b32 s4, 0x48000
	s_nop 0
	v_addc_co_u32_e32 v3, vcc, 0, v1, vcc
	global_load_dwordx4 v[8:11], v[2:3], off nt
	v_add_co_u32_e32 v2, vcc, s4, v0
	s_mov_b32 s4, 0x54000
	s_nop 0
	v_addc_co_u32_e32 v3, vcc, 0, v1, vcc
	global_load_dwordx4 v[4:7], v[2:3], off nt
	v_add_co_u32_e32 v0, vcc, s4, v0
	s_movk_i32 s16, 0xa0
	s_nop 0
	v_addc_co_u32_e32 v1, vcc, 0, v1, vcc
	global_load_dwordx4 v[0:3], v[0:1], off nt
	v_lshlrev_b32_e32 v128, 1, v13
	s_movk_i32 s4, 0x80
	s_waitcnt vmcnt(7)
	v_pk_mul_f32 v[14:15], v[14:15], v[30:31] op_sel_hi:[1,0]
	ds_write2_b32 v53, v14, v15 offset1:1
	v_pk_mul_f32 v[14:15], v[16:17], v[30:31] op_sel_hi:[1,0]
	ds_write2_b32 v53, v14, v15 offset0:2 offset1:3
	global_load_dword v14, v31, s[6:7] offset:32
	s_waitcnt vmcnt(0)
	v_pk_mul_f32 v[16:17], v[18:19], v[14:15] op_sel_hi:[1,0]
	v_add_u32_e32 v15, 0x420, v53
	ds_write2_b32 v15, v16, v17 offset1:1
	v_pk_mul_f32 v[14:15], v[20:21], v[14:15] op_sel_hi:[1,0]
	v_add_u32_e32 v16, 0x428, v53
	ds_write2_b32 v16, v14, v15 offset1:1
	global_load_dword v14, v31, s[6:7] offset:64
	v_add_u32_e32 v18, v33, v59
	s_waitcnt vmcnt(0)
	v_pk_mul_f32 v[16:17], v[22:23], v[14:15] op_sel_hi:[1,0]
	v_add_u32_e32 v15, 0x840, v53
	ds_write2_b32 v15, v16, v17 offset1:1
	v_pk_mul_f32 v[14:15], v[24:25], v[14:15] op_sel_hi:[1,0]
	v_add_u32_e32 v16, 0x848, v53
	ds_write2_b32 v16, v14, v15 offset1:1
	global_load_dword v14, v31, s[6:7] offset:96
	s_waitcnt vmcnt(0)
	v_pk_mul_f32 v[16:17], v[26:27], v[14:15] op_sel_hi:[1,0]
	v_add_u32_e32 v15, 0xc60, v53
	ds_write2_b32 v15, v16, v17 offset1:1
	v_pk_mul_f32 v[14:15], v[28:29], v[14:15] op_sel_hi:[1,0]
	v_add_u32_e32 v16, 0xc68, v53
	ds_write2_b32 v16, v14, v15 offset1:1
	global_load_dword v14, v31, s[6:7] offset:128
	s_waitcnt vmcnt(0)
	v_pk_mul_f32 v[16:17], v[64:65], v[14:15] op_sel_hi:[1,0]
	v_pk_mul_f32 v[14:15], v[66:67], v[14:15] op_sel_hi:[1,0]
	ds_write2_b32 v18, v14, v15 offset0:2 offset1:3
	global_load_dword v14, v31, s[6:7] offset:160
	ds_write2_b32 v18, v16, v17 offset1:1
	s_waitcnt vmcnt(0)
	v_pk_mul_f32 v[8:9], v[8:9], v[14:15] op_sel_hi:[1,0]
	v_add_u32_e32 v15, 0x420, v18
	ds_write2_b32 v15, v8, v9 offset1:1
	v_pk_mul_f32 v[8:9], v[10:11], v[14:15] op_sel_hi:[1,0]
	v_add_u32_e32 v10, 0x428, v18
	ds_write2_b32 v10, v8, v9 offset1:1
	global_load_dword v8, v31, s[6:7] offset:192
	s_waitcnt vmcnt(0)
; #define LAS __attribute__((address_space(3)))
; DI unsigned cvtpk(float lo, float hi) { f32x2 v = {lo, hi}; bf16x2_t b = __builtin_convertvector(v, bf16x2_t); return __builtin_bit_cast(unsigned, b); }
; template <int KIND> DI int map_n(int n) {
;     ...
;     if (KIND == 1) {
;         const int hd = n / 192, w = n % 192;
;         if (w < 128) return n;
;         const int j = w - 128; return hd * 192 + 128 + (j < 32 ? 2 * j : 2 * (j - 32) + 1);
;     }
; template <int KIND>
; DI void transpose_item(const float* W, int K, int N, bf16_t* WT, int ldk, const float* g0, const float* g1, const float* g2, LAS float* scr, int item, int lane) {
;     ...
;     asm volatile("s_waitcnt lgkmcnt(0)" ::: "memory");
;     int kd0 = k0;
;     if (KIND == 4) kd0 = k0 < 1024 ? k0 + 512 : (k0 < 1536 ? k0 - 1024 : k0);
;     const int c = lane & 7;
; #pragma unroll
;     for (int j = 0; j < 4; ++j) { const int n = (lane >> 3) + 8 * j; const LAS float* s = scr + (8 * c) * 33 + n;
;         u32x4 o; o.x = cvtpk(s[0 * 33], s[1 * 33]); o.y = cvtpk(s[2 * 33], s[3 * 33]); o.z = cvtpk(s[4 * 33], s[5 * 33]); o.w = cvtpk(s[6 * 33], s[7 * 33]);
;         *(u32x4*)(WT + (size_t)map_n<KIND>(n0 + n) * ldk + kd0 + 8 * c) = o; }
	v_pk_mul_f32 v[4:5], v[4:5], v[8:9] op_sel_hi:[1,0]
	v_add_u32_e32 v9, 0x840, v18
	ds_write2_b32 v9, v4, v5 offset1:1
	v_pk_mul_f32 v[4:5], v[6:7], v[8:9] op_sel_hi:[1,0]
	v_add_u32_e32 v6, 0x848, v18
	ds_write2_b32 v6, v4, v5 offset1:1
	global_load_dword v4, v31, s[6:7] offset:224
	s_waitcnt vmcnt(0)
	v_pk_mul_f32 v[0:1], v[0:1], v[4:5] op_sel_hi:[1,0]
	v_add_u32_e32 v5, 0xc60, v18
	ds_write2_b32 v5, v0, v1 offset1:1
	v_pk_mul_f32 v[0:1], v[2:3], v[4:5] op_sel_hi:[1,0]
	v_add_u32_e32 v2, 0xc68, v18
	ds_write2_b32 v2, v0, v1 offset1:1
	s_waitcnt lgkmcnt(0)
	ds_read2_b32 v[6:7], v58 offset0:33 offset1:41
	ds_read2_b32 v[8:9], v58 offset1:8
	ds_read2_b32 v[10:11], v58 offset0:66 offset1:74
	ds_read2_b32 v[14:15], v58 offset0:99 offset1:107
	ds_read2_b32 v[16:17], v58 offset0:132 offset1:140
	ds_read2_b32 v[18:19], v58 offset0:165 offset1:173
	ds_read2_b32 v[20:21], v58 offset0:198 offset1:206
	ds_read2_b32 v[22:23], v58 offset0:231 offset1:239
	v_lshl_add_u64 v[4:5], v[46:47], 0, v[128:129]
	s_waitcnt lgkmcnt(6)
	v_cvt_pk_bf16_f32 v0, v8, v6
	v_or_b32_e32 v6, v32, v12
	v_mul_u32_u24_e32 v8, 0x2aab, v6
	v_lshrrev_b32_e32 v8, 21, v8
	v_mul_lo_u16_e32 v8, 0xc0, v8
	v_sub_u16_e32 v8, v6, v8
	v_cmp_gt_u16_e64 s[6:7], s16, v8
	v_sub_u32_e32 v13, v6, v8
	s_waitcnt lgkmcnt(4)
	v_cvt_pk_bf16_f32 v1, v10, v14
	v_cmp_gt_u16_e32 vcc, s4, v8
	v_cndmask_b32_e64 v10, v201, v202, s[6:7]
	v_lshl_add_u32 v8, v8, 1, v13
	v_add3_u32 v8, v8, v10, s4
	v_cndmask_b32_e32 v24, v8, v6, vcc
	v_ashrrev_i32_e32 v25, 31, v24
	v_lshlrev_b64 v[24:25], 10, v[24:25]
	s_waitcnt lgkmcnt(2)
	v_cvt_pk_bf16_f32 v2, v16, v18
	s_waitcnt lgkmcnt(0)
	v_cvt_pk_bf16_f32 v3, v20, v22
	v_lshl_add_u64 v[24:25], v[4:5], 0, v[24:25]
	v_or_b32_e32 v6, v51, v12
	global_store_dwordx4 v[24:25], v[0:3], off nt
	s_nop 1
	v_cvt_pk_bf16_f32 v0, v9, v7
	v_mul_u32_u24_e32 v7, 0x2aab, v6
	v_lshrrev_b32_e32 v7, 21, v7
	v_mul_lo_u16_e32 v7, 0xc0, v7
	v_sub_u16_e32 v7, v6, v7
	v_cmp_gt_u16_e64 s[6:7], s16, v7
	v_sub_u32_e32 v9, v6, v7
	v_cmp_gt_u16_e32 vcc, s4, v7
	v_cndmask_b32_e64 v8, v201, v202, s[6:7]
	v_lshl_add_u32 v7, v7, 1, v9
	v_add3_u32 v7, v7, v8, s4
	v_cndmask_b32_e32 v6, v7, v6, vcc
	v_ashrrev_i32_e32 v7, 31, v6
	v_lshlrev_b64 v[6:7], 10, v[6:7]
	v_cvt_pk_bf16_f32 v1, v11, v15
	v_cvt_pk_bf16_f32 v2, v17, v19
	v_cvt_pk_bf16_f32 v3, v21, v23
	v_lshl_add_u64 v[6:7], v[4:5], 0, v[6:7]
	global_store_dwordx4 v[6:7], v[0:3], off nt
	ds_read2_b32 v[6:7], v58 offset0:16 offset1:24
	ds_read2_b32 v[8:9], v58 offset0:49 offset1:57
	ds_read2_b32 v[10:11], v58 offset0:82 offset1:90
	ds_read2_b32 v[14:15], v58 offset0:115 offset1:123
	ds_read2_b32 v[16:17], v58 offset0:148 offset1:156
	ds_read2_b32 v[18:19], v58 offset0:181 offset1:189
	ds_read2_b32 v[20:21], v58 offset0:214 offset1:222
	ds_read2_b32 v[22:23], v58 offset0:247 offset1:255
	s_waitcnt lgkmcnt(6)
	v_cvt_pk_bf16_f32 v0, v6, v8
	v_or_b32_e32 v6, v56, v12
	v_mul_u32_u24_e32 v8, 0x2aab, v6
	v_lshrrev_b32_e32 v8, 21, v8
	v_mul_lo_u16_e32 v8, 0xc0, v8
	v_sub_u16_e32 v8, v6, v8
	v_cmp_gt_u16_e64 s[6:7], s16, v8
	v_sub_u32_e32 v13, v6, v8
	s_waitcnt lgkmcnt(4)
	v_cvt_pk_bf16_f32 v1, v10, v14
	v_cmp_gt_u16_e32 vcc, s4, v8
	v_cndmask_b32_e64 v10, v201, v202, s[6:7]
	v_lshl_add_u32 v8, v8, 1, v13
	v_add3_u32 v8, v8, v10, s4
	v_cndmask_b32_e32 v24, v8, v6, vcc
	v_ashrrev_i32_e32 v25, 31, v24
	v_lshlrev_b64 v[24:25], 10, v[24:25]
	s_waitcnt lgkmcnt(2)
	v_cvt_pk_bf16_f32 v2, v16, v18
	s_waitcnt lgkmcnt(0)
	v_cvt_pk_bf16_f32 v3, v20, v22
	v_lshl_add_u64 v[24:25], v[4:5], 0, v[24:25]
	v_or_b32_e32 v6, v57, v12
	global_store_dwordx4 v[24:25], v[0:3], off nt
	s_nop 1
	v_cvt_pk_bf16_f32 v0, v7, v9
	v_mul_u32_u24_e32 v7, 0x2aab, v6
	v_lshrrev_b32_e32 v7, 21, v7
	v_mul_lo_u16_e32 v7, 0xc0, v7
	v_sub_u16_e32 v7, v6, v7
	v_cmp_gt_u16_e64 s[6:7], s16, v7
	v_sub_u32_e32 v9, v6, v7
	v_cmp_gt_u16_e32 vcc, s4, v7
	v_cndmask_b32_e64 v8, v201, v202, s[6:7]
	v_lshl_add_u32 v7, v7, 1, v9
	v_add3_u32 v7, v7, v8, s4
	v_cndmask_b32_e32 v6, v7, v6, vcc
	v_ashrrev_i32_e32 v7, 31, v6
	v_lshlrev_b64 v[6:7], 10, v[6:7]
	v_cvt_pk_bf16_f32 v1, v11, v15
	v_cvt_pk_bf16_f32 v2, v17, v19
	v_cvt_pk_bf16_f32 v3, v21, v23
	v_lshl_add_u64 v[4:5], v[4:5], 0, v[6:7]
	global_store_dwordx4 v[4:5], v[0:3], off nt
	s_waitcnt lgkmcnt(0)

; DI float ss_get(const ssacc_t* p) { const ssacc_t v = *p; return (float)(unsigned)(v >> 32) + (float)(unsigned)(v & 0xffffffffull) * 2.3283064365386963e-10f; }
; DI void final_norm(PP p) {
;     ...
;     for (int m = blockIdx.x * 8 + wid; m < M_; m += gridDim.x * 8) {
;         const float rs = rsqrtf(ss_get(ss + m) * (1.f / 2048.f) + EPS_);
; #pragma unroll
;         for (int j = 0; j < 8; ++j) { const int c = j * 256 + lane * 4; const f32x4 v = *(const f32x4*)(X + (size_t)m * 2048 + c), gg = *(const f32x4*)(g + c); *(f32x4*)(p->out + (size_t)m * 2048 + c) = v * rs * gg; }
;     }
.LBB0_1640:
	s_ashr_i32 s1, s0, 31
	s_lshl_b64 s[2:3], s[0:1], 3
	s_add_u32 s2, s10, s2
	s_addc_u32 s3, s11, s3
	global_load_dwordx2 v[26:27], v1, s[2:3]
	s_lshl_b64 s[16:17], s[0:1], 13
	s_add_u32 s4, s8, s16
	s_addc_u32 s5, s9, s17
	global_load_dwordx4 v[64:67], v13, s[4:5] nt
	global_load_dwordx4 v[68:71], v13, s[4:5] offset:1024 nt
	global_load_dwordx4 v[72:75], v13, s[4:5] offset:2048 nt
	global_load_dwordx4 v[76:79], v13, s[4:5] offset:3072 nt
	global_load_dwordx4 v[80:83], v14, s[4:5] nt
	global_load_dwordx4 v[84:87], v15, s[4:5] nt
	global_load_dwordx4 v[88:91], v16, s[4:5] nt
	global_load_dwordx4 v[92:95], v17, s[4:5] nt
	s_add_u32 s2, s6, s16
	s_addc_u32 s3, s7, s17
	s_add_i32 s0, s0, s94
	s_waitcnt vmcnt(8)
	v_mov_b32_e32 v0, v27
	v_cvt_f32_u32_e32 v28, v26
	v_lshlrev_b64 v[26:27], s12, v[0:1]
	v_min_u32_e32 v0, 1, v26
	v_or_b32_e32 v0, v27, v0
	v_cvt_f32_u32_e32 v0, v0
	v_ldexp_f32 v0, v0, s13
	v_fmac_f32_e32 v0, 0x2f800000, v28
	v_fmamk_f32 v0, v0, 0x3a000000, v12
	v_mul_f32_e32 v26, 0x4b800000, v0
	v_cmp_gt_f32_e32 vcc, s14, v0
	s_nop 1
	v_cndmask_b32_e32 v0, v0, v26, vcc
	v_rsq_f32_e32 v0, v0
	s_nop 0
	v_mul_f32_e32 v26, 0x45800000, v0
	v_cndmask_b32_e32 v0, v0, v26, vcc
	s_waitcnt vmcnt(7)
	v_pk_mul_f32 v[64:65], v[64:65], v[0:1] op_sel_hi:[1,0]
	v_pk_mul_f32 v[66:67], v[66:67], v[0:1] op_sel_hi:[1,0]
	v_pk_mul_f32 v[64:65], v[32:33], v[64:65]
	v_pk_mul_f32 v[66:67], v[34:35], v[66:67]
	global_store_dwordx4 v13, v[64:67], s[2:3] nt
	s_waitcnt vmcnt(7)
	v_pk_mul_f32 v[68:69], v[68:69], v[0:1] op_sel_hi:[1,0]
	v_pk_mul_f32 v[70:71], v[70:71], v[0:1] op_sel_hi:[1,0]
	v_pk_mul_f32 v[68:69], v[36:37], v[68:69]
	v_pk_mul_f32 v[70:71], v[38:39], v[70:71]
	global_store_dwordx4 v13, v[68:71], s[2:3] offset:1024 nt
	s_waitcnt vmcnt(7)
	v_pk_mul_f32 v[72:73], v[72:73], v[0:1] op_sel_hi:[1,0]
	v_pk_mul_f32 v[74:75], v[74:75], v[0:1] op_sel_hi:[1,0]
	v_pk_mul_f32 v[72:73], v[40:41], v[72:73]
	v_pk_mul_f32 v[74:75], v[42:43], v[74:75]
	global_store_dwordx4 v13, v[72:75], s[2:3] offset:2048 nt
	s_waitcnt vmcnt(7)
	v_pk_mul_f32 v[76:77], v[76:77], v[0:1] op_sel_hi:[1,0]
	v_pk_mul_f32 v[78:79], v[78:79], v[0:1] op_sel_hi:[1,0]
	v_pk_mul_f32 v[76:77], v[44:45], v[76:77]
	v_pk_mul_f32 v[78:79], v[46:47], v[78:79]
	global_store_dwordx4 v13, v[76:79], s[2:3] offset:3072 nt
	s_waitcnt vmcnt(7)
	v_pk_mul_f32 v[80:81], v[80:81], v[0:1] op_sel_hi:[1,0]
	v_pk_mul_f32 v[82:83], v[82:83], v[0:1] op_sel_hi:[1,0]
	v_pk_mul_f32 v[80:81], v[48:49], v[80:81]
	v_pk_mul_f32 v[82:83], v[50:51], v[82:83]
	global_store_dwordx4 v14, v[80:83], s[2:3] nt
	s_waitcnt vmcnt(7)
	v_pk_mul_f32 v[84:85], v[84:85], v[0:1] op_sel_hi:[1,0]
	v_pk_mul_f32 v[86:87], v[86:87], v[0:1] op_sel_hi:[1,0]
	v_pk_mul_f32 v[84:85], v[52:53], v[84:85]
	v_pk_mul_f32 v[86:87], v[54:55], v[86:87]
	global_store_dwordx4 v15, v[84:87], s[2:3] nt
	s_waitcnt vmcnt(7)
	v_pk_mul_f32 v[88:89], v[88:89], v[0:1] op_sel_hi:[1,0]
	v_pk_mul_f32 v[90:91], v[90:91], v[0:1] op_sel_hi:[1,0]
	v_pk_mul_f32 v[88:89], v[56:57], v[88:89]
	v_pk_mul_f32 v[90:91], v[58:59], v[90:91]
	global_store_dwordx4 v16, v[88:91], s[2:3] nt
	s_waitcnt vmcnt(7)
	v_pk_mul_f32 v[92:93], v[92:93], v[0:1] op_sel_hi:[1,0]
	v_pk_mul_f32 v[94:95], v[94:95], v[0:1] op_sel_hi:[1,0]
	v_pk_mul_f32 v[92:93], v[60:61], v[92:93]
	v_pk_mul_f32 v[94:95], v[62:63], v[94:95]
	global_store_dwordx4 v17, v[92:95], s[2:3] nt
	s_cmpk_lt_i32 s0, 0x2000
	s_cbranch_scc1 .LBB0_1640
